# sc1 (write-through) on the SSD-in / SC-in / FFN-up GEMM epilogue stores
# speedup vs baseline: 1.0130x; 1.0130x over previous
;     __device__ __forceinline__ void fast(const f32x4 (&acc)[2][2][4][2], const pg8::Unit& u, int wr, int wc, int fr, int fq, RsCache& rsc) const {
;         asm volatile("" : "+v"(fr), "+v"(fq));
;         rs_cache_fill(rsc, rs, u.pm, wr, fq * 16 + fr);
;         typedef float f32x2 __attribute__((ext_vector_type(2)));
;         const int ch = u.pn * 128 + wc * 32 + 8 * fq;
;         f32x2 w0[4], w1[4], w2[4], bb[4];
; #pragma unroll
;         for (int h = 0; h < 2; ++h) { const f32x4 t0 = *(const f32x4*)(cw + ch + 4 * h), t1 = *(const f32x4*)(cw + FH + ch + 4 * h), t2 = *(const f32x4*)(cw + 2 * FH + ch + 4 * h), t3 = *(const f32x4*)(cb + ch + 4 * h);
;             w0[2 * h] = (f32x2){t0[0], t0[1]}; w0[2 * h + 1] = (f32x2){t0[2], t0[3]}; w1[2 * h] = (f32x2){t1[0], t1[1]}; w1[2 * h + 1] = (f32x2){t1[2], t1[3]};
;             w2[2 * h] = (f32x2){t2[0], t2[1]}; w2[2 * h + 1] = (f32x2){t2[2], t2[3]}; bb[2 * h] = (f32x2){t3[0], t3[1]}; bb[2 * h + 1] = (f32x2){t3[2], t3[3]}; }
; #pragma unroll
;         for (int ai = 0; ai < 2; ++ai) {
;             const int rowb = u.pm * 256 + ai * 128 + wr * 64, blk = rowb >> 6;
;             f32x2 gp[4];
; #pragma unroll
;             for (int m = 0; m < 4; ++m) {
;                 const int row = rowb + m * 16 + fr; const float s = rsc.tab[ai * 64 + m * 16 + fr]; const f32x2 s2 = (f32x2){s, s};
;                 f32x2 g[4], o[4], v[4];
; #pragma unroll
;                 for (int cp = 0; cp < 4; ++cp) { const int n = cp >> 1, e0 = (cp & 1) * 2;
;                     g[cp] = (f32x2){acc[ai][0][m][n][e0], acc[ai][0][m][n][e0 + 1]} * s2; v[cp] = (f32x2){acc[ai][1][m][n][e0], acc[ai][1][m][n][e0 + 1]} * s2; }
; #pragma unroll
;                 for (int cp = 0; cp < 4; ++cp) {
;                     f32x2 p1 = (f32x2){dppz<0x111>(g[cp].x), dppz<0x111>(g[cp].y)}, p2 = (f32x2){dppz<0x112>(g[cp].x), dppz<0x112>(g[cp].y)};
;                     if (m > 0) { p1 += (f32x2){dppz<0x10F>(gp[cp].x), dppz<0x10F>(gp[cp].y)}; p2 += (f32x2){dppz<0x10E>(gp[cp].x), dppz<0x10E>(gp[cp].y)}; }
;                     const f32x2 gv = bb[cp] + w0[cp] * p2 + w1[cp] * p1 + w2[cp] * g[cp];
;                     const f32x2 ea = gv * (-1.44269504089f);
;                     f32x2 ex; ex.x = __builtin_amdgcn_exp2f(ea.x); ex.y = __builtin_amdgcn_exp2f(ea.y);
;                     const f32x2 dn = ex + 1.0f;
.LBB0_266:
	s_lshl_b32 s0, s2, 7
	s_or_b32 s0, s0, s97
	v_lshl_add_u32 v184, v58, 3, s0
	v_ashrrev_i32_e32 v185, 31, v184
	v_readlane_b32 s0, v255, 22
	v_lshlrev_b64 v[58:59], 2, v[184:185]
	v_readlane_b32 s1, v255, 23
	v_lshl_add_u32 v223, v186, 2, s68
	v_cmp_lt_i32_e64 s[6:7], 1, v186
	v_lshl_add_u64 v[60:61], s[0:1], 0, v[58:59]
	v_readlane_b32 s0, v255, 20
	v_readlane_b32 s1, v255, 21
	v_add_u32_e32 v224, s3, v186
	s_nop 0
	v_lshl_add_u64 v[66:67], s[0:1], 0, v[58:59]
	v_readlane_b32 s0, v255, 24
	v_readlane_b32 s1, v255, 25
	s_nop 1
	v_lshl_add_u64 v[74:75], s[0:1], 0, v[58:59]
	v_readlane_b32 s0, v255, 18
	v_readlane_b32 s1, v255, 19
	s_nop 1
	v_lshl_add_u64 v[102:103], s[0:1], 0, v[58:59]
	global_load_dwordx4 v[70:73], v[60:61], off offset:16
	global_load_dwordx4 v[90:93], v[60:61], off
	s_nop 0
	global_load_dwordx4 v[58:61], v[66:67], off offset:16
	global_load_dwordx4 v[94:97], v[66:67], off
	s_nop 0
	global_load_dwordx4 v[66:69], v[74:75], off offset:16
	global_load_dwordx4 v[98:101], v[74:75], off
	s_nop 0
	global_load_dwordx4 v[74:77], v[102:103], off offset:16
	s_nop 0
	global_load_dwordx4 v[102:105], v[102:103], off
	ds_read_b32 v172, v223
	s_waitcnt lgkmcnt(0)
	v_pk_mul_f32 v[188:189], v[166:167], v[172:173] op_sel_hi:[1,0]
	v_pk_mul_f32 v[190:191], v[158:159], v[172:173] op_sel_hi:[1,0]
	v_pk_mul_f32 v[166:167], v[168:169], v[172:173] op_sel_hi:[1,0]
	v_pk_mul_f32 v[168:169], v[160:161], v[172:173] op_sel_hi:[1,0]
	v_pk_mul_f32 v[160:161], v[162:163], v[172:173] op_sel_hi:[1,0]
	v_pk_mul_f32 v[158:159], v[164:165], v[172:173] op_sel_hi:[1,0]
	v_pk_mul_f32 v[162:163], v[154:155], v[172:173] op_sel_hi:[1,0]
	v_pk_mul_f32 v[156:157], v[156:157], v[172:173] op_sel_hi:[1,0]
	v_mov_b32_dpp v192, v188 row_shr:1 row_mask:0xf bank_mask:0xf bound_ctrl:1
	v_mov_b32_dpp v193, v189 row_shr:1 row_mask:0xf bank_mask:0xf bound_ctrl:1
	v_mov_b32_dpp v194, v188 row_shr:2 row_mask:0xf bank_mask:0xf bound_ctrl:1
	v_mov_b32_dpp v195, v189 row_shr:2 row_mask:0xf bank_mask:0xf bound_ctrl:1
	v_mov_b32_dpp v196, v166 row_shr:1 row_mask:0xf bank_mask:0xf bound_ctrl:1
	v_mov_b32_dpp v197, v167 row_shr:1 row_mask:0xf bank_mask:0xf bound_ctrl:1
	v_mov_b32_dpp v198, v166 row_shr:2 row_mask:0xf bank_mask:0xf bound_ctrl:1
	v_mov_b32_dpp v199, v167 row_shr:2 row_mask:0xf bank_mask:0xf bound_ctrl:1
	v_mov_b32_dpp v200, v160 row_shr:1 row_mask:0xf bank_mask:0xf bound_ctrl:1
	v_mov_b32_dpp v201, v161 row_shr:1 row_mask:0xf bank_mask:0xf bound_ctrl:1
	v_mov_b32_dpp v202, v160 row_shr:2 row_mask:0xf bank_mask:0xf bound_ctrl:1
	v_mov_b32_dpp v203, v161 row_shr:2 row_mask:0xf bank_mask:0xf bound_ctrl:1
	v_mov_b32_dpp v154, v158 row_shr:1 row_mask:0xf bank_mask:0xf bound_ctrl:1
	v_mov_b32_dpp v155, v159 row_shr:1 row_mask:0xf bank_mask:0xf bound_ctrl:1
	v_mov_b32_dpp v164, v158 row_shr:2 row_mask:0xf bank_mask:0xf bound_ctrl:1
	v_mov_b32_dpp v165, v159 row_shr:2 row_mask:0xf bank_mask:0xf bound_ctrl:1
	s_and_saveexec_b64 s[0:1], s[6:7]
	v_readlane_b32 s78, v254, 59
	s_cbranch_execz .LBB0_268
	s_waitcnt vmcnt(0)
	v_pk_fma_f32 v[194:195], v[90:91], v[194:195], v[102:103]
	v_pk_fma_f32 v[164:165], v[72:73], v[164:165], v[76:77]
	v_pk_fma_f32 v[172:173], v[70:71], v[202:203], v[74:75]
	v_pk_fma_f32 v[198:199], v[92:93], v[198:199], v[104:105]
	v_pk_fma_f32 v[192:193], v[94:95], v[192:193], v[194:195]
	v_pk_fma_f32 v[154:155], v[60:61], v[154:155], v[164:165]
	v_pk_fma_f32 v[172:173], v[58:59], v[200:201], v[172:173]
	s_mov_b32 s2, 0xbfb8aa3b
	v_pk_fma_f32 v[196:197], v[96:97], v[196:197], v[198:199]
	v_pk_fma_f32 v[192:193], v[98:99], v[188:189], v[192:193]
	v_pk_fma_f32 v[154:155], v[68:69], v[158:159], v[154:155]
	v_pk_fma_f32 v[172:173], v[66:67], v[160:161], v[172:173]
	v_pk_fma_f32 v[196:197], v[100:101], v[166:167], v[196:197]
	v_pk_mul_f32 v[194:195], v[192:193], s[2:3] op_sel_hi:[1,0]
	v_pk_mul_f32 v[164:165], v[154:155], s[2:3] op_sel_hi:[1,0]
	v_pk_mul_f32 v[200:201], v[172:173], s[2:3] op_sel_hi:[1,0]
	v_pk_mul_f32 v[198:199], v[196:197], s[2:3] op_sel_hi:[1,0]
	v_exp_f32_e32 v194, v194
	v_exp_f32_e32 v195, v195
	v_exp_f32_e32 v164, v164
	v_exp_f32_e32 v165, v165
	v_exp_f32_e32 v200, v200
	v_exp_f32_e32 v201, v201
	v_exp_f32_e32 v198, v198
	v_exp_f32_e32 v199, v199
	v_pk_add_f32 v[194:195], v[194:195], 1.0 op_sel_hi:[1,0]
	v_pk_add_f32 v[164:165], v[164:165], 1.0 op_sel_hi:[1,0]
	v_pk_add_f32 v[200:201], v[200:201], 1.0 op_sel_hi:[1,0]
	v_pk_add_f32 v[198:199], v[198:199], 1.0 op_sel_hi:[1,0]
	v_rcp_f32_e32 v194, v194
	v_rcp_f32_e32 v195, v195
	v_rcp_f32_e32 v164, v164
	v_rcp_f32_e32 v165, v165
	v_rcp_f32_e32 v200, v200
	v_rcp_f32_e32 v201, v201
	v_rcp_f32_e32 v198, v198
	v_rcp_f32_e32 v199, v199
	v_pk_mul_f32 v[192:193], v[192:193], v[194:195]
	v_pk_mul_f32 v[154:155], v[154:155], v[164:165]
	v_readlane_b32 s8, v253, 16
	v_pk_mul_f32 v[172:173], v[172:173], v[200:201]
	v_pk_mul_f32 v[196:197], v[196:197], v[198:199]
	v_pk_mul_f32 v[192:193], v[190:191], v[192:193]
	v_pk_mul_f32 v[154:155], v[156:157], v[154:155]
	v_readlane_b32 s9, v253, 17
	v_pk_mul_f32 v[172:173], v[162:163], v[172:173]
	v_pk_mul_f32 v[196:197], v[168:169], v[196:197]
	v_cvt_pk_bf16_f32 v192, v192, v193
	s_nop 0
	v_cvt_pk_bf16_f32 v193, v196, v197
	v_cvt_pk_bf16_f32 v194, v172, v173
	v_cvt_pk_bf16_f32 v195, v154, v155
	v_mov_b64_e32 v[154:155], s[8:9]
	v_mad_i64_i32 v[154:155], s[8:9], v224, s93, v[154:155]
	v_lshl_add_u64 v[154:155], v[184:185], 1, v[154:155]
	global_store_dwordx4 v[154:155], v[192:195], off sc1
;     __device__ __forceinline__ void fast(const f32x4 (&acc)[2][2][4][2], const pg8::Unit& u, int wr, int wc, int fr, int fq, RsCache& rsc) const {
;     ...
;                 const int row = rowb + m * 16 + fr; const float s = rsc.tab[ai * 64 + m * 16 + fr]; const f32x2 s2 = (f32x2){s, s};
;                 f32x2 g[4], o[4], v[4];
; #pragma unroll
;                 for (int cp = 0; cp < 4; ++cp) { const int n = cp >> 1, e0 = (cp & 1) * 2;
;                     g[cp] = (f32x2){acc[ai][0][m][n][e0], acc[ai][0][m][n][e0 + 1]} * s2; v[cp] = (f32x2){acc[ai][1][m][n][e0], acc[ai][1][m][n][e0 + 1]} * s2; }
; #pragma unroll
;                 for (int cp = 0; cp < 4; ++cp) {
;                     f32x2 p1 = (f32x2){dppz<0x111>(g[cp].x), dppz<0x111>(g[cp].y)}, p2 = (f32x2){dppz<0x112>(g[cp].x), dppz<0x112>(g[cp].y)};
;                     if (m > 0) { p1 += (f32x2){dppz<0x10F>(gp[cp].x), dppz<0x10F>(gp[cp].y)}; p2 += (f32x2){dppz<0x10E>(gp[cp].x), dppz<0x10E>(gp[cp].y)}; }
;                     const f32x2 gv = bb[cp] + w0[cp] * p2 + w1[cp] * p1 + w2[cp] * g[cp];
;                     const f32x2 ea = gv * (-1.44269504089f);
;                     f32x2 ex; ex.x = __builtin_amdgcn_exp2f(ea.x); ex.y = __builtin_amdgcn_exp2f(ea.y);
;                     const f32x2 dn = ex + 1.0f;
;                     f32x2 rc; rc.x = __builtin_amdgcn_rcpf(dn.x); rc.y = __builtin_amdgcn_rcpf(dn.y);
;                     o[cp] = (gv * rc) * v[cp];
;                 }
;                 if (m > 0 || fr >= 2) { uint4 w; w.x = pk2(o[0].x, o[0].y); w.y = pk2(o[1].x, o[1].y); w.z = pk2(o[2].x, o[2].y); w.w = pk2(o[3].x, o[3].y); *(uint4*)(act + (size_t)row * FH + ch) = w; }
;                 if (m == 0 && fr < 2) { uint4 w; w.x = pk2(g[0].x, g[0].y); w.y = pk2(g[1].x, g[1].y); w.z = pk2(g[2].x, g[2].y); w.w = pk2(g[3].x, g[3].y); *(uint4*)(sideg + ((size_t)blk * 4 + fr) * FH + ch) = w;
;                     uint4 q; q.x = pk2(v[0].x, v[0].y); q.y = pk2(v[1].x, v[1].y); q.z = pk2(v[2].x, v[2].y); q.w = pk2(v[3].x, v[3].y); *(uint4*)(sidev + ((size_t)blk * 2 + fr) * FH + ch) = q; }
;                 if (m == 3 && fr >= 14) { uint4 w; w.x = pk2(g[0].x, g[0].y); w.y = pk2(g[1].x, g[1].y); w.z = pk2(g[2].x, g[2].y); w.w = pk2(g[3].x, g[3].y); *(uint4*)(sideg + ((size_t)blk * 4 + 2 + (fr - 14)) * FH + ch) = w; }
; #pragma unroll
;                 for (int cp = 0; cp < 4; ++cp) gp[cp] = g[cp];
.LBB0_268:
	s_or_b64 exec, exec, s[0:1]
	s_ashr_i32 s84, s3, 6
	s_ashr_i32 s85, s84, 31
	v_cmp_gt_i32_e64 s[8:9], 2, v186
	v_ashrrev_i32_e32 v187, 31, v186
	s_lshl_b64 s[0:1], s[84:85], 2
	v_lshlrev_b64 v[154:155], 1, v[184:185]
	s_and_saveexec_b64 s[82:83], s[8:9]
	s_cbranch_execz .LBB0_270
	v_lshl_add_u64 v[164:165], s[0:1], 0, v[186:187]
	s_lshl_b64 s[74:75], s[84:85], 1
	v_mov_b32_e32 v172, s75
	v_subrev_co_u32_e32 v196, vcc, s74, v164
	v_readlane_b32 s74, v254, 1
	v_readlane_b32 s75, v254, 2
	v_subb_co_u32_e32 v197, vcc, v165, v172, vcc
	s_nop 0
	v_mov_b64_e32 v[172:173], s[74:75]
	v_mad_u64_u32 v[172:173], s[74:75], v164, s93, v[172:173]
	v_mad_i32_i24 v173, v165, s93, v173
	v_readlane_b32 s74, v254, 15
	v_cvt_pk_bf16_f32 v192, v188, v189
	v_cvt_pk_bf16_f32 v193, v166, v167
	v_lshl_add_u64 v[164:165], v[172:173], 0, v[154:155]
	v_readlane_b32 s75, v254, 16
	v_cvt_pk_bf16_f32 v194, v160, v161
	v_cvt_pk_bf16_f32 v195, v158, v159
	global_store_dwordx4 v[164:165], v[192:195], off sc1
	v_cvt_pk_bf16_f32 v190, v190, v191
	v_cvt_pk_bf16_f32 v191, v168, v169
	s_nop 1
	v_cvt_pk_bf16_f32 v192, v162, v163
	v_cvt_pk_bf16_f32 v193, v156, v157
	v_mov_b64_e32 v[156:157], s[74:75]
	v_mad_u64_u32 v[156:157], s[74:75], v196, s93, v[156:157]
	v_mad_i32_i24 v157, v197, s93, v157
	v_lshl_add_u64 v[156:157], v[156:157], 0, v[154:155]
	global_store_dwordx4 v[156:157], v[190:193], off sc1
.LBB0_270:
	s_or_b64 exec, exec, s[82:83]
	ds_read_b32 v164, v223 offset:64
	v_mov_b32_dpp v172, v188 row_shl:14 row_mask:0xf bank_mask:0xf bound_ctrl:1
	v_mov_b32_dpp v173, v189 row_shl:14 row_mask:0xf bank_mask:0xf bound_ctrl:1
	s_mov_b32 s2, 0xbfb8aa3b
	v_readlane_b32 s74, v253, 16
	s_waitcnt lgkmcnt(0)
	v_pk_mul_f32 v[162:163], v[150:151], v[164:165] op_sel_hi:[1,0]
	v_pk_mul_f32 v[168:169], v[142:143], v[164:165] op_sel_hi:[1,0]
	v_pk_mul_f32 v[142:143], v[148:149], v[164:165] op_sel_hi:[1,0]
	v_mov_b32_dpp v148, v162 row_shr:2 row_mask:0xf bank_mask:0xf bound_ctrl:1
	v_mov_b32_dpp v149, v163 row_shr:2 row_mask:0xf bank_mask:0xf bound_ctrl:1
	v_pk_mul_f32 v[150:151], v[152:153], v[164:165] op_sel_hi:[1,0]
	v_pk_mul_f32 v[152:153], v[144:145], v[164:165] op_sel_hi:[1,0]
	v_pk_mul_f32 v[144:145], v[146:147], v[164:165] op_sel_hi:[1,0]
	v_pk_mul_f32 v[138:139], v[138:139], v[164:165] op_sel_hi:[1,0]
	v_pk_mul_f32 v[140:141], v[140:141], v[164:165] op_sel_hi:[1,0]
	v_mov_b32_dpp v146, v162 row_shr:1 row_mask:0xf bank_mask:0xf bound_ctrl:1
	v_mov_b32_dpp v147, v163 row_shr:1 row_mask:0xf bank_mask:0xf bound_ctrl:1
	v_mov_b32_dpp v164, v188 row_shl:15 row_mask:0xf bank_mask:0xf bound_ctrl:1
	v_mov_b32_dpp v165, v189 row_shl:15 row_mask:0xf bank_mask:0xf bound_ctrl:1
	v_pk_add_f32 v[148:149], v[148:149], v[172:173]
	v_pk_add_f32 v[146:147], v[146:147], v[164:165]
	s_waitcnt vmcnt(0)
	v_pk_fma_f32 v[148:149], v[90:91], v[148:149], v[102:103]
	v_mov_b32_dpp v164, v150 row_shr:2 row_mask:0xf bank_mask:0xf bound_ctrl:1
	v_pk_fma_f32 v[146:147], v[94:95], v[146:147], v[148:149]
	v_mov_b32_dpp v165, v151 row_shr:2 row_mask:0xf bank_mask:0xf bound_ctrl:1
	v_pk_fma_f32 v[146:147], v[98:99], v[162:163], v[146:147]
	v_readlane_b32 s75, v253, 17
	v_pk_mul_f32 v[148:149], v[146:147], s[2:3] op_sel_hi:[1,0]
	v_cmp_lt_i32_e32 vcc, 13, v186
	v_exp_f32_e32 v148, v148
	v_exp_f32_e32 v149, v149
	v_lshl_add_u64 v[156:157], v[186:187], 0, -12
	v_pk_add_f32 v[148:149], v[148:149], 1.0 op_sel_hi:[1,0]
	s_nop 0
	v_rcp_f32_e32 v148, v148
	v_rcp_f32_e32 v149, v149
	s_nop 0
	v_pk_mul_f32 v[146:147], v[146:147], v[148:149]
	s_nop 0
	v_pk_mul_f32 v[146:147], v[168:169], v[146:147]
	v_mov_b32_dpp v168, v166 row_shl:15 row_mask:0xf bank_mask:0xf bound_ctrl:1
	v_mov_b32_dpp v169, v167 row_shl:15 row_mask:0xf bank_mask:0xf bound_ctrl:1
	v_mov_b32_dpp v166, v166 row_shl:14 row_mask:0xf bank_mask:0xf bound_ctrl:1
	v_mov_b32_dpp v167, v167 row_shl:14 row_mask:0xf bank_mask:0xf bound_ctrl:1
	v_mov_b32_dpp v148, v150 row_shr:1 row_mask:0xf bank_mask:0xf bound_ctrl:1
	v_mov_b32_dpp v149, v151 row_shr:1 row_mask:0xf bank_mask:0xf bound_ctrl:1
	v_pk_add_f32 v[164:165], v[164:165], v[166:167]
	v_pk_add_f32 v[148:149], v[148:149], v[168:169]
	v_pk_fma_f32 v[164:165], v[92:93], v[164:165], v[104:105]
	v_mov_b32_dpp v166, v160 row_shl:15 row_mask:0xf bank_mask:0xf bound_ctrl:1
	v_pk_fma_f32 v[148:149], v[96:97], v[148:149], v[164:165]
	v_mov_b32_dpp v167, v161 row_shl:15 row_mask:0xf bank_mask:0xf bound_ctrl:1
	v_pk_fma_f32 v[148:149], v[100:101], v[150:151], v[148:149]
	v_mov_b32_dpp v160, v160 row_shl:14 row_mask:0xf bank_mask:0xf bound_ctrl:1
	v_pk_mul_f32 v[164:165], v[148:149], s[2:3] op_sel_hi:[1,0]
	v_mov_b32_dpp v161, v161 row_shl:14 row_mask:0xf bank_mask:0xf bound_ctrl:1
	v_exp_f32_e32 v164, v164
	v_exp_f32_e32 v165, v165
	v_cvt_pk_bf16_f32 v146, v146, v147
	s_nop 0
	v_pk_add_f32 v[164:165], v[164:165], 1.0 op_sel_hi:[1,0]
	s_nop 0
	v_rcp_f32_e32 v164, v164
	v_rcp_f32_e32 v165, v165
	s_nop 0
	v_pk_mul_f32 v[148:149], v[148:149], v[164:165]
	v_mov_b32_dpp v164, v144 row_shr:2 row_mask:0xf bank_mask:0xf bound_ctrl:1
	v_mov_b32_dpp v165, v145 row_shr:2 row_mask:0xf bank_mask:0xf bound_ctrl:1
	v_pk_mul_f32 v[148:149], v[152:153], v[148:149]
	v_mov_b32_dpp v152, v144 row_shr:1 row_mask:0xf bank_mask:0xf bound_ctrl:1
	v_mov_b32_dpp v153, v145 row_shr:1 row_mask:0xf bank_mask:0xf bound_ctrl:1
	v_pk_add_f32 v[160:161], v[164:165], v[160:161]
	v_pk_add_f32 v[152:153], v[152:153], v[166:167]
	v_pk_fma_f32 v[160:161], v[70:71], v[160:161], v[74:75]
	v_mov_b32_dpp v164, v158 row_shl:15 row_mask:0xf bank_mask:0xf bound_ctrl:1
	v_pk_fma_f32 v[152:153], v[58:59], v[152:153], v[160:161]
; __device__ __forceinline__ unsigned pk2(float lo, float hi) { unsigned r; asm volatile("v_cvt_pk_bf16_f32 %0, %1, %2" : "=v"(r) : "v"(lo), "v"(hi)); return r; }
; template <int CTRL> __device__ __forceinline__ float dppz(float x) { return __builtin_bit_cast(float, __builtin_amdgcn_update_dpp(0, __builtin_bit_cast(int, x), CTRL, 0xf, 0xf, true)); }
;     __device__ __forceinline__ void fast(const f32x4 (&acc)[2][2][4][2], const pg8::Unit& u, int wr, int wc, int fr, int fq, RsCache& rsc) const {
;     ...
;                 const int row = rowb + m * 16 + fr; const float s = rsc.tab[ai * 64 + m * 16 + fr]; const f32x2 s2 = (f32x2){s, s};
;                 f32x2 g[4], o[4], v[4];
; #pragma unroll
;                 for (int cp = 0; cp < 4; ++cp) { const int n = cp >> 1, e0 = (cp & 1) * 2;
;                     g[cp] = (f32x2){acc[ai][0][m][n][e0], acc[ai][0][m][n][e0 + 1]} * s2; v[cp] = (f32x2){acc[ai][1][m][n][e0], acc[ai][1][m][n][e0 + 1]} * s2; }
; #pragma unroll
;                 for (int cp = 0; cp < 4; ++cp) {
;                     f32x2 p1 = (f32x2){dppz<0x111>(g[cp].x), dppz<0x111>(g[cp].y)}, p2 = (f32x2){dppz<0x112>(g[cp].x), dppz<0x112>(g[cp].y)};
;                     if (m > 0) { p1 += (f32x2){dppz<0x10F>(gp[cp].x), dppz<0x10F>(gp[cp].y)}; p2 += (f32x2){dppz<0x10E>(gp[cp].x), dppz<0x10E>(gp[cp].y)}; }
;                     const f32x2 gv = bb[cp] + w0[cp] * p2 + w1[cp] * p1 + w2[cp] * g[cp];
;                     const f32x2 ea = gv * (-1.44269504089f);
;                     f32x2 ex; ex.x = __builtin_amdgcn_exp2f(ea.x); ex.y = __builtin_amdgcn_exp2f(ea.y);
;                     const f32x2 dn = ex + 1.0f;
;                     f32x2 rc; rc.x = __builtin_amdgcn_rcpf(dn.x); rc.y = __builtin_amdgcn_rcpf(dn.y);
;                     o[cp] = (gv * rc) * v[cp];
;                 }
;                 if (m > 0 || fr >= 2) { uint4 w; w.x = pk2(o[0].x, o[0].y); w.y = pk2(o[1].x, o[1].y); w.z = pk2(o[2].x, o[2].y); w.w = pk2(o[3].x, o[3].y); *(uint4*)(act + (size_t)row * FH + ch) = w; }
	v_mov_b32_dpp v165, v159 row_shl:15 row_mask:0xf bank_mask:0xf bound_ctrl:1
	v_pk_fma_f32 v[152:153], v[66:67], v[144:145], v[152:153]
	v_mov_b32_dpp v158, v158 row_shl:14 row_mask:0xf bank_mask:0xf bound_ctrl:1
	v_pk_mul_f32 v[160:161], v[152:153], s[2:3] op_sel_hi:[1,0]
	v_mov_b32_dpp v159, v159 row_shl:14 row_mask:0xf bank_mask:0xf bound_ctrl:1
	v_exp_f32_e32 v160, v160
	v_exp_f32_e32 v161, v161
	v_add_u32_e32 v166, 16, v224
	v_cvt_pk_bf16_f32 v147, v148, v149
	v_pk_add_f32 v[160:161], v[160:161], 1.0 op_sel_hi:[1,0]
	s_nop 0
	v_rcp_f32_e32 v160, v160
	v_rcp_f32_e32 v161, v161
	s_nop 0
	v_pk_mul_f32 v[152:153], v[152:153], v[160:161]
	v_mov_b32_dpp v160, v142 row_shr:2 row_mask:0xf bank_mask:0xf bound_ctrl:1
	v_mov_b32_dpp v161, v143 row_shr:2 row_mask:0xf bank_mask:0xf bound_ctrl:1
	v_pk_mul_f32 v[138:139], v[138:139], v[152:153]
	v_mov_b32_dpp v152, v142 row_shr:1 row_mask:0xf bank_mask:0xf bound_ctrl:1
	v_mov_b32_dpp v153, v143 row_shr:1 row_mask:0xf bank_mask:0xf bound_ctrl:1
	v_pk_add_f32 v[158:159], v[160:161], v[158:159]
	v_pk_add_f32 v[152:153], v[152:153], v[164:165]
	v_pk_fma_f32 v[158:159], v[72:73], v[158:159], v[76:77]
	v_cvt_pk_bf16_f32 v148, v138, v139
	v_mov_b64_e32 v[138:139], s[74:75]
	v_pk_fma_f32 v[152:153], v[60:61], v[152:153], v[158:159]
	s_nop 0
	v_pk_fma_f32 v[152:153], v[68:69], v[142:143], v[152:153]
	s_nop 0
	v_pk_mul_f32 v[158:159], v[152:153], s[2:3] op_sel_hi:[1,0]
	s_nop 0
	v_exp_f32_e32 v158, v158
	v_exp_f32_e32 v159, v159
	s_nop 0
	v_pk_add_f32 v[158:159], v[158:159], 1.0 op_sel_hi:[1,0]
	s_nop 0
	v_rcp_f32_e32 v158, v158
	v_rcp_f32_e32 v159, v159
	s_nop 0
	v_pk_mul_f32 v[152:153], v[152:153], v[158:159]
	s_nop 0
	v_pk_mul_f32 v[140:141], v[140:141], v[152:153]
	v_mov_b32_dpp v152, v162 row_shl:14 row_mask:0xf bank_mask:0xf bound_ctrl:1
	v_cvt_pk_bf16_f32 v149, v140, v141
	v_mad_i64_i32 v[140:141], s[74:75], v166, s93, v[138:139]
	v_lshl_add_u64 v[140:141], v[140:141], 0, v[154:155]
	global_store_dwordx4 v[140:141], v[146:149], off sc1
	ds_read_b32 v146, v223 offset:128
	v_mov_b32_dpp v153, v163 row_shl:14 row_mask:0xf bank_mask:0xf bound_ctrl:1
	s_waitcnt lgkmcnt(0)
	v_pk_mul_f32 v[140:141], v[134:135], v[146:147] op_sel_hi:[1,0]
	v_pk_mul_f32 v[134:135], v[136:137], v[146:147] op_sel_hi:[1,0]
	s_nop 0
	v_mov_b32_dpp v136, v140 row_shr:2 row_mask:0xf bank_mask:0xf bound_ctrl:1
	v_mov_b32_dpp v137, v141 row_shr:2 row_mask:0xf bank_mask:0xf bound_ctrl:1
	v_pk_mul_f32 v[148:149], v[126:127], v[146:147] op_sel_hi:[1,0]
	v_pk_mul_f32 v[128:129], v[128:129], v[146:147] op_sel_hi:[1,0]
	v_pk_mul_f32 v[126:127], v[130:131], v[146:147] op_sel_hi:[1,0]
	v_pk_mul_f32 v[130:131], v[122:123], v[146:147] op_sel_hi:[1,0]
	v_pk_mul_f32 v[122:123], v[132:133], v[146:147] op_sel_hi:[1,0]
	v_pk_mul_f32 v[124:125], v[124:125], v[146:147] op_sel_hi:[1,0]
	v_mov_b32_dpp v132, v140 row_shr:1 row_mask:0xf bank_mask:0xf bound_ctrl:1
	v_mov_b32_dpp v133, v141 row_shr:1 row_mask:0xf bank_mask:0xf bound_ctrl:1
	v_mov_b32_dpp v146, v162 row_shl:15 row_mask:0xf bank_mask:0xf bound_ctrl:1
	v_mov_b32_dpp v147, v163 row_shl:15 row_mask:0xf bank_mask:0xf bound_ctrl:1
	v_pk_add_f32 v[136:137], v[136:137], v[152:153]
	v_pk_add_f32 v[132:133], v[132:133], v[146:147]
	v_pk_fma_f32 v[136:137], v[90:91], v[136:137], v[102:103]
	v_mov_b32_dpp v146, v134 row_shr:2 row_mask:0xf bank_mask:0xf bound_ctrl:1
	v_pk_fma_f32 v[132:133], v[94:95], v[132:133], v[136:137]
	v_mov_b32_dpp v147, v135 row_shr:2 row_mask:0xf bank_mask:0xf bound_ctrl:1
	v_pk_fma_f32 v[132:133], v[98:99], v[140:141], v[132:133]
	s_nop 0
	v_pk_mul_f32 v[136:137], v[132:133], s[2:3] op_sel_hi:[1,0]
	s_nop 0
	v_exp_f32_e32 v136, v136
	v_exp_f32_e32 v137, v137
	s_nop 0
	v_pk_add_f32 v[136:137], v[136:137], 1.0 op_sel_hi:[1,0]
	s_nop 0
	v_rcp_f32_e32 v136, v136
	v_rcp_f32_e32 v137, v137
	s_nop 0
	v_pk_mul_f32 v[132:133], v[132:133], v[136:137]
	s_nop 0
	v_pk_mul_f32 v[132:133], v[148:149], v[132:133]
	v_mov_b32_dpp v148, v150 row_shl:15 row_mask:0xf bank_mask:0xf bound_ctrl:1
	v_mov_b32_dpp v149, v151 row_shl:15 row_mask:0xf bank_mask:0xf bound_ctrl:1
	v_mov_b32_dpp v150, v150 row_shl:14 row_mask:0xf bank_mask:0xf bound_ctrl:1
	v_mov_b32_dpp v151, v151 row_shl:14 row_mask:0xf bank_mask:0xf bound_ctrl:1
	v_mov_b32_dpp v136, v134 row_shr:1 row_mask:0xf bank_mask:0xf bound_ctrl:1
	v_mov_b32_dpp v137, v135 row_shr:1 row_mask:0xf bank_mask:0xf bound_ctrl:1
	v_pk_add_f32 v[146:147], v[146:147], v[150:151]
	v_pk_add_f32 v[136:137], v[136:137], v[148:149]
	v_pk_fma_f32 v[146:147], v[92:93], v[146:147], v[104:105]
	v_mov_b32_dpp v148, v144 row_shl:15 row_mask:0xf bank_mask:0xf bound_ctrl:1
	v_pk_fma_f32 v[136:137], v[96:97], v[136:137], v[146:147]
	v_mov_b32_dpp v149, v145 row_shl:15 row_mask:0xf bank_mask:0xf bound_ctrl:1
	v_pk_fma_f32 v[136:137], v[100:101], v[134:135], v[136:137]
	v_mov_b32_dpp v144, v144 row_shl:14 row_mask:0xf bank_mask:0xf bound_ctrl:1
	v_pk_mul_f32 v[146:147], v[136:137], s[2:3] op_sel_hi:[1,0]
	v_mov_b32_dpp v145, v145 row_shl:14 row_mask:0xf bank_mask:0xf bound_ctrl:1
	v_exp_f32_e32 v146, v146
	v_exp_f32_e32 v147, v147
	s_nop 0
	v_pk_add_f32 v[146:147], v[146:147], 1.0 op_sel_hi:[1,0]
	s_nop 0
	v_rcp_f32_e32 v146, v146
	v_rcp_f32_e32 v147, v147
	s_nop 0
	v_pk_mul_f32 v[136:137], v[136:137], v[146:147]
	v_mov_b32_dpp v146, v126 row_shr:2 row_mask:0xf bank_mask:0xf bound_ctrl:1
	v_mov_b32_dpp v147, v127 row_shr:2 row_mask:0xf bank_mask:0xf bound_ctrl:1
	v_pk_mul_f32 v[136:137], v[128:129], v[136:137]
	v_mov_b32_dpp v128, v126 row_shr:1 row_mask:0xf bank_mask:0xf bound_ctrl:1
	v_mov_b32_dpp v129, v127 row_shr:1 row_mask:0xf bank_mask:0xf bound_ctrl:1
; __device__ __forceinline__ unsigned pk2(float lo, float hi) { unsigned r; asm volatile("v_cvt_pk_bf16_f32 %0, %1, %2" : "=v"(r) : "v"(lo), "v"(hi)); return r; }
; template <int CTRL> __device__ __forceinline__ float dppz(float x) { return __builtin_bit_cast(float, __builtin_amdgcn_update_dpp(0, __builtin_bit_cast(int, x), CTRL, 0xf, 0xf, true)); }
;     __device__ __forceinline__ void fast(const f32x4 (&acc)[2][2][4][2], const pg8::Unit& u, int wr, int wc, int fr, int fq, RsCache& rsc) const {
;     ...
;                 const int row = rowb + m * 16 + fr; const float s = rsc.tab[ai * 64 + m * 16 + fr]; const f32x2 s2 = (f32x2){s, s};
;                 f32x2 g[4], o[4], v[4];
; #pragma unroll
;                 for (int cp = 0; cp < 4; ++cp) { const int n = cp >> 1, e0 = (cp & 1) * 2;
;                     g[cp] = (f32x2){acc[ai][0][m][n][e0], acc[ai][0][m][n][e0 + 1]} * s2; v[cp] = (f32x2){acc[ai][1][m][n][e0], acc[ai][1][m][n][e0 + 1]} * s2; }
; #pragma unroll
;                 for (int cp = 0; cp < 4; ++cp) {
;                     f32x2 p1 = (f32x2){dppz<0x111>(g[cp].x), dppz<0x111>(g[cp].y)}, p2 = (f32x2){dppz<0x112>(g[cp].x), dppz<0x112>(g[cp].y)};
;                     if (m > 0) { p1 += (f32x2){dppz<0x10F>(gp[cp].x), dppz<0x10F>(gp[cp].y)}; p2 += (f32x2){dppz<0x10E>(gp[cp].x), dppz<0x10E>(gp[cp].y)}; }
;                     const f32x2 gv = bb[cp] + w0[cp] * p2 + w1[cp] * p1 + w2[cp] * g[cp];
;                     const f32x2 ea = gv * (-1.44269504089f);
;                     f32x2 ex; ex.x = __builtin_amdgcn_exp2f(ea.x); ex.y = __builtin_amdgcn_exp2f(ea.y);
;                     const f32x2 dn = ex + 1.0f;
;                     f32x2 rc; rc.x = __builtin_amdgcn_rcpf(dn.x); rc.y = __builtin_amdgcn_rcpf(dn.y);
;                     o[cp] = (gv * rc) * v[cp];
;                 }
;                 if (m > 0 || fr >= 2) { uint4 w; w.x = pk2(o[0].x, o[0].y); w.y = pk2(o[1].x, o[1].y); w.z = pk2(o[2].x, o[2].y); w.w = pk2(o[3].x, o[3].y); *(uint4*)(act + (size_t)row * FH + ch) = w; }
	v_pk_add_f32 v[144:145], v[146:147], v[144:145]
	v_pk_add_f32 v[128:129], v[128:129], v[148:149]
	v_pk_fma_f32 v[144:145], v[70:71], v[144:145], v[74:75]
	v_mov_b32_dpp v146, v142 row_shl:15 row_mask:0xf bank_mask:0xf bound_ctrl:1
	v_pk_fma_f32 v[128:129], v[58:59], v[128:129], v[144:145]
	v_mov_b32_dpp v147, v143 row_shl:15 row_mask:0xf bank_mask:0xf bound_ctrl:1
	v_pk_fma_f32 v[128:129], v[66:67], v[126:127], v[128:129]
	v_mov_b32_dpp v142, v142 row_shl:14 row_mask:0xf bank_mask:0xf bound_ctrl:1
	v_pk_mul_f32 v[144:145], v[128:129], s[2:3] op_sel_hi:[1,0]
	v_mov_b32_dpp v143, v143 row_shl:14 row_mask:0xf bank_mask:0xf bound_ctrl:1
	v_exp_f32_e32 v144, v144
	v_exp_f32_e32 v145, v145
	v_add_u32_e32 v148, 32, v224
	v_pk_add_f32 v[144:145], v[144:145], 1.0 op_sel_hi:[1,0]
	s_nop 0
	v_rcp_f32_e32 v144, v144
	v_rcp_f32_e32 v145, v145
	s_nop 0
	v_pk_mul_f32 v[128:129], v[128:129], v[144:145]
	v_mov_b32_dpp v144, v122 row_shr:2 row_mask:0xf bank_mask:0xf bound_ctrl:1
	v_mov_b32_dpp v145, v123 row_shr:2 row_mask:0xf bank_mask:0xf bound_ctrl:1
	v_pk_mul_f32 v[130:131], v[130:131], v[128:129]
	v_mov_b32_dpp v128, v122 row_shr:1 row_mask:0xf bank_mask:0xf bound_ctrl:1
	v_mov_b32_dpp v129, v123 row_shr:1 row_mask:0xf bank_mask:0xf bound_ctrl:1
	v_pk_add_f32 v[142:143], v[144:145], v[142:143]
	v_pk_add_f32 v[128:129], v[128:129], v[146:147]
	v_pk_fma_f32 v[142:143], v[72:73], v[142:143], v[76:77]
	s_nop 0
	v_pk_fma_f32 v[128:129], v[60:61], v[128:129], v[142:143]
	s_nop 0
	v_pk_fma_f32 v[128:129], v[68:69], v[122:123], v[128:129]
	s_nop 0
	v_pk_mul_f32 v[142:143], v[128:129], s[2:3] op_sel_hi:[1,0]
	s_nop 0
	v_exp_f32_e32 v142, v142
	v_exp_f32_e32 v143, v143
	s_nop 0
	v_pk_add_f32 v[142:143], v[142:143], 1.0 op_sel_hi:[1,0]
	s_nop 0
	v_rcp_f32_e32 v142, v142
	v_rcp_f32_e32 v143, v143
	s_nop 0
	v_pk_mul_f32 v[128:129], v[128:129], v[142:143]
	s_nop 0
	v_pk_mul_f32 v[124:125], v[124:125], v[128:129]
	v_cvt_pk_bf16_f32 v128, v132, v133
	v_cvt_pk_bf16_f32 v129, v136, v137
	v_cvt_pk_bf16_f32 v130, v130, v131
	v_mov_b32_dpp v132, v140 row_shl:14 row_mask:0xf bank_mask:0xf bound_ctrl:1
	v_cvt_pk_bf16_f32 v131, v124, v125
	v_mad_i64_i32 v[124:125], s[74:75], v148, s93, v[138:139]
	v_lshl_add_u64 v[124:125], v[124:125], 0, v[154:155]
	global_store_dwordx4 v[124:125], v[128:131], off sc1
	ds_read_b32 v124, v223 offset:192
	v_mov_b32_dpp v133, v141 row_shl:14 row_mask:0xf bank_mask:0xf bound_ctrl:1
	v_mov_b32_dpp v130, v140 row_shl:15 row_mask:0xf bank_mask:0xf bound_ctrl:1
	v_mov_b32_dpp v131, v141 row_shl:15 row_mask:0xf bank_mask:0xf bound_ctrl:1
	s_waitcnt lgkmcnt(0)
	v_pk_mul_f32 v[118:119], v[118:119], v[124:125] op_sel_hi:[1,0]
	v_pk_mul_f32 v[128:129], v[110:111], v[124:125] op_sel_hi:[1,0]
	v_pk_mul_f32 v[110:111], v[120:121], v[124:125] op_sel_hi:[1,0]
	v_pk_mul_f32 v[120:121], v[112:113], v[124:125] op_sel_hi:[1,0]
	v_pk_mul_f32 v[112:113], v[114:115], v[124:125] op_sel_hi:[1,0]
	v_pk_mul_f32 v[114:115], v[106:107], v[124:125] op_sel_hi:[1,0]
	v_pk_mul_f32 v[106:107], v[116:117], v[124:125] op_sel_hi:[1,0]
	v_pk_mul_f32 v[108:109], v[108:109], v[124:125] op_sel_hi:[1,0]
	v_mov_b32_dpp v124, v118 row_shr:2 row_mask:0xf bank_mask:0xf bound_ctrl:1
	v_mov_b32_dpp v125, v119 row_shr:2 row_mask:0xf bank_mask:0xf bound_ctrl:1
	v_mov_b32_dpp v116, v118 row_shr:1 row_mask:0xf bank_mask:0xf bound_ctrl:1
	v_mov_b32_dpp v117, v119 row_shr:1 row_mask:0xf bank_mask:0xf bound_ctrl:1
	v_pk_add_f32 v[124:125], v[124:125], v[132:133]
	v_pk_add_f32 v[116:117], v[116:117], v[130:131]
	v_pk_fma_f32 v[124:125], v[90:91], v[124:125], v[102:103]
	v_mov_b32_dpp v132, v134 row_shl:14 row_mask:0xf bank_mask:0xf bound_ctrl:1
	v_pk_fma_f32 v[116:117], v[94:95], v[116:117], v[124:125]
	v_mov_b32_dpp v133, v135 row_shl:14 row_mask:0xf bank_mask:0xf bound_ctrl:1
	v_pk_fma_f32 v[116:117], v[98:99], v[118:119], v[116:117]
	v_mov_b32_dpp v130, v134 row_shl:15 row_mask:0xf bank_mask:0xf bound_ctrl:1
	v_pk_mul_f32 v[124:125], v[116:117], s[2:3] op_sel_hi:[1,0]
	v_mov_b32_dpp v131, v135 row_shl:15 row_mask:0xf bank_mask:0xf bound_ctrl:1
	v_exp_f32_e32 v124, v124
	v_exp_f32_e32 v125, v125
	s_nop 0
	v_pk_add_f32 v[124:125], v[124:125], 1.0 op_sel_hi:[1,0]
	s_nop 0
	v_rcp_f32_e32 v124, v124
	v_rcp_f32_e32 v125, v125
	s_nop 0
	v_pk_mul_f32 v[116:117], v[116:117], v[124:125]
	s_nop 0
	v_pk_mul_f32 v[116:117], v[128:129], v[116:117]
	v_mov_b32_dpp v128, v110 row_shr:2 row_mask:0xf bank_mask:0xf bound_ctrl:1
	v_mov_b32_dpp v129, v111 row_shr:2 row_mask:0xf bank_mask:0xf bound_ctrl:1
	v_mov_b32_dpp v124, v110 row_shr:1 row_mask:0xf bank_mask:0xf bound_ctrl:1
	v_mov_b32_dpp v125, v111 row_shr:1 row_mask:0xf bank_mask:0xf bound_ctrl:1
	v_pk_add_f32 v[128:129], v[128:129], v[132:133]
	v_pk_add_f32 v[124:125], v[124:125], v[130:131]
	v_pk_fma_f32 v[128:129], v[92:93], v[128:129], v[104:105]
	v_mov_b32_dpp v130, v126 row_shl:15 row_mask:0xf bank_mask:0xf bound_ctrl:1
	v_pk_fma_f32 v[124:125], v[96:97], v[124:125], v[128:129]
	v_mov_b32_dpp v131, v127 row_shl:15 row_mask:0xf bank_mask:0xf bound_ctrl:1
	v_pk_fma_f32 v[124:125], v[100:101], v[110:111], v[124:125]
	v_mov_b32_dpp v126, v126 row_shl:14 row_mask:0xf bank_mask:0xf bound_ctrl:1
	v_pk_mul_f32 v[128:129], v[124:125], s[2:3] op_sel_hi:[1,0]
	v_mov_b32_dpp v127, v127 row_shl:14 row_mask:0xf bank_mask:0xf bound_ctrl:1
	v_exp_f32_e32 v128, v128
	v_exp_f32_e32 v129, v129
	s_nop 0
	v_pk_add_f32 v[128:129], v[128:129], 1.0 op_sel_hi:[1,0]
	s_nop 0
	v_rcp_f32_e32 v128, v128
	v_rcp_f32_e32 v129, v129
	s_nop 0
	v_pk_mul_f32 v[124:125], v[124:125], v[128:129]
	v_mov_b32_dpp v128, v112 row_shr:2 row_mask:0xf bank_mask:0xf bound_ctrl:1
;     __device__ __forceinline__ void fast(const f32x4 (&acc)[2][2][4][2], const pg8::Unit& u, int wr, int wc, int fr, int fq, RsCache& rsc) const {
;     ...
;                 const int row = rowb + m * 16 + fr; const float s = rsc.tab[ai * 64 + m * 16 + fr]; const f32x2 s2 = (f32x2){s, s};
;                 f32x2 g[4], o[4], v[4];
; #pragma unroll
;                 for (int cp = 0; cp < 4; ++cp) { const int n = cp >> 1, e0 = (cp & 1) * 2;
;                     g[cp] = (f32x2){acc[ai][0][m][n][e0], acc[ai][0][m][n][e0 + 1]} * s2; v[cp] = (f32x2){acc[ai][1][m][n][e0], acc[ai][1][m][n][e0 + 1]} * s2; }
; #pragma unroll
;                 for (int cp = 0; cp < 4; ++cp) {
;                     f32x2 p1 = (f32x2){dppz<0x111>(g[cp].x), dppz<0x111>(g[cp].y)}, p2 = (f32x2){dppz<0x112>(g[cp].x), dppz<0x112>(g[cp].y)};
;                     if (m > 0) { p1 += (f32x2){dppz<0x10F>(gp[cp].x), dppz<0x10F>(gp[cp].y)}; p2 += (f32x2){dppz<0x10E>(gp[cp].x), dppz<0x10E>(gp[cp].y)}; }
;                     const f32x2 gv = bb[cp] + w0[cp] * p2 + w1[cp] * p1 + w2[cp] * g[cp];
;                     const f32x2 ea = gv * (-1.44269504089f);
;                     f32x2 ex; ex.x = __builtin_amdgcn_exp2f(ea.x); ex.y = __builtin_amdgcn_exp2f(ea.y);
;                     const f32x2 dn = ex + 1.0f;
;                     f32x2 rc; rc.x = __builtin_amdgcn_rcpf(dn.x); rc.y = __builtin_amdgcn_rcpf(dn.y);
;                     o[cp] = (gv * rc) * v[cp];
;                 }
;                 if (m > 0 || fr >= 2) { uint4 w; w.x = pk2(o[0].x, o[0].y); w.y = pk2(o[1].x, o[1].y); w.z = pk2(o[2].x, o[2].y); w.w = pk2(o[3].x, o[3].y); *(uint4*)(act + (size_t)row * FH + ch) = w; }
;                 if (m == 0 && fr < 2) { uint4 w; w.x = pk2(g[0].x, g[0].y); w.y = pk2(g[1].x, g[1].y); w.z = pk2(g[2].x, g[2].y); w.w = pk2(g[3].x, g[3].y); *(uint4*)(sideg + ((size_t)blk * 4 + fr) * FH + ch) = w;
;                     uint4 q; q.x = pk2(v[0].x, v[0].y); q.y = pk2(v[1].x, v[1].y); q.z = pk2(v[2].x, v[2].y); q.w = pk2(v[3].x, v[3].y); *(uint4*)(sidev + ((size_t)blk * 2 + fr) * FH + ch) = q; }
;                 if (m == 3 && fr >= 14) { uint4 w; w.x = pk2(g[0].x, g[0].y); w.y = pk2(g[1].x, g[1].y); w.z = pk2(g[2].x, g[2].y); w.w = pk2(g[3].x, g[3].y); *(uint4*)(sideg + ((size_t)blk * 4 + 2 + (fr - 14)) * FH + ch) = w; }
	v_mov_b32_dpp v129, v113 row_shr:2 row_mask:0xf bank_mask:0xf bound_ctrl:1
	v_pk_mul_f32 v[120:121], v[120:121], v[124:125]
	v_mov_b32_dpp v124, v112 row_shr:1 row_mask:0xf bank_mask:0xf bound_ctrl:1
	v_mov_b32_dpp v125, v113 row_shr:1 row_mask:0xf bank_mask:0xf bound_ctrl:1
	v_pk_add_f32 v[126:127], v[128:129], v[126:127]
	v_pk_add_f32 v[124:125], v[124:125], v[130:131]
	v_pk_fma_f32 v[126:127], v[70:71], v[126:127], v[74:75]
	v_mov_b32_dpp v128, v122 row_shl:15 row_mask:0xf bank_mask:0xf bound_ctrl:1
	v_pk_fma_f32 v[124:125], v[58:59], v[124:125], v[126:127]
	v_mov_b32_dpp v129, v123 row_shl:15 row_mask:0xf bank_mask:0xf bound_ctrl:1
	v_pk_fma_f32 v[124:125], v[66:67], v[112:113], v[124:125]
	v_mov_b32_dpp v122, v122 row_shl:14 row_mask:0xf bank_mask:0xf bound_ctrl:1
	v_pk_mul_f32 v[126:127], v[124:125], s[2:3] op_sel_hi:[1,0]
	v_mov_b32_dpp v123, v123 row_shl:14 row_mask:0xf bank_mask:0xf bound_ctrl:1
	v_exp_f32_e32 v126, v126
	v_exp_f32_e32 v127, v127
	v_add_u32_e32 v130, 48, v224
	v_pk_add_f32 v[126:127], v[126:127], 1.0 op_sel_hi:[1,0]
	s_nop 0
	v_rcp_f32_e32 v126, v126
	v_rcp_f32_e32 v127, v127
	s_nop 0
	v_pk_mul_f32 v[124:125], v[124:125], v[126:127]
	v_mov_b32_dpp v126, v106 row_shr:2 row_mask:0xf bank_mask:0xf bound_ctrl:1
	v_mov_b32_dpp v127, v107 row_shr:2 row_mask:0xf bank_mask:0xf bound_ctrl:1
	v_pk_mul_f32 v[124:125], v[114:115], v[124:125]
	v_mov_b32_dpp v114, v106 row_shr:1 row_mask:0xf bank_mask:0xf bound_ctrl:1
	v_mov_b32_dpp v115, v107 row_shr:1 row_mask:0xf bank_mask:0xf bound_ctrl:1
	v_pk_add_f32 v[122:123], v[126:127], v[122:123]
	v_pk_add_f32 v[114:115], v[114:115], v[128:129]
	v_pk_fma_f32 v[122:123], v[72:73], v[122:123], v[76:77]
	s_nop 0
	v_pk_fma_f32 v[114:115], v[60:61], v[114:115], v[122:123]
	s_nop 0
	v_pk_fma_f32 v[114:115], v[68:69], v[106:107], v[114:115]
	s_nop 0
	v_pk_mul_f32 v[122:123], v[114:115], s[2:3] op_sel_hi:[1,0]
	s_nop 0
	v_exp_f32_e32 v122, v122
	v_exp_f32_e32 v123, v123
	s_nop 0
	v_pk_add_f32 v[122:123], v[122:123], 1.0 op_sel_hi:[1,0]
	s_nop 0
	v_rcp_f32_e32 v122, v122
	v_rcp_f32_e32 v123, v123
	s_nop 0
	v_pk_mul_f32 v[114:115], v[114:115], v[122:123]
	s_nop 0
	v_pk_mul_f32 v[108:109], v[108:109], v[114:115]
	v_cvt_pk_bf16_f32 v114, v116, v117
	v_cvt_pk_bf16_f32 v115, v120, v121
	v_cvt_pk_bf16_f32 v116, v124, v125
	s_nop 0
	v_cvt_pk_bf16_f32 v117, v108, v109
	v_mad_i64_i32 v[108:109], s[74:75], v130, s93, v[138:139]
	v_lshl_add_u64 v[108:109], v[108:109], 0, v[154:155]
	global_store_dwordx4 v[108:109], v[114:117], off sc1
	s_and_saveexec_b64 s[82:83], vcc
	s_cbranch_execz .LBB0_272
	v_lshl_add_u64 v[114:115], s[0:1], 0, v[156:157]
	v_readlane_b32 s0, v254, 1
	v_readlane_b32 s1, v254, 2
	v_cvt_pk_bf16_f32 v108, v118, v119
	v_cvt_pk_bf16_f32 v109, v110, v111
	v_cvt_pk_bf16_f32 v110, v112, v113
	v_cvt_pk_bf16_f32 v111, v106, v107
	s_nop 1
	v_mov_b64_e32 v[106:107], s[0:1]
	v_mad_u64_u32 v[106:107], s[0:1], v114, s93, v[106:107]
	v_mad_i32_i24 v107, v115, s93, v107
	v_lshl_add_u64 v[106:107], v[184:185], 1, v[106:107]
	global_store_dwordx4 v[106:107], v[108:111], off sc1
.LBB0_272:
	s_or_b64 exec, exec, s[82:83]
	ds_read_b32 v110, v223 offset:256
	s_add_i32 s2, s3, 0x80
	v_add_u32_e32 v122, s2, v186
	s_waitcnt lgkmcnt(0)
	v_pk_mul_f32 v[106:107], v[86:87], v[110:111] op_sel_hi:[1,0]
	v_pk_mul_f32 v[108:109], v[78:79], v[110:111] op_sel_hi:[1,0]
	v_pk_mul_f32 v[86:87], v[88:89], v[110:111] op_sel_hi:[1,0]
	v_pk_mul_f32 v[78:79], v[82:83], v[110:111] op_sel_hi:[1,0]
	v_pk_mul_f32 v[82:83], v[62:63], v[110:111] op_sel_hi:[1,0]
	v_pk_mul_f32 v[62:63], v[84:85], v[110:111] op_sel_hi:[1,0]
	v_pk_mul_f32 v[80:81], v[80:81], v[110:111] op_sel_hi:[1,0]
	v_pk_mul_f32 v[64:65], v[64:65], v[110:111] op_sel_hi:[1,0]
	v_mov_b32_dpp v110, v106 row_shr:1 row_mask:0xf bank_mask:0xf bound_ctrl:1
	v_mov_b32_dpp v111, v107 row_shr:1 row_mask:0xf bank_mask:0xf bound_ctrl:1
	v_mov_b32_dpp v112, v106 row_shr:2 row_mask:0xf bank_mask:0xf bound_ctrl:1
	v_mov_b32_dpp v113, v107 row_shr:2 row_mask:0xf bank_mask:0xf bound_ctrl:1
	v_mov_b32_dpp v114, v86 row_shr:1 row_mask:0xf bank_mask:0xf bound_ctrl:1
	v_mov_b32_dpp v115, v87 row_shr:1 row_mask:0xf bank_mask:0xf bound_ctrl:1
	v_mov_b32_dpp v116, v86 row_shr:2 row_mask:0xf bank_mask:0xf bound_ctrl:1
	v_mov_b32_dpp v117, v87 row_shr:2 row_mask:0xf bank_mask:0xf bound_ctrl:1
	v_mov_b32_dpp v118, v78 row_shr:1 row_mask:0xf bank_mask:0xf bound_ctrl:1
	v_mov_b32_dpp v119, v79 row_shr:1 row_mask:0xf bank_mask:0xf bound_ctrl:1
	v_mov_b32_dpp v120, v78 row_shr:2 row_mask:0xf bank_mask:0xf bound_ctrl:1
	v_mov_b32_dpp v121, v79 row_shr:2 row_mask:0xf bank_mask:0xf bound_ctrl:1
	v_mov_b32_dpp v84, v62 row_shr:1 row_mask:0xf bank_mask:0xf bound_ctrl:1
	v_mov_b32_dpp v85, v63 row_shr:1 row_mask:0xf bank_mask:0xf bound_ctrl:1
	v_mov_b32_dpp v88, v62 row_shr:2 row_mask:0xf bank_mask:0xf bound_ctrl:1
	v_mov_b32_dpp v89, v63 row_shr:2 row_mask:0xf bank_mask:0xf bound_ctrl:1
	s_and_saveexec_b64 s[0:1], s[6:7]
	s_cbranch_execz .LBB0_274
;     __device__ __forceinline__ void fast(const f32x4 (&acc)[2][2][4][2], const pg8::Unit& u, int wr, int wc, int fr, int fq, RsCache& rsc) const {
;     ...
;                 const int row = rowb + m * 16 + fr; const float s = rsc.tab[ai * 64 + m * 16 + fr]; const f32x2 s2 = (f32x2){s, s};
;                 f32x2 g[4], o[4], v[4];
; #pragma unroll
;                 for (int cp = 0; cp < 4; ++cp) { const int n = cp >> 1, e0 = (cp & 1) * 2;
;                     g[cp] = (f32x2){acc[ai][0][m][n][e0], acc[ai][0][m][n][e0 + 1]} * s2; v[cp] = (f32x2){acc[ai][1][m][n][e0], acc[ai][1][m][n][e0 + 1]} * s2; }
; #pragma unroll
;                 for (int cp = 0; cp < 4; ++cp) {
;                     f32x2 p1 = (f32x2){dppz<0x111>(g[cp].x), dppz<0x111>(g[cp].y)}, p2 = (f32x2){dppz<0x112>(g[cp].x), dppz<0x112>(g[cp].y)};
;                     if (m > 0) { p1 += (f32x2){dppz<0x10F>(gp[cp].x), dppz<0x10F>(gp[cp].y)}; p2 += (f32x2){dppz<0x10E>(gp[cp].x), dppz<0x10E>(gp[cp].y)}; }
;                     const f32x2 gv = bb[cp] + w0[cp] * p2 + w1[cp] * p1 + w2[cp] * g[cp];
;                     const f32x2 ea = gv * (-1.44269504089f);
;                     f32x2 ex; ex.x = __builtin_amdgcn_exp2f(ea.x); ex.y = __builtin_amdgcn_exp2f(ea.y);
;                     const f32x2 dn = ex + 1.0f;
;                     f32x2 rc; rc.x = __builtin_amdgcn_rcpf(dn.x); rc.y = __builtin_amdgcn_rcpf(dn.y);
;                     o[cp] = (gv * rc) * v[cp];
;                 }
;                 if (m > 0 || fr >= 2) { uint4 w; w.x = pk2(o[0].x, o[0].y); w.y = pk2(o[1].x, o[1].y); w.z = pk2(o[2].x, o[2].y); w.w = pk2(o[3].x, o[3].y); *(uint4*)(act + (size_t)row * FH + ch) = w; }
;                 if (m == 0 && fr < 2) { uint4 w; w.x = pk2(g[0].x, g[0].y); w.y = pk2(g[1].x, g[1].y); w.z = pk2(g[2].x, g[2].y); w.w = pk2(g[3].x, g[3].y); *(uint4*)(sideg + ((size_t)blk * 4 + fr) * FH + ch) = w;
;                     uint4 q; q.x = pk2(v[0].x, v[0].y); q.y = pk2(v[1].x, v[1].y); q.z = pk2(v[2].x, v[2].y); q.w = pk2(v[3].x, v[3].y); *(uint4*)(sidev + ((size_t)blk * 2 + fr) * FH + ch) = q; }
;                 if (m == 3 && fr >= 14) { uint4 w; w.x = pk2(g[0].x, g[0].y); w.y = pk2(g[1].x, g[1].y); w.z = pk2(g[2].x, g[2].y); w.w = pk2(g[3].x, g[3].y); *(uint4*)(sideg + ((size_t)blk * 4 + 2 + (fr - 14)) * FH + ch) = w; }
	v_pk_fma_f32 v[112:113], v[90:91], v[112:113], v[102:103]
	v_pk_fma_f32 v[88:89], v[72:73], v[88:89], v[76:77]
	v_pk_fma_f32 v[120:121], v[70:71], v[120:121], v[74:75]
	v_pk_fma_f32 v[116:117], v[92:93], v[116:117], v[104:105]
	v_pk_fma_f32 v[110:111], v[94:95], v[110:111], v[112:113]
	v_pk_fma_f32 v[84:85], v[60:61], v[84:85], v[88:89]
	v_pk_fma_f32 v[118:119], v[58:59], v[118:119], v[120:121]
	s_mov_b32 s6, 0xbfb8aa3b
	v_pk_fma_f32 v[114:115], v[96:97], v[114:115], v[116:117]
	v_pk_fma_f32 v[110:111], v[98:99], v[106:107], v[110:111]
	v_pk_fma_f32 v[84:85], v[68:69], v[62:63], v[84:85]
	v_pk_fma_f32 v[118:119], v[66:67], v[78:79], v[118:119]
	v_pk_fma_f32 v[114:115], v[100:101], v[86:87], v[114:115]
	v_pk_mul_f32 v[112:113], v[110:111], s[6:7] op_sel_hi:[1,0]
	v_pk_mul_f32 v[88:89], v[84:85], s[6:7] op_sel_hi:[1,0]
	v_pk_mul_f32 v[120:121], v[118:119], s[6:7] op_sel_hi:[1,0]
	v_pk_mul_f32 v[116:117], v[114:115], s[6:7] op_sel_hi:[1,0]
	v_exp_f32_e32 v112, v112
	v_exp_f32_e32 v113, v113
	v_exp_f32_e32 v88, v88
	v_exp_f32_e32 v89, v89
	v_exp_f32_e32 v120, v120
	v_exp_f32_e32 v121, v121
	v_exp_f32_e32 v116, v116
	v_exp_f32_e32 v117, v117
	v_pk_add_f32 v[112:113], v[112:113], 1.0 op_sel_hi:[1,0]
	v_pk_add_f32 v[88:89], v[88:89], 1.0 op_sel_hi:[1,0]
	v_pk_add_f32 v[120:121], v[120:121], 1.0 op_sel_hi:[1,0]
	v_pk_add_f32 v[116:117], v[116:117], 1.0 op_sel_hi:[1,0]
	v_rcp_f32_e32 v112, v112
	v_rcp_f32_e32 v113, v113
	v_rcp_f32_e32 v88, v88
	v_rcp_f32_e32 v89, v89
	v_rcp_f32_e32 v120, v120
	v_rcp_f32_e32 v121, v121
	v_rcp_f32_e32 v116, v116
	v_rcp_f32_e32 v117, v117
	v_pk_mul_f32 v[110:111], v[110:111], v[112:113]
	v_pk_mul_f32 v[84:85], v[84:85], v[88:89]
	v_readlane_b32 s6, v253, 16
	v_pk_mul_f32 v[118:119], v[118:119], v[120:121]
	v_pk_mul_f32 v[114:115], v[114:115], v[116:117]
	v_pk_mul_f32 v[110:111], v[108:109], v[110:111]
	v_pk_mul_f32 v[84:85], v[64:65], v[84:85]
	v_readlane_b32 s7, v253, 17
	v_pk_mul_f32 v[118:119], v[82:83], v[118:119]
	v_pk_mul_f32 v[114:115], v[80:81], v[114:115]
	v_cvt_pk_bf16_f32 v110, v110, v111
	s_nop 0
	v_cvt_pk_bf16_f32 v111, v114, v115
	v_cvt_pk_bf16_f32 v112, v118, v119
	v_cvt_pk_bf16_f32 v113, v84, v85
	v_mov_b64_e32 v[84:85], s[6:7]
	v_mad_i64_i32 v[84:85], s[6:7], v122, s93, v[84:85]
	v_lshl_add_u64 v[84:85], v[184:185], 1, v[84:85]
	global_store_dwordx4 v[84:85], v[110:113], off sc1
.LBB0_274:
	s_or_b64 exec, exec, s[0:1]
	s_ashr_i32 s0, s2, 6
	s_ashr_i32 s1, s0, 31
	s_lshl_b64 s[6:7], s[0:1], 2
	s_and_saveexec_b64 s[82:83], s[8:9]
	s_cbranch_execz .LBB0_276
	v_lshl_add_u64 v[84:85], s[6:7], 0, v[186:187]
	s_lshl_b64 s[0:1], s[0:1], 1
	v_mov_b32_e32 v88, s1
	v_subrev_co_u32_e64 v114, s[0:1], s0, v84
	v_cvt_pk_bf16_f32 v110, v106, v107
	v_cvt_pk_bf16_f32 v111, v86, v87
	v_cvt_pk_bf16_f32 v112, v78, v79
	v_cvt_pk_bf16_f32 v113, v62, v63
	s_nop 1
	v_subb_co_u32_e64 v115, s[0:1], v85, v88, s[0:1]
	v_readlane_b32 s0, v254, 1
	v_readlane_b32 s1, v254, 2
	s_nop 1
	v_mov_b64_e32 v[88:89], s[0:1]
	v_mad_u64_u32 v[88:89], s[0:1], v84, s93, v[88:89]
	v_mad_i32_i24 v89, v85, s93, v89
	v_readlane_b32 s0, v254, 15
	v_lshl_add_u64 v[84:85], v[88:89], 0, v[154:155]
	v_readlane_b32 s1, v254, 16
	global_store_dwordx4 v[84:85], v[110:113], off sc1
	v_cvt_pk_bf16_f32 v108, v108, v109
	v_cvt_pk_bf16_f32 v109, v80, v81
	s_nop 1
	v_cvt_pk_bf16_f32 v110, v82, v83
	v_cvt_pk_bf16_f32 v111, v64, v65
	v_mov_b64_e32 v[64:65], s[0:1]
	v_mad_u64_u32 v[64:65], s[0:1], v114, s93, v[64:65]
	v_mad_i32_i24 v65, v115, s93, v65
	v_lshl_add_u64 v[64:65], v[64:65], 0, v[154:155]
	global_store_dwordx4 v[64:65], v[108:111], off sc1
.LBB0_276:
	s_or_b64 exec, exec, s[82:83]
	ds_read_b32 v80, v223 offset:320
	v_mov_b32_dpp v84, v106 row_shl:14 row_mask:0xf bank_mask:0xf bound_ctrl:1
	v_mov_b32_dpp v85, v107 row_shl:14 row_mask:0xf bank_mask:0xf bound_ctrl:1
	s_mov_b32 s2, 0xbfb8aa3b
	v_readlane_b32 s0, v253, 16
	s_waitcnt lgkmcnt(0)
	v_pk_mul_f32 v[64:65], v[54:55], v[80:81] op_sel_hi:[1,0]
	v_pk_mul_f32 v[82:83], v[46:47], v[80:81] op_sel_hi:[1,0]
	v_pk_mul_f32 v[46:47], v[52:53], v[80:81] op_sel_hi:[1,0]
	v_mov_b32_dpp v52, v64 row_shr:2 row_mask:0xf bank_mask:0xf bound_ctrl:1
	v_mov_b32_dpp v53, v65 row_shr:2 row_mask:0xf bank_mask:0xf bound_ctrl:1
	v_pk_mul_f32 v[54:55], v[56:57], v[80:81] op_sel_hi:[1,0]
	v_pk_mul_f32 v[56:57], v[48:49], v[80:81] op_sel_hi:[1,0]
	v_pk_mul_f32 v[48:49], v[50:51], v[80:81] op_sel_hi:[1,0]
	v_pk_mul_f32 v[42:43], v[42:43], v[80:81] op_sel_hi:[1,0]
	v_pk_mul_f32 v[44:45], v[44:45], v[80:81] op_sel_hi:[1,0]
	v_mov_b32_dpp v50, v64 row_shr:1 row_mask:0xf bank_mask:0xf bound_ctrl:1
	v_mov_b32_dpp v51, v65 row_shr:1 row_mask:0xf bank_mask:0xf bound_ctrl:1
	v_mov_b32_dpp v80, v106 row_shl:15 row_mask:0xf bank_mask:0xf bound_ctrl:1
	v_mov_b32_dpp v81, v107 row_shl:15 row_mask:0xf bank_mask:0xf bound_ctrl:1
	v_pk_add_f32 v[52:53], v[52:53], v[84:85]
	v_pk_add_f32 v[50:51], v[50:51], v[80:81]
	v_pk_fma_f32 v[52:53], v[90:91], v[52:53], v[102:103]
	v_mov_b32_dpp v80, v54 row_shr:2 row_mask:0xf bank_mask:0xf bound_ctrl:1
	v_pk_fma_f32 v[50:51], v[94:95], v[50:51], v[52:53]
	v_mov_b32_dpp v81, v55 row_shr:2 row_mask:0xf bank_mask:0xf bound_ctrl:1
	v_pk_fma_f32 v[50:51], v[98:99], v[64:65], v[50:51]
	v_mov_b32_dpp v84, v86 row_shl:14 row_mask:0xf bank_mask:0xf bound_ctrl:1
	v_pk_mul_f32 v[52:53], v[50:51], s[2:3] op_sel_hi:[1,0]
	v_mov_b32_dpp v85, v87 row_shl:14 row_mask:0xf bank_mask:0xf bound_ctrl:1
	v_exp_f32_e32 v52, v52
	v_exp_f32_e32 v53, v53
	v_pk_add_f32 v[80:81], v[80:81], v[84:85]
	v_readlane_b32 s1, v253, 17
	v_pk_fma_f32 v[80:81], v[92:93], v[80:81], v[104:105]
	v_pk_add_f32 v[52:53], v[52:53], 1.0 op_sel_hi:[1,0]
; __device__ __forceinline__ unsigned pk2(float lo, float hi) { unsigned r; asm volatile("v_cvt_pk_bf16_f32 %0, %1, %2" : "=v"(r) : "v"(lo), "v"(hi)); return r; }
; template <int CTRL> __device__ __forceinline__ float dppz(float x) { return __builtin_bit_cast(float, __builtin_amdgcn_update_dpp(0, __builtin_bit_cast(int, x), CTRL, 0xf, 0xf, true)); }
;     __device__ __forceinline__ void fast(const f32x4 (&acc)[2][2][4][2], const pg8::Unit& u, int wr, int wc, int fr, int fq, RsCache& rsc) const {
;     ...
;                 const int row = rowb + m * 16 + fr; const float s = rsc.tab[ai * 64 + m * 16 + fr]; const f32x2 s2 = (f32x2){s, s};
;                 f32x2 g[4], o[4], v[4];
; #pragma unroll
;                 for (int cp = 0; cp < 4; ++cp) { const int n = cp >> 1, e0 = (cp & 1) * 2;
;                     g[cp] = (f32x2){acc[ai][0][m][n][e0], acc[ai][0][m][n][e0 + 1]} * s2; v[cp] = (f32x2){acc[ai][1][m][n][e0], acc[ai][1][m][n][e0 + 1]} * s2; }
; #pragma unroll
;                 for (int cp = 0; cp < 4; ++cp) {
;                     f32x2 p1 = (f32x2){dppz<0x111>(g[cp].x), dppz<0x111>(g[cp].y)}, p2 = (f32x2){dppz<0x112>(g[cp].x), dppz<0x112>(g[cp].y)};
;                     if (m > 0) { p1 += (f32x2){dppz<0x10F>(gp[cp].x), dppz<0x10F>(gp[cp].y)}; p2 += (f32x2){dppz<0x10E>(gp[cp].x), dppz<0x10E>(gp[cp].y)}; }
;                     const f32x2 gv = bb[cp] + w0[cp] * p2 + w1[cp] * p1 + w2[cp] * g[cp];
;                     const f32x2 ea = gv * (-1.44269504089f);
;                     f32x2 ex; ex.x = __builtin_amdgcn_exp2f(ea.x); ex.y = __builtin_amdgcn_exp2f(ea.y);
;                     const f32x2 dn = ex + 1.0f;
;                     f32x2 rc; rc.x = __builtin_amdgcn_rcpf(dn.x); rc.y = __builtin_amdgcn_rcpf(dn.y);
;                     o[cp] = (gv * rc) * v[cp];
;                 }
;                 if (m > 0 || fr >= 2) { uint4 w; w.x = pk2(o[0].x, o[0].y); w.y = pk2(o[1].x, o[1].y); w.z = pk2(o[2].x, o[2].y); w.w = pk2(o[3].x, o[3].y); *(uint4*)(act + (size_t)row * FH + ch) = w; }
	s_nop 0
	v_rcp_f32_e32 v52, v52
	v_rcp_f32_e32 v53, v53
	s_nop 0
	v_pk_mul_f32 v[50:51], v[50:51], v[52:53]
	s_nop 0
	v_pk_mul_f32 v[50:51], v[82:83], v[50:51]
	v_mov_b32_dpp v52, v54 row_shr:1 row_mask:0xf bank_mask:0xf bound_ctrl:1
	v_mov_b32_dpp v53, v55 row_shr:1 row_mask:0xf bank_mask:0xf bound_ctrl:1
	v_mov_b32_dpp v82, v86 row_shl:15 row_mask:0xf bank_mask:0xf bound_ctrl:1
	v_mov_b32_dpp v83, v87 row_shl:15 row_mask:0xf bank_mask:0xf bound_ctrl:1
	v_pk_add_f32 v[52:53], v[52:53], v[82:83]
	v_mov_b32_dpp v82, v78 row_shl:15 row_mask:0xf bank_mask:0xf bound_ctrl:1
	v_pk_fma_f32 v[52:53], v[96:97], v[52:53], v[80:81]
	v_mov_b32_dpp v83, v79 row_shl:15 row_mask:0xf bank_mask:0xf bound_ctrl:1
	v_pk_fma_f32 v[52:53], v[100:101], v[54:55], v[52:53]
	v_mov_b32_dpp v78, v78 row_shl:14 row_mask:0xf bank_mask:0xf bound_ctrl:1
	v_pk_mul_f32 v[80:81], v[52:53], s[2:3] op_sel_hi:[1,0]
	v_mov_b32_dpp v79, v79 row_shl:14 row_mask:0xf bank_mask:0xf bound_ctrl:1
	v_exp_f32_e32 v80, v80
	v_exp_f32_e32 v81, v81
	v_cvt_pk_bf16_f32 v50, v50, v51
	s_nop 0
	v_pk_add_f32 v[80:81], v[80:81], 1.0 op_sel_hi:[1,0]
	s_nop 0
	v_rcp_f32_e32 v80, v80
	v_rcp_f32_e32 v81, v81
	s_nop 0
	v_pk_mul_f32 v[52:53], v[52:53], v[80:81]
	v_mov_b32_dpp v80, v48 row_shr:2 row_mask:0xf bank_mask:0xf bound_ctrl:1
	v_mov_b32_dpp v81, v49 row_shr:2 row_mask:0xf bank_mask:0xf bound_ctrl:1
	v_pk_mul_f32 v[52:53], v[56:57], v[52:53]
	v_mov_b32_dpp v56, v48 row_shr:1 row_mask:0xf bank_mask:0xf bound_ctrl:1
	v_mov_b32_dpp v57, v49 row_shr:1 row_mask:0xf bank_mask:0xf bound_ctrl:1
	v_pk_add_f32 v[78:79], v[80:81], v[78:79]
	v_pk_add_f32 v[56:57], v[56:57], v[82:83]
	v_pk_fma_f32 v[78:79], v[70:71], v[78:79], v[74:75]
	v_mov_b32_dpp v80, v62 row_shl:15 row_mask:0xf bank_mask:0xf bound_ctrl:1
	v_pk_fma_f32 v[56:57], v[58:59], v[56:57], v[78:79]
	v_mov_b32_dpp v81, v63 row_shl:15 row_mask:0xf bank_mask:0xf bound_ctrl:1
	v_pk_fma_f32 v[56:57], v[66:67], v[48:49], v[56:57]
	v_mov_b32_dpp v62, v62 row_shl:14 row_mask:0xf bank_mask:0xf bound_ctrl:1
	v_pk_mul_f32 v[78:79], v[56:57], s[2:3] op_sel_hi:[1,0]
	v_mov_b32_dpp v63, v63 row_shl:14 row_mask:0xf bank_mask:0xf bound_ctrl:1
	v_exp_f32_e32 v78, v78
	v_exp_f32_e32 v79, v79
	v_add_u32_e32 v82, 16, v122
	v_cvt_pk_bf16_f32 v51, v52, v53
	v_pk_add_f32 v[78:79], v[78:79], 1.0 op_sel_hi:[1,0]
	s_nop 0
	v_rcp_f32_e32 v78, v78
	v_rcp_f32_e32 v79, v79
	s_nop 0
	v_pk_mul_f32 v[56:57], v[56:57], v[78:79]
	v_mov_b32_dpp v78, v46 row_shr:2 row_mask:0xf bank_mask:0xf bound_ctrl:1
	v_mov_b32_dpp v79, v47 row_shr:2 row_mask:0xf bank_mask:0xf bound_ctrl:1
	v_pk_mul_f32 v[42:43], v[42:43], v[56:57]
	v_mov_b32_dpp v56, v46 row_shr:1 row_mask:0xf bank_mask:0xf bound_ctrl:1
	v_mov_b32_dpp v57, v47 row_shr:1 row_mask:0xf bank_mask:0xf bound_ctrl:1
	v_pk_add_f32 v[62:63], v[78:79], v[62:63]
	v_pk_add_f32 v[56:57], v[56:57], v[80:81]
	v_pk_fma_f32 v[62:63], v[72:73], v[62:63], v[76:77]
	v_cvt_pk_bf16_f32 v52, v42, v43
	v_mov_b64_e32 v[42:43], s[0:1]
	v_pk_fma_f32 v[56:57], v[60:61], v[56:57], v[62:63]
	s_nop 0
	v_pk_fma_f32 v[56:57], v[68:69], v[46:47], v[56:57]
	s_nop 0
	v_pk_mul_f32 v[62:63], v[56:57], s[2:3] op_sel_hi:[1,0]
	s_nop 0
	v_exp_f32_e32 v62, v62
	v_exp_f32_e32 v63, v63
	s_nop 0
	v_pk_add_f32 v[62:63], v[62:63], 1.0 op_sel_hi:[1,0]
	s_nop 0
	v_rcp_f32_e32 v62, v62
	v_rcp_f32_e32 v63, v63
	s_nop 0
	v_pk_mul_f32 v[56:57], v[56:57], v[62:63]
	s_nop 0
	v_pk_mul_f32 v[44:45], v[44:45], v[56:57]
	v_mov_b32_dpp v56, v64 row_shl:14 row_mask:0xf bank_mask:0xf bound_ctrl:1
	v_cvt_pk_bf16_f32 v53, v44, v45
	v_mad_i64_i32 v[44:45], s[0:1], v82, s93, v[42:43]
	v_lshl_add_u64 v[44:45], v[44:45], 0, v[154:155]
	global_store_dwordx4 v[44:45], v[50:53], off sc1
	ds_read_b32 v50, v223 offset:384
	v_mov_b32_dpp v57, v65 row_shl:14 row_mask:0xf bank_mask:0xf bound_ctrl:1
	s_waitcnt lgkmcnt(0)
	v_pk_mul_f32 v[44:45], v[38:39], v[50:51] op_sel_hi:[1,0]
	v_pk_mul_f32 v[38:39], v[40:41], v[50:51] op_sel_hi:[1,0]
	s_nop 0
	v_mov_b32_dpp v40, v44 row_shr:2 row_mask:0xf bank_mask:0xf bound_ctrl:1
	v_mov_b32_dpp v41, v45 row_shr:2 row_mask:0xf bank_mask:0xf bound_ctrl:1
	v_pk_mul_f32 v[52:53], v[30:31], v[50:51] op_sel_hi:[1,0]
	v_pk_mul_f32 v[32:33], v[32:33], v[50:51] op_sel_hi:[1,0]
	v_pk_mul_f32 v[30:31], v[34:35], v[50:51] op_sel_hi:[1,0]
	v_pk_mul_f32 v[34:35], v[26:27], v[50:51] op_sel_hi:[1,0]
	v_pk_mul_f32 v[26:27], v[36:37], v[50:51] op_sel_hi:[1,0]
	v_pk_mul_f32 v[28:29], v[28:29], v[50:51] op_sel_hi:[1,0]
	v_mov_b32_dpp v36, v44 row_shr:1 row_mask:0xf bank_mask:0xf bound_ctrl:1
	v_mov_b32_dpp v37, v45 row_shr:1 row_mask:0xf bank_mask:0xf bound_ctrl:1
	v_mov_b32_dpp v50, v64 row_shl:15 row_mask:0xf bank_mask:0xf bound_ctrl:1
	v_mov_b32_dpp v51, v65 row_shl:15 row_mask:0xf bank_mask:0xf bound_ctrl:1
	v_pk_add_f32 v[40:41], v[40:41], v[56:57]
	v_pk_add_f32 v[36:37], v[36:37], v[50:51]
	v_pk_fma_f32 v[40:41], v[90:91], v[40:41], v[102:103]
	v_mov_b32_dpp v50, v38 row_shr:2 row_mask:0xf bank_mask:0xf bound_ctrl:1
	v_pk_fma_f32 v[36:37], v[94:95], v[36:37], v[40:41]
	v_mov_b32_dpp v51, v39 row_shr:2 row_mask:0xf bank_mask:0xf bound_ctrl:1
	v_pk_fma_f32 v[36:37], v[98:99], v[44:45], v[36:37]
	s_nop 0
	v_pk_mul_f32 v[40:41], v[36:37], s[2:3] op_sel_hi:[1,0]
	s_nop 0
	v_exp_f32_e32 v40, v40
	v_exp_f32_e32 v41, v41
	s_nop 0
	v_pk_add_f32 v[40:41], v[40:41], 1.0 op_sel_hi:[1,0]
	s_nop 0
	v_rcp_f32_e32 v40, v40
	v_rcp_f32_e32 v41, v41
	s_nop 0
	v_pk_mul_f32 v[36:37], v[36:37], v[40:41]
	s_nop 0
	v_pk_mul_f32 v[36:37], v[52:53], v[36:37]
	v_mov_b32_dpp v52, v54 row_shl:15 row_mask:0xf bank_mask:0xf bound_ctrl:1
	v_mov_b32_dpp v53, v55 row_shl:15 row_mask:0xf bank_mask:0xf bound_ctrl:1
; __device__ __forceinline__ unsigned pk2(float lo, float hi) { unsigned r; asm volatile("v_cvt_pk_bf16_f32 %0, %1, %2" : "=v"(r) : "v"(lo), "v"(hi)); return r; }
; template <int CTRL> __device__ __forceinline__ float dppz(float x) { return __builtin_bit_cast(float, __builtin_amdgcn_update_dpp(0, __builtin_bit_cast(int, x), CTRL, 0xf, 0xf, true)); }
;     __device__ __forceinline__ void fast(const f32x4 (&acc)[2][2][4][2], const pg8::Unit& u, int wr, int wc, int fr, int fq, RsCache& rsc) const {
;     ...
;                 const int row = rowb + m * 16 + fr; const float s = rsc.tab[ai * 64 + m * 16 + fr]; const f32x2 s2 = (f32x2){s, s};
;                 f32x2 g[4], o[4], v[4];
; #pragma unroll
;                 for (int cp = 0; cp < 4; ++cp) { const int n = cp >> 1, e0 = (cp & 1) * 2;
;                     g[cp] = (f32x2){acc[ai][0][m][n][e0], acc[ai][0][m][n][e0 + 1]} * s2; v[cp] = (f32x2){acc[ai][1][m][n][e0], acc[ai][1][m][n][e0 + 1]} * s2; }
; #pragma unroll
;                 for (int cp = 0; cp < 4; ++cp) {
;                     f32x2 p1 = (f32x2){dppz<0x111>(g[cp].x), dppz<0x111>(g[cp].y)}, p2 = (f32x2){dppz<0x112>(g[cp].x), dppz<0x112>(g[cp].y)};
;                     if (m > 0) { p1 += (f32x2){dppz<0x10F>(gp[cp].x), dppz<0x10F>(gp[cp].y)}; p2 += (f32x2){dppz<0x10E>(gp[cp].x), dppz<0x10E>(gp[cp].y)}; }
;                     const f32x2 gv = bb[cp] + w0[cp] * p2 + w1[cp] * p1 + w2[cp] * g[cp];
;                     const f32x2 ea = gv * (-1.44269504089f);
;                     f32x2 ex; ex.x = __builtin_amdgcn_exp2f(ea.x); ex.y = __builtin_amdgcn_exp2f(ea.y);
;                     const f32x2 dn = ex + 1.0f;
;                     f32x2 rc; rc.x = __builtin_amdgcn_rcpf(dn.x); rc.y = __builtin_amdgcn_rcpf(dn.y);
;                     o[cp] = (gv * rc) * v[cp];
;                 }
;                 if (m > 0 || fr >= 2) { uint4 w; w.x = pk2(o[0].x, o[0].y); w.y = pk2(o[1].x, o[1].y); w.z = pk2(o[2].x, o[2].y); w.w = pk2(o[3].x, o[3].y); *(uint4*)(act + (size_t)row * FH + ch) = w; }
	v_mov_b32_dpp v54, v54 row_shl:14 row_mask:0xf bank_mask:0xf bound_ctrl:1
	v_mov_b32_dpp v55, v55 row_shl:14 row_mask:0xf bank_mask:0xf bound_ctrl:1
	v_mov_b32_dpp v40, v38 row_shr:1 row_mask:0xf bank_mask:0xf bound_ctrl:1
	v_mov_b32_dpp v41, v39 row_shr:1 row_mask:0xf bank_mask:0xf bound_ctrl:1
	v_pk_add_f32 v[50:51], v[50:51], v[54:55]
	v_pk_add_f32 v[40:41], v[40:41], v[52:53]
	v_pk_fma_f32 v[50:51], v[92:93], v[50:51], v[104:105]
	v_mov_b32_dpp v52, v48 row_shl:15 row_mask:0xf bank_mask:0xf bound_ctrl:1
	v_pk_fma_f32 v[40:41], v[96:97], v[40:41], v[50:51]
	v_mov_b32_dpp v53, v49 row_shl:15 row_mask:0xf bank_mask:0xf bound_ctrl:1
	v_pk_fma_f32 v[40:41], v[100:101], v[38:39], v[40:41]
	v_mov_b32_dpp v48, v48 row_shl:14 row_mask:0xf bank_mask:0xf bound_ctrl:1
	v_pk_mul_f32 v[50:51], v[40:41], s[2:3] op_sel_hi:[1,0]
	v_mov_b32_dpp v49, v49 row_shl:14 row_mask:0xf bank_mask:0xf bound_ctrl:1
	v_exp_f32_e32 v50, v50
	v_exp_f32_e32 v51, v51
	s_nop 0
	v_pk_add_f32 v[50:51], v[50:51], 1.0 op_sel_hi:[1,0]
	s_nop 0
	v_rcp_f32_e32 v50, v50
	v_rcp_f32_e32 v51, v51
	s_nop 0
	v_pk_mul_f32 v[40:41], v[40:41], v[50:51]
	v_mov_b32_dpp v50, v30 row_shr:2 row_mask:0xf bank_mask:0xf bound_ctrl:1
	v_mov_b32_dpp v51, v31 row_shr:2 row_mask:0xf bank_mask:0xf bound_ctrl:1
	v_pk_mul_f32 v[40:41], v[32:33], v[40:41]
	v_mov_b32_dpp v32, v30 row_shr:1 row_mask:0xf bank_mask:0xf bound_ctrl:1
	v_mov_b32_dpp v33, v31 row_shr:1 row_mask:0xf bank_mask:0xf bound_ctrl:1
	v_pk_add_f32 v[48:49], v[50:51], v[48:49]
	v_pk_add_f32 v[32:33], v[32:33], v[52:53]
	v_pk_fma_f32 v[48:49], v[70:71], v[48:49], v[74:75]
	v_mov_b32_dpp v50, v46 row_shl:15 row_mask:0xf bank_mask:0xf bound_ctrl:1
	v_pk_fma_f32 v[32:33], v[58:59], v[32:33], v[48:49]
	v_mov_b32_dpp v51, v47 row_shl:15 row_mask:0xf bank_mask:0xf bound_ctrl:1
	v_pk_fma_f32 v[32:33], v[66:67], v[30:31], v[32:33]
	v_mov_b32_dpp v46, v46 row_shl:14 row_mask:0xf bank_mask:0xf bound_ctrl:1
	v_pk_mul_f32 v[48:49], v[32:33], s[2:3] op_sel_hi:[1,0]
	v_mov_b32_dpp v47, v47 row_shl:14 row_mask:0xf bank_mask:0xf bound_ctrl:1
	v_exp_f32_e32 v48, v48
	v_exp_f32_e32 v49, v49
	v_add_u32_e32 v52, 32, v122
	v_pk_add_f32 v[48:49], v[48:49], 1.0 op_sel_hi:[1,0]
	s_nop 0
	v_rcp_f32_e32 v48, v48
	v_rcp_f32_e32 v49, v49
	s_nop 0
	v_pk_mul_f32 v[32:33], v[32:33], v[48:49]
	v_mov_b32_dpp v48, v26 row_shr:2 row_mask:0xf bank_mask:0xf bound_ctrl:1
	v_mov_b32_dpp v49, v27 row_shr:2 row_mask:0xf bank_mask:0xf bound_ctrl:1
	v_pk_mul_f32 v[34:35], v[34:35], v[32:33]
	v_mov_b32_dpp v32, v26 row_shr:1 row_mask:0xf bank_mask:0xf bound_ctrl:1
	v_mov_b32_dpp v33, v27 row_shr:1 row_mask:0xf bank_mask:0xf bound_ctrl:1
	v_pk_add_f32 v[46:47], v[48:49], v[46:47]
	v_pk_add_f32 v[32:33], v[32:33], v[50:51]
	v_pk_fma_f32 v[46:47], v[72:73], v[46:47], v[76:77]
	s_nop 0
	v_pk_fma_f32 v[32:33], v[60:61], v[32:33], v[46:47]
	s_nop 0
	v_pk_fma_f32 v[32:33], v[68:69], v[26:27], v[32:33]
	s_nop 0
	v_pk_mul_f32 v[46:47], v[32:33], s[2:3] op_sel_hi:[1,0]
	s_nop 0
	v_exp_f32_e32 v46, v46
	v_exp_f32_e32 v47, v47
	s_nop 0
	v_pk_add_f32 v[46:47], v[46:47], 1.0 op_sel_hi:[1,0]
	s_nop 0
	v_rcp_f32_e32 v46, v46
	v_rcp_f32_e32 v47, v47
	s_nop 0
	v_pk_mul_f32 v[32:33], v[32:33], v[46:47]
	s_nop 0
	v_pk_mul_f32 v[28:29], v[28:29], v[32:33]
	v_cvt_pk_bf16_f32 v32, v36, v37
	v_cvt_pk_bf16_f32 v33, v40, v41
	v_cvt_pk_bf16_f32 v34, v34, v35
	v_mov_b32_dpp v36, v44 row_shl:14 row_mask:0xf bank_mask:0xf bound_ctrl:1
	v_cvt_pk_bf16_f32 v35, v28, v29
	v_mad_i64_i32 v[28:29], s[0:1], v52, s93, v[42:43]
	v_lshl_add_u64 v[28:29], v[28:29], 0, v[154:155]
	global_store_dwordx4 v[28:29], v[32:35], off sc1
	ds_read_b32 v28, v223 offset:448
	v_mov_b32_dpp v37, v45 row_shl:14 row_mask:0xf bank_mask:0xf bound_ctrl:1
	v_mov_b32_dpp v34, v44 row_shl:15 row_mask:0xf bank_mask:0xf bound_ctrl:1
	v_mov_b32_dpp v35, v45 row_shl:15 row_mask:0xf bank_mask:0xf bound_ctrl:1
	s_waitcnt lgkmcnt(0)
;     __device__ __forceinline__ void fast(const f32x4 (&acc)[2][2][4][2], const pg8::Unit& u, int wr, int wc, int fr, int fq, RsCache& rsc) const {
;     ...
;                 const int row = rowb + m * 16 + fr; const float s = rsc.tab[ai * 64 + m * 16 + fr]; const f32x2 s2 = (f32x2){s, s};
;                 f32x2 g[4], o[4], v[4];
; #pragma unroll
;                 for (int cp = 0; cp < 4; ++cp) { const int n = cp >> 1, e0 = (cp & 1) * 2;
;                     g[cp] = (f32x2){acc[ai][0][m][n][e0], acc[ai][0][m][n][e0 + 1]} * s2; v[cp] = (f32x2){acc[ai][1][m][n][e0], acc[ai][1][m][n][e0 + 1]} * s2; }
; #pragma unroll
;                 for (int cp = 0; cp < 4; ++cp) {
;                     f32x2 p1 = (f32x2){dppz<0x111>(g[cp].x), dppz<0x111>(g[cp].y)}, p2 = (f32x2){dppz<0x112>(g[cp].x), dppz<0x112>(g[cp].y)};
;                     if (m > 0) { p1 += (f32x2){dppz<0x10F>(gp[cp].x), dppz<0x10F>(gp[cp].y)}; p2 += (f32x2){dppz<0x10E>(gp[cp].x), dppz<0x10E>(gp[cp].y)}; }
;                     const f32x2 gv = bb[cp] + w0[cp] * p2 + w1[cp] * p1 + w2[cp] * g[cp];
;                     const f32x2 ea = gv * (-1.44269504089f);
;                     f32x2 ex; ex.x = __builtin_amdgcn_exp2f(ea.x); ex.y = __builtin_amdgcn_exp2f(ea.y);
;                     const f32x2 dn = ex + 1.0f;
;                     f32x2 rc; rc.x = __builtin_amdgcn_rcpf(dn.x); rc.y = __builtin_amdgcn_rcpf(dn.y);
;                     o[cp] = (gv * rc) * v[cp];
;                 }
;                 if (m > 0 || fr >= 2) { uint4 w; w.x = pk2(o[0].x, o[0].y); w.y = pk2(o[1].x, o[1].y); w.z = pk2(o[2].x, o[2].y); w.w = pk2(o[3].x, o[3].y); *(uint4*)(act + (size_t)row * FH + ch) = w; }
;                 if (m == 0 && fr < 2) { uint4 w; w.x = pk2(g[0].x, g[0].y); w.y = pk2(g[1].x, g[1].y); w.z = pk2(g[2].x, g[2].y); w.w = pk2(g[3].x, g[3].y); *(uint4*)(sideg + ((size_t)blk * 4 + fr) * FH + ch) = w;
;                     uint4 q; q.x = pk2(v[0].x, v[0].y); q.y = pk2(v[1].x, v[1].y); q.z = pk2(v[2].x, v[2].y); q.w = pk2(v[3].x, v[3].y); *(uint4*)(sidev + ((size_t)blk * 2 + fr) * FH + ch) = q; }
;                 if (m == 3 && fr >= 14) { uint4 w; w.x = pk2(g[0].x, g[0].y); w.y = pk2(g[1].x, g[1].y); w.z = pk2(g[2].x, g[2].y); w.w = pk2(g[3].x, g[3].y); *(uint4*)(sideg + ((size_t)blk * 4 + 2 + (fr - 14)) * FH + ch) = w; }
	v_pk_mul_f32 v[22:23], v[22:23], v[28:29] op_sel_hi:[1,0]
	v_pk_mul_f32 v[32:33], v[14:15], v[28:29] op_sel_hi:[1,0]
	v_pk_mul_f32 v[14:15], v[24:25], v[28:29] op_sel_hi:[1,0]
	v_pk_mul_f32 v[24:25], v[16:17], v[28:29] op_sel_hi:[1,0]
	v_pk_mul_f32 v[16:17], v[18:19], v[28:29] op_sel_hi:[1,0]
	v_pk_mul_f32 v[18:19], v[10:11], v[28:29] op_sel_hi:[1,0]
	v_pk_mul_f32 v[10:11], v[20:21], v[28:29] op_sel_hi:[1,0]
	v_pk_mul_f32 v[12:13], v[12:13], v[28:29] op_sel_hi:[1,0]
	v_mov_b32_dpp v28, v22 row_shr:2 row_mask:0xf bank_mask:0xf bound_ctrl:1
	v_mov_b32_dpp v29, v23 row_shr:2 row_mask:0xf bank_mask:0xf bound_ctrl:1
	v_mov_b32_dpp v20, v22 row_shr:1 row_mask:0xf bank_mask:0xf bound_ctrl:1
	v_mov_b32_dpp v21, v23 row_shr:1 row_mask:0xf bank_mask:0xf bound_ctrl:1
	v_pk_add_f32 v[28:29], v[28:29], v[36:37]
	v_pk_add_f32 v[20:21], v[20:21], v[34:35]
	v_pk_fma_f32 v[28:29], v[90:91], v[28:29], v[102:103]
	v_mov_b32_dpp v36, v38 row_shl:14 row_mask:0xf bank_mask:0xf bound_ctrl:1
	v_pk_fma_f32 v[20:21], v[94:95], v[20:21], v[28:29]
	v_mov_b32_dpp v37, v39 row_shl:14 row_mask:0xf bank_mask:0xf bound_ctrl:1
	v_pk_fma_f32 v[20:21], v[98:99], v[22:23], v[20:21]
	v_mov_b32_dpp v34, v38 row_shl:15 row_mask:0xf bank_mask:0xf bound_ctrl:1
	v_pk_mul_f32 v[28:29], v[20:21], s[2:3] op_sel_hi:[1,0]
	v_mov_b32_dpp v35, v39 row_shl:15 row_mask:0xf bank_mask:0xf bound_ctrl:1
	v_exp_f32_e32 v28, v28
	v_exp_f32_e32 v29, v29
	s_nop 0
	v_pk_add_f32 v[28:29], v[28:29], 1.0 op_sel_hi:[1,0]
	s_nop 0
	v_rcp_f32_e32 v28, v28
	v_rcp_f32_e32 v29, v29
	s_nop 0
	v_pk_mul_f32 v[20:21], v[20:21], v[28:29]
	s_nop 0
	v_pk_mul_f32 v[20:21], v[32:33], v[20:21]
	v_mov_b32_dpp v32, v14 row_shr:2 row_mask:0xf bank_mask:0xf bound_ctrl:1
	v_mov_b32_dpp v33, v15 row_shr:2 row_mask:0xf bank_mask:0xf bound_ctrl:1
	v_mov_b32_dpp v28, v14 row_shr:1 row_mask:0xf bank_mask:0xf bound_ctrl:1
	v_mov_b32_dpp v29, v15 row_shr:1 row_mask:0xf bank_mask:0xf bound_ctrl:1
	v_pk_add_f32 v[32:33], v[32:33], v[36:37]
	v_pk_add_f32 v[28:29], v[28:29], v[34:35]
	v_pk_fma_f32 v[32:33], v[92:93], v[32:33], v[104:105]
	v_mov_b32_dpp v34, v30 row_shl:15 row_mask:0xf bank_mask:0xf bound_ctrl:1
	v_pk_fma_f32 v[28:29], v[96:97], v[28:29], v[32:33]
	v_mov_b32_dpp v35, v31 row_shl:15 row_mask:0xf bank_mask:0xf bound_ctrl:1
	v_pk_fma_f32 v[28:29], v[100:101], v[14:15], v[28:29]
	v_mov_b32_dpp v30, v30 row_shl:14 row_mask:0xf bank_mask:0xf bound_ctrl:1
	v_pk_mul_f32 v[32:33], v[28:29], s[2:3] op_sel_hi:[1,0]
	v_mov_b32_dpp v31, v31 row_shl:14 row_mask:0xf bank_mask:0xf bound_ctrl:1
	v_exp_f32_e32 v32, v32
	v_exp_f32_e32 v33, v33
	s_nop 0
	v_pk_add_f32 v[32:33], v[32:33], 1.0 op_sel_hi:[1,0]
	s_nop 0
	v_rcp_f32_e32 v32, v32
	v_rcp_f32_e32 v33, v33
	s_nop 0
	v_pk_mul_f32 v[28:29], v[28:29], v[32:33]
	v_mov_b32_dpp v32, v16 row_shr:2 row_mask:0xf bank_mask:0xf bound_ctrl:1
	v_mov_b32_dpp v33, v17 row_shr:2 row_mask:0xf bank_mask:0xf bound_ctrl:1
	v_pk_mul_f32 v[24:25], v[24:25], v[28:29]
	v_mov_b32_dpp v28, v16 row_shr:1 row_mask:0xf bank_mask:0xf bound_ctrl:1
	v_mov_b32_dpp v29, v17 row_shr:1 row_mask:0xf bank_mask:0xf bound_ctrl:1
	v_pk_add_f32 v[30:31], v[32:33], v[30:31]
	v_pk_add_f32 v[28:29], v[28:29], v[34:35]
	v_pk_fma_f32 v[30:31], v[70:71], v[30:31], v[74:75]
	v_mov_b32_dpp v32, v26 row_shl:15 row_mask:0xf bank_mask:0xf bound_ctrl:1
	v_pk_fma_f32 v[28:29], v[58:59], v[28:29], v[30:31]
	v_mov_b32_dpp v33, v27 row_shl:15 row_mask:0xf bank_mask:0xf bound_ctrl:1
	v_pk_fma_f32 v[28:29], v[66:67], v[16:17], v[28:29]
	v_mov_b32_dpp v26, v26 row_shl:14 row_mask:0xf bank_mask:0xf bound_ctrl:1
	v_pk_mul_f32 v[30:31], v[28:29], s[2:3] op_sel_hi:[1,0]
	v_mov_b32_dpp v27, v27 row_shl:14 row_mask:0xf bank_mask:0xf bound_ctrl:1
	v_exp_f32_e32 v30, v30
	v_exp_f32_e32 v31, v31
	v_add_u32_e32 v34, 48, v122
	v_pk_add_f32 v[30:31], v[30:31], 1.0 op_sel_hi:[1,0]
	s_nop 0
	v_rcp_f32_e32 v30, v30
	v_rcp_f32_e32 v31, v31
	s_nop 0
	v_pk_mul_f32 v[28:29], v[28:29], v[30:31]
	v_mov_b32_dpp v30, v10 row_shr:2 row_mask:0xf bank_mask:0xf bound_ctrl:1
	v_mov_b32_dpp v31, v11 row_shr:2 row_mask:0xf bank_mask:0xf bound_ctrl:1
	v_pk_mul_f32 v[28:29], v[18:19], v[28:29]
	v_mov_b32_dpp v18, v10 row_shr:1 row_mask:0xf bank_mask:0xf bound_ctrl:1
	v_mov_b32_dpp v19, v11 row_shr:1 row_mask:0xf bank_mask:0xf bound_ctrl:1
	v_pk_add_f32 v[26:27], v[30:31], v[26:27]
	v_pk_add_f32 v[18:19], v[18:19], v[32:33]
	v_pk_fma_f32 v[26:27], v[72:73], v[26:27], v[76:77]
	s_nop 0
	v_pk_fma_f32 v[18:19], v[60:61], v[18:19], v[26:27]
	s_nop 0
	v_pk_fma_f32 v[18:19], v[68:69], v[10:11], v[18:19]
	s_nop 0
	v_pk_mul_f32 v[26:27], v[18:19], s[2:3] op_sel_hi:[1,0]
	s_nop 0
	v_exp_f32_e32 v26, v26
	v_exp_f32_e32 v27, v27
	s_nop 0
	v_pk_add_f32 v[26:27], v[26:27], 1.0 op_sel_hi:[1,0]
	s_nop 0
	v_rcp_f32_e32 v26, v26
	v_rcp_f32_e32 v27, v27
	s_nop 0
	v_pk_mul_f32 v[18:19], v[18:19], v[26:27]
	s_nop 0
	v_pk_mul_f32 v[12:13], v[12:13], v[18:19]
	v_cvt_pk_bf16_f32 v18, v20, v21
	v_cvt_pk_bf16_f32 v19, v24, v25
	v_cvt_pk_bf16_f32 v20, v28, v29
	s_nop 0
	v_cvt_pk_bf16_f32 v21, v12, v13
	v_mad_i64_i32 v[12:13], s[0:1], v34, s93, v[42:43]
	v_lshl_add_u64 v[12:13], v[12:13], 0, v[154:155]
	global_store_dwordx4 v[12:13], v[18:21], off sc1
	s_and_saveexec_b64 s[0:1], vcc
	s_cbranch_execz .LBB0_278
	v_readlane_b32 s2, v254, 1
	v_readlane_b32 s3, v254, 2
	v_lshl_add_u64 v[18:19], s[6:7], 0, v[156:157]
	v_cvt_pk_bf16_f32 v12, v22, v23
	v_cvt_pk_bf16_f32 v13, v14, v15
	v_cvt_pk_bf16_f32 v14, v16, v17
	v_cvt_pk_bf16_f32 v15, v10, v11
	s_nop 0
	v_mov_b64_e32 v[10:11], s[2:3]
	v_mad_u64_u32 v[10:11], s[2:3], v18, s93, v[10:11]
	v_mad_i32_i24 v11, v19, s93, v11
	v_lshl_add_u64 v[10:11], v[184:185], 1, v[10:11]
	global_store_dwordx4 v[10:11], v[12:15], off sc1

; __device__ __forceinline__ unsigned pk2(float lo, float hi) { unsigned r; asm volatile("v_cvt_pk_bf16_f32 %0, %1, %2" : "=v"(r) : "v"(lo), "v"(hi)); return r; }
;     __device__ __forceinline__ void fast(const f32x4 (&acc)[2][2][4][2], const pg8::Unit& u, int wr, int wc, int fr, int fq, RsCache& rsc) const {
;     ...
;         } else {
;             const int cb = (u.pn - 8) * 256 + wc * 32 + 8 * fq;
; #pragma unroll
;             for (int ai = 0; ai < 2; ++ai)
; #pragma unroll
;                 for (int m = 0; m < 4; ++m) { const int row = row0 + ai * 128 + m * 16; const float s = rsc.tab[ai * 64 + m * 16 + fr]; bf16_t* rowp = out + (size_t)row * ldc + cb;
; #pragma unroll
;                     for (int bj = 0; bj < 2; ++bj) { const f32x4 v0 = acc[ai][bj][m][0] * s, v1 = acc[ai][bj][m][1] * s;
;                         u32x4 w; w.x = pk2(v0[0], v0[1]); w.y = pk2(v0[2], v0[3]); w.z = pk2(v1[0], v1[1]); w.w = pk2(v1[2], v1[3]);
;                         *(u32x4*)(rowp + bj * 128) = w; }
;                     asm volatile("" ::: "memory"); }
;         }
.LBB0_304:
	v_lshl_add_u32 v156, v147, 2, s89
	ds_read_b32 v148, v156
	s_add_i32 s0, s36, s92
	v_add_u32_e32 v180, s0, v147
	v_lshlrev_b32_e32 v146, 3, v146
	v_ashrrev_i32_e32 v150, 31, v180
	v_add_u32_e32 v177, 16, v180
	v_add_u32_e32 v169, 32, v180
	v_add_u32_e32 v166, 48, v180
	v_add_u32_e32 v163, 0x80, v180
	v_add_u32_e32 v160, 0x90, v180
	v_add_u32_e32 v157, 0xa0, v180
	s_cmp_gt_i32 s3, 7
	s_mov_b64 s[0:1], -1
	v_ashrrev_i32_e32 v147, 31, v146
	v_mul_lo_u32 v181, s19, v180
	v_mul_lo_u32 v182, s18, v150
	v_ashrrev_i32_e32 v179, 31, v177
	v_mul_lo_u32 v178, s19, v177
	v_ashrrev_i32_e32 v176, 31, v169
	v_mul_lo_u32 v175, s19, v169
	v_ashrrev_i32_e32 v168, 31, v166
	v_mul_lo_u32 v167, s19, v166
	v_ashrrev_i32_e32 v165, 31, v163
	v_mul_lo_u32 v164, s19, v163
	v_ashrrev_i32_e32 v162, 31, v160
	v_mul_lo_u32 v161, s19, v160
	v_ashrrev_i32_e32 v159, 31, v157
	v_mul_lo_u32 v158, s19, v157
	v_add_u32_e32 v155, 0xb0, v180
	s_cbranch_scc0 .LBB0_307
	s_lshl_b32 s36, s3, 8
	v_mad_u64_u32 v[150:151], s[0:1], s18, v180, 0
	v_add3_u32 v151, v151, v182, v181
	s_or_b32 s36, s8, s36
	v_lshl_add_u64 v[172:173], v[150:151], 1, s[20:21]
	v_lshl_add_u64 v[150:151], s[36:37], 0, v[146:147]
	v_lshlrev_b64 v[150:151], 1, v[150:151]
	s_waitcnt lgkmcnt(0)
	v_pk_mul_f32 v[186:187], v[136:137], v[148:149] op_sel_hi:[1,0]
	v_pk_mul_f32 v[184:185], v[134:135], v[148:149] op_sel_hi:[1,0]
	v_lshl_add_u64 v[172:173], v[172:173], 0, v[150:151]
	v_pk_mul_f32 v[188:189], v[132:133], v[148:149] op_sel_hi:[1,0]
	v_pk_mul_f32 v[190:191], v[130:131], v[148:149] op_sel_hi:[1,0]
	v_cvt_pk_bf16_f32 v184, v184, v185
	v_cvt_pk_bf16_f32 v185, v186, v187
	v_mul_lo_u32 v183, s19, v155
	v_cvt_pk_bf16_f32 v186, v190, v191
	v_cvt_pk_bf16_f32 v187, v188, v189
	global_store_dwordx4 v[172:173], v[184:187], off offset:-4096 sc1
	v_pk_mul_f32 v[188:189], v[124:125], v[148:149] op_sel_hi:[1,0]
	v_pk_mul_f32 v[190:191], v[122:123], v[148:149] op_sel_hi:[1,0]
	v_pk_mul_f32 v[186:187], v[128:129], v[148:149] op_sel_hi:[1,0]
	v_pk_mul_f32 v[184:185], v[126:127], v[148:149] op_sel_hi:[1,0]
	s_nop 0
	v_cvt_pk_bf16_f32 v184, v184, v185
	v_cvt_pk_bf16_f32 v185, v186, v187
	v_cvt_pk_bf16_f32 v186, v190, v191
	v_cvt_pk_bf16_f32 v187, v188, v189
	global_store_dwordx4 v[172:173], v[184:187], off offset:-3840 sc1
	ds_read_b32 v172, v156 offset:64
	v_mul_lo_u32 v173, s18, v179
	v_mad_u64_u32 v[184:185], s[0:1], s18, v177, 0
	v_add3_u32 v185, v185, v173, v178
	v_lshl_add_u64 v[184:185], v[184:185], 1, s[20:21]
	v_lshl_add_u64 v[188:189], v[184:185], 0, v[150:151]
	s_waitcnt lgkmcnt(0)
	v_pk_mul_f32 v[186:187], v[120:121], v[172:173] op_sel_hi:[1,0]
	v_pk_mul_f32 v[184:185], v[118:119], v[172:173] op_sel_hi:[1,0]
	v_pk_mul_f32 v[190:191], v[116:117], v[172:173] op_sel_hi:[1,0]
	v_pk_mul_f32 v[192:193], v[114:115], v[172:173] op_sel_hi:[1,0]
	v_cvt_pk_bf16_f32 v184, v184, v185
	v_cvt_pk_bf16_f32 v185, v186, v187
	s_nop 0
	v_cvt_pk_bf16_f32 v186, v192, v193
	v_cvt_pk_bf16_f32 v187, v190, v191
	global_store_dwordx4 v[188:189], v[184:187], off offset:-4096 sc1
	v_pk_mul_f32 v[190:191], v[108:109], v[172:173] op_sel_hi:[1,0]
	s_nop 0
	v_pk_mul_f32 v[186:187], v[112:113], v[172:173] op_sel_hi:[1,0]
	v_pk_mul_f32 v[184:185], v[110:111], v[172:173] op_sel_hi:[1,0]
	v_pk_mul_f32 v[172:173], v[106:107], v[172:173] op_sel_hi:[1,0]
	v_cvt_pk_bf16_f32 v184, v184, v185
	v_cvt_pk_bf16_f32 v185, v186, v187
	s_nop 0
	v_cvt_pk_bf16_f32 v186, v172, v173
	v_cvt_pk_bf16_f32 v187, v190, v191
	global_store_dwordx4 v[188:189], v[184:187], off offset:-3840 sc1
	ds_read_b32 v172, v156 offset:128
	v_mul_lo_u32 v173, s18, v176
	v_mad_u64_u32 v[184:185], s[0:1], s18, v169, 0
	v_add3_u32 v185, v185, v173, v175
	v_lshl_add_u64 v[184:185], v[184:185], 1, s[20:21]
	v_lshl_add_u64 v[188:189], v[184:185], 0, v[150:151]
	s_waitcnt lgkmcnt(0)
	v_pk_mul_f32 v[186:187], v[104:105], v[172:173] op_sel_hi:[1,0]
	v_pk_mul_f32 v[184:185], v[102:103], v[172:173] op_sel_hi:[1,0]
	v_pk_mul_f32 v[190:191], v[100:101], v[172:173] op_sel_hi:[1,0]
	v_pk_mul_f32 v[192:193], v[98:99], v[172:173] op_sel_hi:[1,0]
	v_cvt_pk_bf16_f32 v184, v184, v185
	v_cvt_pk_bf16_f32 v185, v186, v187
	s_nop 0
	v_cvt_pk_bf16_f32 v186, v192, v193
	v_cvt_pk_bf16_f32 v187, v190, v191
	global_store_dwordx4 v[188:189], v[184:187], off offset:-4096 sc1
	v_pk_mul_f32 v[190:191], v[92:93], v[172:173] op_sel_hi:[1,0]
	s_nop 0
	v_pk_mul_f32 v[186:187], v[96:97], v[172:173] op_sel_hi:[1,0]
	v_pk_mul_f32 v[184:185], v[94:95], v[172:173] op_sel_hi:[1,0]
	v_pk_mul_f32 v[172:173], v[90:91], v[172:173] op_sel_hi:[1,0]
	v_cvt_pk_bf16_f32 v184, v184, v185
	v_cvt_pk_bf16_f32 v185, v186, v187
	s_nop 0
	v_cvt_pk_bf16_f32 v186, v172, v173
	v_cvt_pk_bf16_f32 v187, v190, v191
	global_store_dwordx4 v[188:189], v[184:187], off offset:-3840 sc1
	ds_read_b32 v172, v156 offset:192
	v_mul_lo_u32 v173, s18, v168
	v_mad_u64_u32 v[184:185], s[0:1], s18, v166, 0
	v_add3_u32 v185, v185, v173, v167
	v_lshl_add_u64 v[184:185], v[184:185], 1, s[20:21]
	v_lshl_add_u64 v[188:189], v[184:185], 0, v[150:151]
	s_waitcnt lgkmcnt(0)
; __device__ __forceinline__ unsigned pk2(float lo, float hi) { unsigned r; asm volatile("v_cvt_pk_bf16_f32 %0, %1, %2" : "=v"(r) : "v"(lo), "v"(hi)); return r; }
;     __device__ __forceinline__ void fast(const f32x4 (&acc)[2][2][4][2], const pg8::Unit& u, int wr, int wc, int fr, int fq, RsCache& rsc) const {
;     ...
;         } else {
;             const int cb = (u.pn - 8) * 256 + wc * 32 + 8 * fq;
; #pragma unroll
;             for (int ai = 0; ai < 2; ++ai)
; #pragma unroll
;                 for (int m = 0; m < 4; ++m) { const int row = row0 + ai * 128 + m * 16; const float s = rsc.tab[ai * 64 + m * 16 + fr]; bf16_t* rowp = out + (size_t)row * ldc + cb;
; #pragma unroll
;                     for (int bj = 0; bj < 2; ++bj) { const f32x4 v0 = acc[ai][bj][m][0] * s, v1 = acc[ai][bj][m][1] * s;
;                         u32x4 w; w.x = pk2(v0[0], v0[1]); w.y = pk2(v0[2], v0[3]); w.z = pk2(v1[0], v1[1]); w.w = pk2(v1[2], v1[3]);
;                         *(u32x4*)(rowp + bj * 128) = w; }
;                     asm volatile("" ::: "memory"); }
;         }
	v_pk_mul_f32 v[186:187], v[88:89], v[172:173] op_sel_hi:[1,0]
	v_pk_mul_f32 v[184:185], v[86:87], v[172:173] op_sel_hi:[1,0]
	v_pk_mul_f32 v[190:191], v[84:85], v[172:173] op_sel_hi:[1,0]
	v_pk_mul_f32 v[192:193], v[82:83], v[172:173] op_sel_hi:[1,0]
	v_cvt_pk_bf16_f32 v184, v184, v185
	v_cvt_pk_bf16_f32 v185, v186, v187
	s_nop 0
	v_cvt_pk_bf16_f32 v186, v192, v193
	v_cvt_pk_bf16_f32 v187, v190, v191
	global_store_dwordx4 v[188:189], v[184:187], off offset:-4096 sc1
	v_pk_mul_f32 v[190:191], v[76:77], v[172:173] op_sel_hi:[1,0]
	s_nop 0
	v_pk_mul_f32 v[186:187], v[80:81], v[172:173] op_sel_hi:[1,0]
	v_pk_mul_f32 v[184:185], v[78:79], v[172:173] op_sel_hi:[1,0]
	v_pk_mul_f32 v[172:173], v[74:75], v[172:173] op_sel_hi:[1,0]
	v_cvt_pk_bf16_f32 v184, v184, v185
	v_cvt_pk_bf16_f32 v185, v186, v187
	s_nop 0
	v_cvt_pk_bf16_f32 v186, v172, v173
	v_cvt_pk_bf16_f32 v187, v190, v191
	global_store_dwordx4 v[188:189], v[184:187], off offset:-3840 sc1
	ds_read_b32 v172, v156 offset:256
	v_mul_lo_u32 v173, s18, v165
	v_mad_u64_u32 v[184:185], s[0:1], s18, v163, 0
	v_add3_u32 v185, v185, v173, v164
	v_lshl_add_u64 v[184:185], v[184:185], 1, s[20:21]
	v_lshl_add_u64 v[188:189], v[184:185], 0, v[150:151]
	s_waitcnt lgkmcnt(0)
	v_pk_mul_f32 v[186:187], v[72:73], v[172:173] op_sel_hi:[1,0]
	v_pk_mul_f32 v[184:185], v[70:71], v[172:173] op_sel_hi:[1,0]
	v_pk_mul_f32 v[190:191], v[68:69], v[172:173] op_sel_hi:[1,0]
	v_pk_mul_f32 v[192:193], v[66:67], v[172:173] op_sel_hi:[1,0]
	v_cvt_pk_bf16_f32 v184, v184, v185
	v_cvt_pk_bf16_f32 v185, v186, v187
	s_nop 0
	v_cvt_pk_bf16_f32 v186, v192, v193
	v_cvt_pk_bf16_f32 v187, v190, v191
	global_store_dwordx4 v[188:189], v[184:187], off offset:-4096 sc1
	v_pk_mul_f32 v[190:191], v[60:61], v[172:173] op_sel_hi:[1,0]
	s_nop 0
	v_pk_mul_f32 v[186:187], v[64:65], v[172:173] op_sel_hi:[1,0]
	v_pk_mul_f32 v[184:185], v[62:63], v[172:173] op_sel_hi:[1,0]
	v_pk_mul_f32 v[172:173], v[58:59], v[172:173] op_sel_hi:[1,0]
	v_cvt_pk_bf16_f32 v184, v184, v185
	v_cvt_pk_bf16_f32 v185, v186, v187
	s_nop 0
	v_cvt_pk_bf16_f32 v186, v172, v173
	v_cvt_pk_bf16_f32 v187, v190, v191
	global_store_dwordx4 v[188:189], v[184:187], off offset:-3840 sc1
	ds_read_b32 v172, v156 offset:320
	v_mul_lo_u32 v173, s18, v162
	v_mad_u64_u32 v[184:185], s[0:1], s18, v160, 0
	v_add3_u32 v185, v185, v173, v161
	v_lshl_add_u64 v[184:185], v[184:185], 1, s[20:21]
	v_lshl_add_u64 v[188:189], v[184:185], 0, v[150:151]
	s_waitcnt lgkmcnt(0)
	v_pk_mul_f32 v[186:187], v[56:57], v[172:173] op_sel_hi:[1,0]
	v_pk_mul_f32 v[184:185], v[54:55], v[172:173] op_sel_hi:[1,0]
	v_pk_mul_f32 v[190:191], v[52:53], v[172:173] op_sel_hi:[1,0]
	v_pk_mul_f32 v[192:193], v[50:51], v[172:173] op_sel_hi:[1,0]
	v_cvt_pk_bf16_f32 v184, v184, v185
	v_cvt_pk_bf16_f32 v185, v186, v187
	s_nop 0
	v_cvt_pk_bf16_f32 v186, v192, v193
	v_cvt_pk_bf16_f32 v187, v190, v191
	global_store_dwordx4 v[188:189], v[184:187], off offset:-4096 sc1
	v_pk_mul_f32 v[190:191], v[44:45], v[172:173] op_sel_hi:[1,0]
	s_nop 0
	v_pk_mul_f32 v[186:187], v[48:49], v[172:173] op_sel_hi:[1,0]
	v_pk_mul_f32 v[184:185], v[46:47], v[172:173] op_sel_hi:[1,0]
	v_pk_mul_f32 v[172:173], v[42:43], v[172:173] op_sel_hi:[1,0]
	v_cvt_pk_bf16_f32 v184, v184, v185
	v_cvt_pk_bf16_f32 v185, v186, v187
	s_nop 0
	v_cvt_pk_bf16_f32 v186, v172, v173
	v_cvt_pk_bf16_f32 v187, v190, v191
	global_store_dwordx4 v[188:189], v[184:187], off offset:-3840 sc1
	ds_read_b32 v172, v156 offset:384
	v_mul_lo_u32 v173, s18, v159
	v_mad_u64_u32 v[184:185], s[0:1], s18, v157, 0
	v_add3_u32 v185, v185, v173, v158
	v_lshl_add_u64 v[184:185], v[184:185], 1, s[20:21]
	v_lshl_add_u64 v[188:189], v[184:185], 0, v[150:151]
	s_waitcnt lgkmcnt(0)
	v_pk_mul_f32 v[186:187], v[40:41], v[172:173] op_sel_hi:[1,0]
	v_pk_mul_f32 v[184:185], v[38:39], v[172:173] op_sel_hi:[1,0]
	v_pk_mul_f32 v[190:191], v[36:37], v[172:173] op_sel_hi:[1,0]
	v_pk_mul_f32 v[192:193], v[34:35], v[172:173] op_sel_hi:[1,0]
	v_cvt_pk_bf16_f32 v184, v184, v185
	v_cvt_pk_bf16_f32 v185, v186, v187
	s_nop 0
	v_cvt_pk_bf16_f32 v186, v192, v193
	v_cvt_pk_bf16_f32 v187, v190, v191
	global_store_dwordx4 v[188:189], v[184:187], off offset:-4096 sc1
	v_pk_mul_f32 v[190:191], v[28:29], v[172:173] op_sel_hi:[1,0]
	s_nop 0
	v_pk_mul_f32 v[186:187], v[32:33], v[172:173] op_sel_hi:[1,0]
	v_pk_mul_f32 v[184:185], v[30:31], v[172:173] op_sel_hi:[1,0]
	v_pk_mul_f32 v[172:173], v[26:27], v[172:173] op_sel_hi:[1,0]
	v_cvt_pk_bf16_f32 v184, v184, v185
	v_cvt_pk_bf16_f32 v185, v186, v187
	s_nop 0
	v_cvt_pk_bf16_f32 v186, v172, v173
	v_cvt_pk_bf16_f32 v187, v190, v191
	global_store_dwordx4 v[188:189], v[184:187], off offset:-3840 sc1
	ds_read_b32 v172, v156 offset:448
	v_ashrrev_i32_e32 v173, 31, v155
	v_mul_lo_u32 v173, s18, v173
	v_mad_u64_u32 v[184:185], s[0:1], s18, v155, 0
	v_add3_u32 v185, v185, v173, v183
	v_lshl_add_u64 v[184:185], v[184:185], 1, s[20:21]
	v_lshl_add_u64 v[150:151], v[184:185], 0, v[150:151]
	s_waitcnt lgkmcnt(0)
	v_pk_mul_f32 v[186:187], v[24:25], v[172:173] op_sel_hi:[1,0]
	v_pk_mul_f32 v[184:185], v[22:23], v[172:173] op_sel_hi:[1,0]
	v_pk_mul_f32 v[188:189], v[20:21], v[172:173] op_sel_hi:[1,0]
	v_pk_mul_f32 v[190:191], v[18:19], v[172:173] op_sel_hi:[1,0]
	v_cvt_pk_bf16_f32 v184, v184, v185
	v_cvt_pk_bf16_f32 v185, v186, v187
	s_nop 0
	v_cvt_pk_bf16_f32 v186, v190, v191
	v_cvt_pk_bf16_f32 v187, v188, v189
	global_store_dwordx4 v[150:151], v[184:187], off offset:-4096 sc1
	v_pk_mul_f32 v[188:189], v[12:13], v[172:173] op_sel_hi:[1,0]
	s_nop 0
	v_pk_mul_f32 v[186:187], v[16:17], v[172:173] op_sel_hi:[1,0]
	v_pk_mul_f32 v[184:185], v[14:15], v[172:173] op_sel_hi:[1,0]
	v_pk_mul_f32 v[172:173], v[10:11], v[172:173] op_sel_hi:[1,0]
	v_cvt_pk_bf16_f32 v184, v184, v185
	v_cvt_pk_bf16_f32 v185, v186, v187
	s_nop 0
	v_cvt_pk_bf16_f32 v186, v172, v173
	v_cvt_pk_bf16_f32 v187, v188, v189
	global_store_dwordx4 v[150:151], v[184:187], off offset:-3840 sc1
	s_cbranch_execz .LBB0_308

; __device__ __forceinline__ unsigned pk2(float lo, float hi) { unsigned r; asm volatile("v_cvt_pk_bf16_f32 %0, %1, %2" : "=v"(r) : "v"(lo), "v"(hi)); return r; }
;     __device__ __forceinline__ void fast(const f32x4 (&acc)[2][2][4][2], const pg8::Unit& u, int wr, int wc, int fr, int fq, RsCache& rsc) const {
;     ...
;         if (u.pn < 8) {
;             const int cb = 1024 + u.pn * 128 + wc * 32 + 8 * fq;
; #pragma unroll
;             for (int ai = 0; ai < 2; ++ai)
; #pragma unroll
;                 for (int m = 0; m < 4; ++m) { const int row = row0 + ai * 128 + m * 16; const float s = rsc.tab[ai * 64 + m * 16 + fr]; const float s2 = s * s;
;                     const f32x4 v0 = acc[ai][0][m][0] * acc[ai][1][m][0] * s2, v1 = acc[ai][0][m][1] * acc[ai][1][m][1] * s2;
;                     u32x4 w; w.x = pk2(v0[0], v0[1]); w.y = pk2(v0[2], v0[3]); w.z = pk2(v1[0], v1[1]); w.w = pk2(v1[2], v1[3]);
;                     *(u32x4*)(out + (size_t)row * ldc + cb) = w;
;                     asm volatile("" ::: "memory"); }
.LBB0_308:
	s_waitcnt lgkmcnt(0)
	v_mul_f32_e32 v148, v148, v148
	v_pk_mul_f32 v[126:127], v[134:135], v[126:127]
	v_pk_mul_f32 v[122:123], v[130:131], v[122:123]
	s_lshl_b32 s0, s3, 7
	v_pk_mul_f32 v[128:129], v[136:137], v[128:129]
	v_pk_mul_f32 v[126:127], v[126:127], v[148:149] op_sel_hi:[1,0]
	v_pk_mul_f32 v[124:125], v[132:133], v[124:125]
	v_pk_mul_f32 v[122:123], v[122:123], v[148:149] op_sel_hi:[1,0]
	v_pk_mul_f32 v[128:129], v[128:129], v[148:149] op_sel_hi:[1,0]
	v_pk_mul_f32 v[130:131], v[124:125], v[148:149] op_sel_hi:[1,0]
	v_cvt_pk_bf16_f32 v124, v126, v127
	v_cvt_pk_bf16_f32 v125, v128, v129
	v_cvt_pk_bf16_f32 v126, v122, v123
	v_mad_u64_u32 v[122:123], s[80:81], s18, v180, 0
	s_ashr_i32 s1, s0, 31
	v_add3_u32 v123, v123, v182, v181
	s_or_b64 s[0:1], s[8:9], s[0:1]
	v_lshl_add_u64 v[128:129], v[122:123], 1, s[20:21]
	v_lshl_add_u64 v[122:123], s[0:1], 0, v[146:147]
	v_lshlrev_b64 v[122:123], 1, v[122:123]
	v_lshl_add_u64 v[128:129], v[128:129], 0, v[122:123]
	v_cvt_pk_bf16_f32 v127, v130, v131
	global_store_dwordx4 v[128:129], v[124:127], off offset:2048 sc1
	ds_read_b32 v124, v156 offset:64
	v_pk_mul_f32 v[112:113], v[120:121], v[112:113]
	v_pk_mul_f32 v[110:111], v[118:119], v[110:111]
	v_pk_mul_f32 v[108:109], v[116:117], v[108:109]
	v_pk_mul_f32 v[106:107], v[114:115], v[106:107]
	s_waitcnt lgkmcnt(0)
	v_mul_f32_e32 v124, v124, v124
	v_pk_mul_f32 v[112:113], v[112:113], v[124:125] op_sel_hi:[1,0]
	v_pk_mul_f32 v[110:111], v[110:111], v[124:125] op_sel_hi:[1,0]
	v_pk_mul_f32 v[114:115], v[108:109], v[124:125] op_sel_hi:[1,0]
	v_pk_mul_f32 v[108:109], v[106:107], v[124:125] op_sel_hi:[1,0]
	v_cvt_pk_bf16_f32 v106, v110, v111
	v_cvt_pk_bf16_f32 v107, v112, v113
	v_mul_lo_u32 v112, s18, v179
	v_mad_u64_u32 v[110:111], s[0:1], s18, v177, 0
	v_add3_u32 v111, v111, v112, v178
	v_lshl_add_u64 v[110:111], v[110:111], 1, s[20:21]
	v_lshl_add_u64 v[110:111], v[110:111], 0, v[122:123]
	v_cvt_pk_bf16_f32 v108, v108, v109
	v_cvt_pk_bf16_f32 v109, v114, v115
	global_store_dwordx4 v[110:111], v[106:109], off offset:2048 sc1
	ds_read_b32 v106, v156 offset:128
	v_pk_mul_f32 v[96:97], v[104:105], v[96:97]
	v_pk_mul_f32 v[94:95], v[102:103], v[94:95]
	v_pk_mul_f32 v[92:93], v[100:101], v[92:93]
	v_pk_mul_f32 v[90:91], v[98:99], v[90:91]
	s_waitcnt lgkmcnt(0)
	v_mul_f32_e32 v106, v106, v106
	v_pk_mul_f32 v[96:97], v[96:97], v[106:107] op_sel_hi:[1,0]
	v_pk_mul_f32 v[94:95], v[94:95], v[106:107] op_sel_hi:[1,0]
	v_pk_mul_f32 v[98:99], v[92:93], v[106:107] op_sel_hi:[1,0]
	v_pk_mul_f32 v[92:93], v[90:91], v[106:107] op_sel_hi:[1,0]
	v_cvt_pk_bf16_f32 v90, v94, v95
	v_cvt_pk_bf16_f32 v91, v96, v97
	v_mul_lo_u32 v96, s18, v176
	v_mad_u64_u32 v[94:95], s[0:1], s18, v169, 0
	v_add3_u32 v95, v95, v96, v175
	v_lshl_add_u64 v[94:95], v[94:95], 1, s[20:21]
	v_lshl_add_u64 v[94:95], v[94:95], 0, v[122:123]
	v_cvt_pk_bf16_f32 v92, v92, v93
	v_cvt_pk_bf16_f32 v93, v98, v99
	global_store_dwordx4 v[94:95], v[90:93], off offset:2048 sc1
	ds_read_b32 v90, v156 offset:192
	v_pk_mul_f32 v[80:81], v[88:89], v[80:81]
	v_pk_mul_f32 v[78:79], v[86:87], v[78:79]
	v_pk_mul_f32 v[76:77], v[84:85], v[76:77]
	v_pk_mul_f32 v[74:75], v[82:83], v[74:75]
	s_waitcnt lgkmcnt(0)
	v_mul_f32_e32 v90, v90, v90
	v_pk_mul_f32 v[80:81], v[80:81], v[90:91] op_sel_hi:[1,0]
	v_pk_mul_f32 v[78:79], v[78:79], v[90:91] op_sel_hi:[1,0]
	v_pk_mul_f32 v[82:83], v[76:77], v[90:91] op_sel_hi:[1,0]
	v_pk_mul_f32 v[76:77], v[74:75], v[90:91] op_sel_hi:[1,0]
	v_cvt_pk_bf16_f32 v74, v78, v79
	v_cvt_pk_bf16_f32 v75, v80, v81
	v_mul_lo_u32 v80, s18, v168
	v_mad_u64_u32 v[78:79], s[0:1], s18, v166, 0
	v_add3_u32 v79, v79, v80, v167
	v_lshl_add_u64 v[78:79], v[78:79], 1, s[20:21]
	v_lshl_add_u64 v[78:79], v[78:79], 0, v[122:123]
	v_cvt_pk_bf16_f32 v76, v76, v77
	v_cvt_pk_bf16_f32 v77, v82, v83
	global_store_dwordx4 v[78:79], v[74:77], off offset:2048 sc1
	ds_read_b32 v74, v156 offset:256
	v_pk_mul_f32 v[64:65], v[72:73], v[64:65]
	v_pk_mul_f32 v[62:63], v[70:71], v[62:63]
	v_pk_mul_f32 v[60:61], v[68:69], v[60:61]
	v_pk_mul_f32 v[58:59], v[66:67], v[58:59]
	s_waitcnt lgkmcnt(0)
; __device__ __forceinline__ unsigned pk2(float lo, float hi) { unsigned r; asm volatile("v_cvt_pk_bf16_f32 %0, %1, %2" : "=v"(r) : "v"(lo), "v"(hi)); return r; }
;     __device__ __forceinline__ void fast(const f32x4 (&acc)[2][2][4][2], const pg8::Unit& u, int wr, int wc, int fr, int fq, RsCache& rsc) const {
;     ...
;         if (u.pn < 8) {
;             const int cb = 1024 + u.pn * 128 + wc * 32 + 8 * fq;
; #pragma unroll
;             for (int ai = 0; ai < 2; ++ai)
; #pragma unroll
;                 for (int m = 0; m < 4; ++m) { const int row = row0 + ai * 128 + m * 16; const float s = rsc.tab[ai * 64 + m * 16 + fr]; const float s2 = s * s;
;                     const f32x4 v0 = acc[ai][0][m][0] * acc[ai][1][m][0] * s2, v1 = acc[ai][0][m][1] * acc[ai][1][m][1] * s2;
;                     u32x4 w; w.x = pk2(v0[0], v0[1]); w.y = pk2(v0[2], v0[3]); w.z = pk2(v1[0], v1[1]); w.w = pk2(v1[2], v1[3]);
;                     *(u32x4*)(out + (size_t)row * ldc + cb) = w;
;                     asm volatile("" ::: "memory"); }
	v_mul_f32_e32 v74, v74, v74
	v_pk_mul_f32 v[64:65], v[64:65], v[74:75] op_sel_hi:[1,0]
	v_pk_mul_f32 v[62:63], v[62:63], v[74:75] op_sel_hi:[1,0]
	v_pk_mul_f32 v[66:67], v[60:61], v[74:75] op_sel_hi:[1,0]
	v_pk_mul_f32 v[60:61], v[58:59], v[74:75] op_sel_hi:[1,0]
	v_cvt_pk_bf16_f32 v58, v62, v63
	v_cvt_pk_bf16_f32 v59, v64, v65
	v_mul_lo_u32 v64, s18, v165
	v_mad_u64_u32 v[62:63], s[0:1], s18, v163, 0
	v_add3_u32 v63, v63, v64, v164
	v_lshl_add_u64 v[62:63], v[62:63], 1, s[20:21]
	v_lshl_add_u64 v[62:63], v[62:63], 0, v[122:123]
	v_cvt_pk_bf16_f32 v60, v60, v61
	v_cvt_pk_bf16_f32 v61, v66, v67
	global_store_dwordx4 v[62:63], v[58:61], off offset:2048 sc1
	ds_read_b32 v58, v156 offset:320
	v_pk_mul_f32 v[48:49], v[56:57], v[48:49]
	v_pk_mul_f32 v[46:47], v[54:55], v[46:47]
	v_pk_mul_f32 v[44:45], v[52:53], v[44:45]
	v_pk_mul_f32 v[42:43], v[50:51], v[42:43]
	s_waitcnt lgkmcnt(0)
	v_mul_f32_e32 v58, v58, v58
	v_pk_mul_f32 v[48:49], v[48:49], v[58:59] op_sel_hi:[1,0]
	v_pk_mul_f32 v[46:47], v[46:47], v[58:59] op_sel_hi:[1,0]
	v_pk_mul_f32 v[50:51], v[44:45], v[58:59] op_sel_hi:[1,0]
	v_pk_mul_f32 v[44:45], v[42:43], v[58:59] op_sel_hi:[1,0]
	v_cvt_pk_bf16_f32 v42, v46, v47
	v_cvt_pk_bf16_f32 v43, v48, v49
	v_mul_lo_u32 v48, s18, v162
	v_mad_u64_u32 v[46:47], s[0:1], s18, v160, 0
	v_add3_u32 v47, v47, v48, v161
	v_lshl_add_u64 v[46:47], v[46:47], 1, s[20:21]
	v_lshl_add_u64 v[46:47], v[46:47], 0, v[122:123]
	v_cvt_pk_bf16_f32 v44, v44, v45
	v_cvt_pk_bf16_f32 v45, v50, v51
	global_store_dwordx4 v[46:47], v[42:45], off offset:2048 sc1
	ds_read_b32 v42, v156 offset:384
	v_pk_mul_f32 v[32:33], v[40:41], v[32:33]
	v_pk_mul_f32 v[30:31], v[38:39], v[30:31]
	v_pk_mul_f32 v[28:29], v[36:37], v[28:29]
	v_pk_mul_f32 v[26:27], v[34:35], v[26:27]
	s_waitcnt lgkmcnt(0)
	v_mul_f32_e32 v42, v42, v42
	v_pk_mul_f32 v[32:33], v[32:33], v[42:43] op_sel_hi:[1,0]
	v_pk_mul_f32 v[30:31], v[30:31], v[42:43] op_sel_hi:[1,0]
	v_pk_mul_f32 v[34:35], v[28:29], v[42:43] op_sel_hi:[1,0]
	v_pk_mul_f32 v[28:29], v[26:27], v[42:43] op_sel_hi:[1,0]
	v_cvt_pk_bf16_f32 v26, v30, v31
	v_cvt_pk_bf16_f32 v27, v32, v33
	v_mul_lo_u32 v32, s18, v159
	v_mad_u64_u32 v[30:31], s[0:1], s18, v157, 0
	v_add3_u32 v31, v31, v32, v158
	v_lshl_add_u64 v[30:31], v[30:31], 1, s[20:21]
	v_lshl_add_u64 v[30:31], v[30:31], 0, v[122:123]
	v_cvt_pk_bf16_f32 v28, v28, v29
	v_cvt_pk_bf16_f32 v29, v34, v35
	global_store_dwordx4 v[30:31], v[26:29], off offset:2048 sc1
	ds_read_b32 v26, v156 offset:448
	v_pk_mul_f32 v[14:15], v[22:23], v[14:15]
	v_pk_mul_f32 v[16:17], v[24:25], v[16:17]
	v_pk_mul_f32 v[12:13], v[20:21], v[12:13]
	v_pk_mul_f32 v[10:11], v[18:19], v[10:11]
	s_waitcnt lgkmcnt(0)
	v_mul_f32_e32 v26, v26, v26
	v_pk_mul_f32 v[14:15], v[14:15], v[26:27] op_sel_hi:[1,0]
	v_pk_mul_f32 v[16:17], v[16:17], v[26:27] op_sel_hi:[1,0]
	v_pk_mul_f32 v[18:19], v[12:13], v[26:27] op_sel_hi:[1,0]
	v_pk_mul_f32 v[12:13], v[10:11], v[26:27] op_sel_hi:[1,0]
	v_cvt_pk_bf16_f32 v10, v14, v15
	v_ashrrev_i32_e32 v14, 31, v155
	v_cvt_pk_bf16_f32 v11, v16, v17
	v_mul_lo_u32 v16, s18, v14
	v_mul_lo_u32 v17, s19, v155
	v_mad_u64_u32 v[14:15], s[0:1], s18, v155, 0
	v_add3_u32 v15, v15, v16, v17
	v_lshl_add_u64 v[14:15], v[14:15], 1, s[20:21]
	v_lshl_add_u64 v[14:15], v[14:15], 0, v[122:123]
	v_cvt_pk_bf16_f32 v12, v12, v13
	v_cvt_pk_bf16_f32 v13, v18, v19
	global_store_dwordx4 v[14:15], v[10:13], off offset:2048 sc1
	s_and_b64 vcc, exec, s[4:5]
	s_mov_b64 s[0:1], -1
	s_cbranch_vccnz .LBB0_289

; __device__ __forceinline__ unsigned pk2(float lo, float hi) { unsigned r; asm volatile("v_cvt_pk_bf16_f32 %0, %1, %2" : "=v"(r) : "v"(lo), "v"(hi)); return r; }
;     __device__ __forceinline__ void fast(const f32x4 (&acc)[2][2][4][2], const pg8::Unit& u, int wr, int wc, int fr, int fq, RsCache& rsc) const {
;     ...
;         if (u.pn < 24) {
;             const int cb = u.pn * 256 + wc * 32 + 8 * fq; const bool hal = (u.pn >= 8) && (fr >= 13);
; #pragma unroll
;             for (int ai = 0; ai < 2; ++ai)
; #pragma unroll
;                 for (int m = 0; m < 4; ++m) { const int row = row0 + ai * 128 + m * 16; const float s = rsc.tab[ai * 64 + m * 16 + fr]; bf16_t* rowp = big + (size_t)row * BIGW + cb;
; #pragma unroll
;                     for (int bj = 0; bj < 2; ++bj) { const f32x4 v0 = acc[ai][bj][m][0] * s, v1 = acc[ai][bj][m][1] * s;
;                         u32x4 w; w.x = pk2(v0[0], v0[1]); w.y = pk2(v0[2], v0[3]); w.z = pk2(v1[0], v1[1]); w.w = pk2(v1[2], v1[3]);
;                         *(u32x4*)(rowp + bj * 128) = w;
;                         if (m == 3 && hal) *(u32x4*)(halo + ((size_t)(row >> 6) * 3 + (fr - 13)) * 4096 + (cb - DI_) + bj * 128) = w; }
;                     asm volatile("" ::: "memory"); }
.LBB0_340:
	v_lshl_add_u32 v142, v177, 2, s8
	s_lshl_b32 s0, s21, 8
	ds_read_b32 v144, v142
	s_or_b32 s0, s0, s97
	v_readlane_b32 s2, v253, 16
	v_lshl_add_u32 v138, v2, 3, s0
	v_readlane_b32 s3, v253, 17
	v_ashrrev_i32_e32 v139, 31, v138
	s_movk_i32 s10, 0x3000
	v_mov_b64_e32 v[146:147], s[2:3]
	v_mad_i64_i32 v[148:149], s[2:3], v164, s10, v[146:147]
	v_lshlrev_b64 v[140:141], 1, v[138:139]
	v_lshl_add_u64 v[148:149], v[148:149], 0, v[140:141]
	s_waitcnt lgkmcnt(0)
	v_pk_mul_f32 v[136:137], v[136:137], v[144:145] op_sel_hi:[1,0]
	v_pk_mul_f32 v[134:135], v[134:135], v[144:145] op_sel_hi:[1,0]
	v_pk_mul_f32 v[150:151], v[132:133], v[144:145] op_sel_hi:[1,0]
	v_pk_mul_f32 v[132:133], v[130:131], v[144:145] op_sel_hi:[1,0]
	v_cvt_pk_bf16_f32 v130, v134, v135
	v_cvt_pk_bf16_f32 v131, v136, v137
	v_pk_mul_f32 v[128:129], v[128:129], v[144:145] op_sel_hi:[1,0]
	v_cvt_pk_bf16_f32 v132, v132, v133
	v_cvt_pk_bf16_f32 v133, v150, v151
	global_store_dwordx4 v[148:149], v[130:133], off sc1
	v_pk_mul_f32 v[126:127], v[126:127], v[144:145] op_sel_hi:[1,0]
	v_add_u32_e32 v2, -13, v177
	v_pk_mul_f32 v[130:131], v[120:121], v[144:145] op_sel_hi:[1,0]
	v_pk_mul_f32 v[120:121], v[118:119], v[144:145] op_sel_hi:[1,0]
	v_cvt_pk_bf16_f32 v118, v126, v127
	v_cvt_pk_bf16_f32 v119, v128, v129
	s_cmp_gt_i32 s21, 7
	v_cvt_pk_bf16_f32 v120, v120, v121
	v_cvt_pk_bf16_f32 v121, v130, v131
	global_store_dwordx4 v[148:149], v[118:121], off offset:256 sc1
	ds_read_b32 v118, v142 offset:64
	s_cselect_b64 s[0:1], -1, 0
	v_add_u32_e32 v119, 16, v164
	v_mad_i64_i32 v[120:121], s[2:3], v119, s10, v[146:147]
	v_lshl_add_u64 v[120:121], v[120:121], 0, v[140:141]
	s_waitcnt lgkmcnt(0)
	v_pk_mul_f32 v[124:125], v[124:125], v[118:119] op_sel_hi:[1,0]
	v_pk_mul_f32 v[122:123], v[122:123], v[118:119] op_sel_hi:[1,0]
	v_pk_mul_f32 v[126:127], v[116:117], v[118:119] op_sel_hi:[1,0]
	v_pk_mul_f32 v[116:117], v[114:115], v[118:119] op_sel_hi:[1,0]
	v_cvt_pk_bf16_f32 v114, v122, v123
	v_cvt_pk_bf16_f32 v115, v124, v125
	v_pk_mul_f32 v[112:113], v[112:113], v[118:119] op_sel_hi:[1,0]
	v_cvt_pk_bf16_f32 v116, v116, v117
	v_cvt_pk_bf16_f32 v117, v126, v127
	global_store_dwordx4 v[120:121], v[114:117], off sc1
	v_pk_mul_f32 v[110:111], v[110:111], v[118:119] op_sel_hi:[1,0]
	v_cmp_lt_i32_e32 vcc, 12, v177
	v_pk_mul_f32 v[114:115], v[104:105], v[118:119] op_sel_hi:[1,0]
	v_pk_mul_f32 v[104:105], v[102:103], v[118:119] op_sel_hi:[1,0]
	v_cvt_pk_bf16_f32 v102, v110, v111
	v_cvt_pk_bf16_f32 v103, v112, v113
	s_and_b64 s[0:1], s[0:1], vcc
	v_cvt_pk_bf16_f32 v104, v104, v105
	v_cvt_pk_bf16_f32 v105, v114, v115
	global_store_dwordx4 v[120:121], v[102:105], off offset:256 sc1
	ds_read_b32 v102, v142 offset:128
	s_nop 0
	v_add_u32_e32 v103, 32, v164
	v_mad_i64_i32 v[104:105], s[2:3], v103, s10, v[146:147]
	v_lshl_add_u64 v[104:105], v[104:105], 0, v[140:141]
	s_waitcnt lgkmcnt(0)
	v_pk_mul_f32 v[108:109], v[108:109], v[102:103] op_sel_hi:[1,0]
	v_pk_mul_f32 v[106:107], v[106:107], v[102:103] op_sel_hi:[1,0]
	v_pk_mul_f32 v[110:111], v[100:101], v[102:103] op_sel_hi:[1,0]
	v_pk_mul_f32 v[100:101], v[98:99], v[102:103] op_sel_hi:[1,0]
	v_cvt_pk_bf16_f32 v98, v106, v107
	v_cvt_pk_bf16_f32 v99, v108, v109
	v_pk_mul_f32 v[96:97], v[96:97], v[102:103] op_sel_hi:[1,0]
	v_cvt_pk_bf16_f32 v100, v100, v101
	v_cvt_pk_bf16_f32 v101, v110, v111
	global_store_dwordx4 v[104:105], v[98:101], off sc1
	v_pk_mul_f32 v[94:95], v[94:95], v[102:103] op_sel_hi:[1,0]
	s_nop 0
	v_pk_mul_f32 v[98:99], v[92:93], v[102:103] op_sel_hi:[1,0]
	v_pk_mul_f32 v[92:93], v[90:91], v[102:103] op_sel_hi:[1,0]
	v_cvt_pk_bf16_f32 v90, v94, v95
	v_cvt_pk_bf16_f32 v91, v96, v97
	s_nop 0
	v_cvt_pk_bf16_f32 v92, v92, v93
	v_cvt_pk_bf16_f32 v93, v98, v99
	global_store_dwordx4 v[104:105], v[90:93], off offset:256 sc1
	ds_read_b32 v92, v142 offset:192
	s_nop 0
	v_add_u32_e32 v93, 48, v164
	v_mad_i64_i32 v[90:91], s[2:3], v93, s10, v[146:147]
	v_ashrrev_i32_e32 v93, 6, v93
	v_lshl_add_u32 v94, v93, 1, v93
	v_ashrrev_i32_e32 v95, 31, v94
	v_lshl_add_u64 v[94:95], v[94:95], 0, v[2:3]
	v_readlane_b32 s2, v254, 1
	v_lshlrev_b64 v[94:95], 13, v[94:95]
	s_waitcnt lgkmcnt(0)
	v_pk_mul_f32 v[86:87], v[86:87], v[92:93] op_sel_hi:[1,0]
	v_readlane_b32 s3, v254, 2
	v_pk_mul_f32 v[96:97], v[84:85], v[92:93] op_sel_hi:[1,0]
	v_pk_mul_f32 v[84:85], v[82:83], v[92:93] op_sel_hi:[1,0]
	v_cvt_pk_bf16_f32 v82, v86, v87
	v_lshl_add_u64 v[86:87], s[2:3], 0, v[94:95]
	v_lshl_add_u64 v[90:91], v[90:91], 0, v[140:141]
	v_lshl_add_u64 v[86:87], v[138:139], 1, v[86:87]
	v_pk_mul_f32 v[88:89], v[88:89], v[92:93] op_sel_hi:[1,0]
	s_nop 0
	v_cvt_pk_bf16_f32 v83, v88, v89
	v_cvt_pk_bf16_f32 v84, v84, v85
	v_cvt_pk_bf16_f32 v85, v96, v97
	global_store_dwordx4 v[90:91], v[82:85], off sc1
	s_and_saveexec_b64 s[82:83], s[0:1]
	s_cbranch_execz .LBB0_342
	global_store_dwordx4 v[86:87], v[82:85], off offset:-4096 sc1
.LBB0_342:
	s_or_b64 exec, exec, s[82:83]
	v_mov_b32_e32 v93, v92
	v_mov_b32_e32 v82, v92
	v_mov_b32_e32 v83, v92
	v_pk_mul_f32 v[80:81], v[80:81], v[82:83]
	v_pk_mul_f32 v[82:83], v[76:77], v[82:83]
	v_pk_mul_f32 v[76:77], v[74:75], v[92:93]
	v_pk_mul_f32 v[78:79], v[78:79], v[92:93]
	s_nop 0
	v_cvt_pk_bf16_f32 v74, v78, v79
	v_cvt_pk_bf16_f32 v75, v80, v81
	v_cvt_pk_bf16_f32 v76, v76, v77
	v_cvt_pk_bf16_f32 v77, v82, v83
	global_store_dwordx4 v[90:91], v[74:77], off offset:256 sc1
	s_and_saveexec_b64 s[82:83], s[0:1]
	s_cbranch_execz .LBB0_344
	global_store_dwordx4 v[86:87], v[74:77], off offset:-3840 sc1
; __device__ __forceinline__ unsigned pk2(float lo, float hi) { unsigned r; asm volatile("v_cvt_pk_bf16_f32 %0, %1, %2" : "=v"(r) : "v"(lo), "v"(hi)); return r; }
;     __device__ __forceinline__ void fast(const f32x4 (&acc)[2][2][4][2], const pg8::Unit& u, int wr, int wc, int fr, int fq, RsCache& rsc) const {
;     ...
;         if (u.pn < 24) {
;             const int cb = u.pn * 256 + wc * 32 + 8 * fq; const bool hal = (u.pn >= 8) && (fr >= 13);
; #pragma unroll
;             for (int ai = 0; ai < 2; ++ai)
; #pragma unroll
;                 for (int m = 0; m < 4; ++m) { const int row = row0 + ai * 128 + m * 16; const float s = rsc.tab[ai * 64 + m * 16 + fr]; bf16_t* rowp = big + (size_t)row * BIGW + cb;
; #pragma unroll
;                     for (int bj = 0; bj < 2; ++bj) { const f32x4 v0 = acc[ai][bj][m][0] * s, v1 = acc[ai][bj][m][1] * s;
;                         u32x4 w; w.x = pk2(v0[0], v0[1]); w.y = pk2(v0[2], v0[3]); w.z = pk2(v1[0], v1[1]); w.w = pk2(v1[2], v1[3]);
;                         *(u32x4*)(rowp + bj * 128) = w;
;                         if (m == 3 && hal) *(u32x4*)(halo + ((size_t)(row >> 6) * 3 + (fr - 13)) * 4096 + (cb - DI_) + bj * 128) = w; }
;                     asm volatile("" ::: "memory"); }
.LBB0_344:
	s_or_b64 exec, exec, s[82:83]
	ds_read_b32 v74, v142 offset:256
	v_readlane_b32 s2, v253, 16
	v_readlane_b32 s3, v253, 17
	v_add_u32_e32 v75, 0x80, v164
	s_waitcnt lgkmcnt(0)
	v_pk_mul_f32 v[72:73], v[72:73], v[74:75] op_sel_hi:[1,0]
	v_mov_b64_e32 v[76:77], s[2:3]
	v_mad_i64_i32 v[78:79], s[2:3], v75, s10, v[76:77]
	v_lshl_add_u64 v[78:79], v[78:79], 0, v[140:141]
	v_pk_mul_f32 v[70:71], v[70:71], v[74:75] op_sel_hi:[1,0]
	v_pk_mul_f32 v[80:81], v[68:69], v[74:75] op_sel_hi:[1,0]
	v_pk_mul_f32 v[68:69], v[66:67], v[74:75] op_sel_hi:[1,0]
	v_cvt_pk_bf16_f32 v66, v70, v71
	v_cvt_pk_bf16_f32 v67, v72, v73
	v_pk_mul_f32 v[64:65], v[64:65], v[74:75] op_sel_hi:[1,0]
	v_cvt_pk_bf16_f32 v68, v68, v69
	v_cvt_pk_bf16_f32 v69, v80, v81
	global_store_dwordx4 v[78:79], v[66:69], off sc1
	v_pk_mul_f32 v[62:63], v[62:63], v[74:75] op_sel_hi:[1,0]
	s_nop 0
	v_pk_mul_f32 v[66:67], v[56:57], v[74:75] op_sel_hi:[1,0]
	v_pk_mul_f32 v[56:57], v[54:55], v[74:75] op_sel_hi:[1,0]
	v_cvt_pk_bf16_f32 v54, v62, v63
	v_cvt_pk_bf16_f32 v55, v64, v65
	s_nop 0
	v_cvt_pk_bf16_f32 v56, v56, v57
	v_cvt_pk_bf16_f32 v57, v66, v67
	global_store_dwordx4 v[78:79], v[54:57], off offset:256 sc1
	ds_read_b32 v54, v142 offset:320
	s_nop 0
	v_add_u32_e32 v55, 0x90, v164
	v_mad_i64_i32 v[56:57], s[2:3], v55, s10, v[76:77]
	v_lshl_add_u64 v[56:57], v[56:57], 0, v[140:141]
	s_waitcnt lgkmcnt(0)
	v_pk_mul_f32 v[60:61], v[60:61], v[54:55] op_sel_hi:[1,0]
	v_pk_mul_f32 v[58:59], v[58:59], v[54:55] op_sel_hi:[1,0]
	v_pk_mul_f32 v[62:63], v[52:53], v[54:55] op_sel_hi:[1,0]
	v_pk_mul_f32 v[52:53], v[50:51], v[54:55] op_sel_hi:[1,0]
	v_cvt_pk_bf16_f32 v50, v58, v59
	v_cvt_pk_bf16_f32 v51, v60, v61
	v_pk_mul_f32 v[48:49], v[48:49], v[54:55] op_sel_hi:[1,0]
	v_cvt_pk_bf16_f32 v52, v52, v53
	v_cvt_pk_bf16_f32 v53, v62, v63
	global_store_dwordx4 v[56:57], v[50:53], off sc1
	v_pk_mul_f32 v[46:47], v[46:47], v[54:55] op_sel_hi:[1,0]
	s_nop 0
	v_pk_mul_f32 v[50:51], v[40:41], v[54:55] op_sel_hi:[1,0]
	v_pk_mul_f32 v[40:41], v[38:39], v[54:55] op_sel_hi:[1,0]
	v_cvt_pk_bf16_f32 v38, v46, v47
	v_cvt_pk_bf16_f32 v39, v48, v49
	s_nop 0
	v_cvt_pk_bf16_f32 v40, v40, v41
	v_cvt_pk_bf16_f32 v41, v50, v51
	global_store_dwordx4 v[56:57], v[38:41], off offset:256 sc1
	ds_read_b32 v38, v142 offset:384
	s_nop 0
	v_add_u32_e32 v39, 0xa0, v164
	v_mad_i64_i32 v[40:41], s[2:3], v39, s10, v[76:77]
	v_lshl_add_u64 v[40:41], v[40:41], 0, v[140:141]
	s_waitcnt lgkmcnt(0)
	v_pk_mul_f32 v[44:45], v[44:45], v[38:39] op_sel_hi:[1,0]
	v_pk_mul_f32 v[42:43], v[42:43], v[38:39] op_sel_hi:[1,0]
	v_pk_mul_f32 v[46:47], v[36:37], v[38:39] op_sel_hi:[1,0]
	v_pk_mul_f32 v[36:37], v[34:35], v[38:39] op_sel_hi:[1,0]
	v_cvt_pk_bf16_f32 v34, v42, v43
	v_cvt_pk_bf16_f32 v35, v44, v45
	v_pk_mul_f32 v[32:33], v[32:33], v[38:39] op_sel_hi:[1,0]
	v_cvt_pk_bf16_f32 v36, v36, v37
	v_cvt_pk_bf16_f32 v37, v46, v47
	global_store_dwordx4 v[40:41], v[34:37], off sc1
	v_pk_mul_f32 v[30:31], v[30:31], v[38:39] op_sel_hi:[1,0]
	s_nop 0
	v_pk_mul_f32 v[34:35], v[28:29], v[38:39] op_sel_hi:[1,0]
	v_pk_mul_f32 v[28:29], v[26:27], v[38:39] op_sel_hi:[1,0]
	v_cvt_pk_bf16_f32 v26, v30, v31
	v_cvt_pk_bf16_f32 v27, v32, v33
	s_nop 0
	v_cvt_pk_bf16_f32 v28, v28, v29
	v_cvt_pk_bf16_f32 v29, v34, v35
	global_store_dwordx4 v[40:41], v[26:29], off offset:256 sc1
	ds_read_b32 v28, v142 offset:448
	s_nop 0
	v_add_u32_e32 v29, 0xb0, v164
	v_mad_i64_i32 v[26:27], s[2:3], v29, s10, v[76:77]
	v_ashrrev_i32_e32 v29, 6, v29
	v_lshl_add_u32 v30, v29, 1, v29
	v_ashrrev_i32_e32 v31, 31, v30
	v_lshl_add_u64 v[30:31], v[30:31], 0, v[2:3]
	v_readlane_b32 s2, v254, 1
	v_lshlrev_b64 v[30:31], 13, v[30:31]
	s_waitcnt lgkmcnt(0)
	v_pk_mul_f32 v[22:23], v[22:23], v[28:29] op_sel_hi:[1,0]
	v_readlane_b32 s3, v254, 2
	v_pk_mul_f32 v[32:33], v[20:21], v[28:29] op_sel_hi:[1,0]
	v_pk_mul_f32 v[20:21], v[18:19], v[28:29] op_sel_hi:[1,0]
	v_cvt_pk_bf16_f32 v18, v22, v23
	v_lshl_add_u64 v[22:23], s[2:3], 0, v[30:31]
	v_lshl_add_u64 v[26:27], v[26:27], 0, v[140:141]
	v_lshl_add_u64 v[22:23], v[138:139], 1, v[22:23]
	v_pk_mul_f32 v[24:25], v[24:25], v[28:29] op_sel_hi:[1,0]
	s_nop 0
	v_cvt_pk_bf16_f32 v19, v24, v25
	v_cvt_pk_bf16_f32 v20, v20, v21
	v_cvt_pk_bf16_f32 v21, v32, v33
	global_store_dwordx4 v[26:27], v[18:21], off sc1
	s_and_saveexec_b64 s[82:83], s[0:1]
	s_cbranch_execz .LBB0_346
	global_store_dwordx4 v[22:23], v[18:21], off offset:-4096 sc1
.LBB0_346:
	s_or_b64 exec, exec, s[82:83]
	v_mov_b32_e32 v29, v28
	v_mov_b32_e32 v18, v28
	v_mov_b32_e32 v19, v28
	v_pk_mul_f32 v[16:17], v[16:17], v[18:19]
	v_pk_mul_f32 v[18:19], v[12:13], v[18:19]
	v_pk_mul_f32 v[12:13], v[10:11], v[28:29]
	v_pk_mul_f32 v[14:15], v[14:15], v[28:29]
	s_nop 0
	v_cvt_pk_bf16_f32 v10, v14, v15
	v_cvt_pk_bf16_f32 v11, v16, v17
	v_cvt_pk_bf16_f32 v12, v12, v13
	v_cvt_pk_bf16_f32 v13, v18, v19
	global_store_dwordx4 v[26:27], v[10:13], off offset:256 sc1
	s_and_saveexec_b64 s[82:83], s[0:1]
	s_cbranch_execz .LBB0_348
	global_store_dwordx4 v[22:23], v[10:13], off offset:-3840 sc1

; __device__ __forceinline__ float softplus_f(float x) { return x > 20.f ? x : log1pf(__expf(x)); }
;     __device__ __forceinline__ void fast(const f32x4 (&acc)[2][2][4][2], const pg8::Unit& u, int wr, int wc, int fr, int fq, RsCache& rsc) const {
;     ...
;         } else if (wc == 0) {
;             const f32x4 b0 = *(const f32x4*)(dt_bias + 8 * fq), b1 = *(const f32x4*)(dt_bias + 8 * fq + 4);
; #pragma unroll
;             for (int ai = 0; ai < 2; ++ai)
; #pragma unroll
;                 for (int m = 0; m < 4; ++m) { const int row = row0 + ai * 128 + m * 16; const float s = rsc.tab[ai * 64 + m * 16 + fr];
;                     const f32x4 v0 = acc[ai][0][m][0] * s + b0, v1 = acc[ai][0][m][1] * s + b1; f32x4 o0, o1;
; #pragma unroll
;                     for (int e = 0; e < 4; ++e) { o0[e] = softplus_f(v0[e]); o1[e] = softplus_f(v1[e]); }
;                     float* dp = dt + (size_t)row * 32 + 8 * fq; *(f32x4*)dp = o0; *(f32x4*)(dp + 4) = o1;
;                     asm volatile("" ::: "memory"); }
.LBB0_367:
	s_or_b64 exec, exec, s[0:1]
	v_ashrrev_i32_e32 v165, 31, v164
	v_lshlrev_b64 v[172:173], 7, v[164:165]
	v_lshl_add_u64 v[172:173], s[80:81], 0, v[172:173]
	v_lshl_add_u64 v[172:173], v[166:167], 2, v[172:173]
	global_store_dwordx4 v[172:173], v[146:149], off sc1
	global_store_dwordx4 v[172:173], v[150:153], off offset:16 sc1
	ds_read_b32 v153, v178 offset:64
	s_waitcnt lgkmcnt(0)
	v_fma_f32 v146, v122, v153, v142
	v_cmp_nlt_f32_e32 vcc, s10, v146
	s_and_saveexec_b64 s[0:1], vcc
	s_cbranch_execz .LBB0_369
	v_mul_f32_e32 v146, 0x3fb8aa3b, v146
	v_exp_f32_e32 v152, v146
	s_mov_b32 s2, 0x7f800000
	v_add_f32_e32 v148, 1.0, v152
	v_frexp_mant_f32_e32 v150, v148
	v_cvt_f64_f32_e32 v[146:147], v148
	v_frexp_exp_i32_f64_e32 v146, v[146:147]
	v_cmp_gt_f32_e32 vcc, s11, v150
	v_add_f32_e32 v149, -1.0, v148
	v_sub_f32_e32 v151, v149, v148
	v_subbrev_co_u32_e32 v179, vcc, 0, v146, vcc
	v_sub_u32_e32 v146, 0, v179
	v_sub_f32_e32 v149, v152, v149
	v_add_f32_e32 v151, 1.0, v151
	v_ldexp_f32 v147, v148, v146
	v_add_f32_e32 v149, v149, v151
	v_add_f32_e32 v148, -1.0, v147
	v_add_f32_e32 v150, 1.0, v147
	v_ldexp_f32 v146, v149, v146
	v_add_f32_e32 v149, 1.0, v148
	v_add_f32_e32 v151, -1.0, v150
	v_sub_f32_e32 v149, v147, v149
	v_sub_f32_e32 v147, v147, v151
	v_add_f32_e32 v149, v146, v149
	v_add_f32_e32 v146, v146, v147
	v_add_f32_e32 v175, v150, v146
	v_rcp_f32_e32 v181, v175
	v_sub_f32_e32 v147, v175, v150
	v_sub_f32_e32 v180, v146, v147
	v_add_f32_e32 v147, v148, v149
	v_mul_f32_e32 v183, v147, v181
	v_sub_f32_e32 v146, v147, v148
	v_mul_f32_e32 v148, v175, v183
	v_fma_f32 v150, v183, v175, -v148
	v_fmac_f32_e32 v150, v183, v180
	v_sub_f32_e32 v182, v149, v146
	v_add_f32_e32 v146, v148, v150
	v_sub_f32_e32 v149, v147, v146
	v_pk_add_f32 v[172:173], v[146:147], v[148:149] neg_lo:[0,1] neg_hi:[0,1]
	v_mov_b32_e32 v151, v146
	v_pk_add_f32 v[146:147], v[172:173], v[150:151] neg_lo:[0,1] neg_hi:[0,1]
	v_cmp_neq_f32_e32 vcc, s2, v152
	v_add_f32_e32 v147, v182, v147
	v_add_f32_e32 v146, v146, v147
	v_add_f32_e32 v147, v149, v146
	v_mul_f32_e32 v182, v181, v147
	v_mul_f32_e32 v148, v175, v182
	v_fma_f32 v150, v182, v175, -v148
	v_fmac_f32_e32 v150, v182, v180
	v_sub_f32_e32 v149, v149, v147
	v_add_f32_e32 v175, v146, v149
	v_add_f32_e32 v146, v148, v150
	v_sub_f32_e32 v149, v147, v146
	v_pk_add_f32 v[172:173], v[146:147], v[148:149] neg_lo:[0,1] neg_hi:[0,1]
	v_mov_b32_e32 v151, v146
	v_pk_add_f32 v[146:147], v[172:173], v[150:151] neg_lo:[0,1] neg_hi:[0,1]
	s_mov_b32 s2, 0x33800000
	v_add_f32_e32 v147, v175, v147
	v_add_f32_e32 v146, v146, v147
	v_add_f32_e32 v147, v183, v182
	v_add_f32_e32 v146, v149, v146
	v_sub_f32_e32 v148, v147, v183
	v_mul_f32_e32 v146, v181, v146
	v_sub_f32_e32 v148, v182, v148
	v_add_f32_e32 v148, v148, v146
	v_add_f32_e32 v150, v147, v148
	v_mul_f32_e32 v151, v150, v150
	v_fmamk_f32 v146, v151, 0x3e9b6dac, v206
	v_fmaak_f32 v175, v151, v146, 0x3f2aaada
	v_cvt_f32_i32_e32 v146, v179
	v_sub_f32_e32 v147, v150, v147
	v_sub_f32_e32 v147, v148, v147
	v_ldexp_f32 v172, v147, 1
	v_mul_f32_e32 v147, v150, v151
	v_ldexp_f32 v149, v150, 1
	v_pk_mul_f32 v[150:151], v[146:147], v[174:175]
	s_nop 0
	v_fma_f32 v148, v146, s26, -v150
	v_fmac_f32_e32 v148, 0xb102e308, v146
	v_pk_add_f32 v[146:147], v[150:151], v[148:149]
	s_nop 0
	v_sub_f32_e32 v149, v147, v149
	v_sub_f32_e32 v149, v151, v149
	v_add_f32_e32 v173, v172, v149
	v_mov_b32_e32 v172, v150
	v_pk_add_f32 v[150:151], v[146:147], v[150:151] neg_lo:[0,1] neg_hi:[0,1]
	v_pk_add_f32 v[180:181], v[146:147], v[172:173]
	v_mov_b32_e32 v149, v146
	v_mov_b32_e32 v151, v181
	v_pk_add_f32 v[182:183], v[148:149], v[150:151] neg_lo:[0,1] neg_hi:[0,1]
	v_pk_add_f32 v[148:149], v[148:149], v[150:151]
	v_mov_b32_e32 v172, v173
	v_pk_add_f32 v[150:151], v[148:149], v[146:147] op_sel:[1,0] op_sel_hi:[0,1] neg_lo:[0,1] neg_hi:[0,1]
	v_pk_add_f32 v[184:185], v[180:181], v[150:151] op_sel_hi:[1,0] neg_lo:[0,1] neg_hi:[0,1]
	v_mov_b32_e32 v180, v181
	v_mov_b32_e32 v181, v149
	v_pk_mov_b32 v[150:151], v[146:147], v[150:151] op_sel:[1,0]
	v_mov_b32_e32 v173, v146
	v_pk_add_f32 v[150:151], v[180:181], v[150:151] neg_lo:[0,1] neg_hi:[0,1]
	v_mov_b32_e32 v184, v182
	v_pk_add_f32 v[146:147], v[172:173], v[150:151] neg_lo:[0,1] neg_hi:[0,1]
	v_mov_b32_e32 v183, v149
	v_pk_add_f32 v[150:151], v[184:185], v[146:147]
	s_nop 0
	v_pk_add_f32 v[172:173], v[150:151], v[150:151] op_sel:[0,1] op_sel_hi:[1,0]
	s_nop 0
	v_pk_add_f32 v[148:149], v[148:149], v[172:173] op_sel:[1,0] op_sel_hi:[0,1]
	v_mov_b32_e32 v151, v148
	v_pk_add_f32 v[180:181], v[150:151], v[182:183] neg_lo:[0,1] neg_hi:[0,1]
	v_mov_b32_e32 v147, v172
	v_sub_f32_e32 v149, v150, v180
	v_pk_add_f32 v[146:147], v[146:147], v[180:181] neg_lo:[0,1] neg_hi:[0,1]
	v_sub_f32_e32 v149, v182, v149
	v_add_f32_e32 v146, v146, v149
	v_add_f32_e32 v146, v146, v147
	v_add_f32_e32 v146, v148, v146
	v_cndmask_b32_e32 v146, v216, v146, vcc
	v_cmp_ngt_f32_e32 vcc, -1.0, v152
	s_nop 1
	v_cndmask_b32_e32 v146, v217, v146, vcc
	v_cmp_neq_f32_e32 vcc, -1.0, v152
	s_nop 1
	v_cndmask_b32_e32 v146, v218, v146, vcc
	v_cmp_lt_f32_e64 vcc, |v152|, s2
	s_nop 1
	v_cndmask_b32_e32 v146, v146, v152, vcc

; __device__ __forceinline__ float softplus_f(float x) { return x > 20.f ? x : log1pf(__expf(x)); }
;     __device__ __forceinline__ void fast(const f32x4 (&acc)[2][2][4][2], const pg8::Unit& u, int wr, int wc, int fr, int fq, RsCache& rsc) const {
;     ...
;         } else if (wc == 0) {
;             const f32x4 b0 = *(const f32x4*)(dt_bias + 8 * fq), b1 = *(const f32x4*)(dt_bias + 8 * fq + 4);
; #pragma unroll
;             for (int ai = 0; ai < 2; ++ai)
; #pragma unroll
;                 for (int m = 0; m < 4; ++m) { const int row = row0 + ai * 128 + m * 16; const float s = rsc.tab[ai * 64 + m * 16 + fr];
;                     const f32x4 v0 = acc[ai][0][m][0] * s + b0, v1 = acc[ai][0][m][1] * s + b1; f32x4 o0, o1;
; #pragma unroll
;                     for (int e = 0; e < 4; ++e) { o0[e] = softplus_f(v0[e]); o1[e] = softplus_f(v1[e]); }
;                     float* dp = dt + (size_t)row * 32 + 8 * fq; *(f32x4*)dp = o0; *(f32x4*)(dp + 4) = o1;
;                     asm volatile("" ::: "memory"); }
.LBB0_383:
	s_or_b64 exec, exec, s[0:1]
	v_lshlrev_b64 v[172:173], 7, v[164:165]
	v_lshl_add_u64 v[172:173], s[80:81], 0, v[172:173]
	v_lshl_add_u64 v[172:173], v[166:167], 2, v[172:173]
	global_store_dwordx4 v[172:173], v[146:149], off offset:2048 sc1
	global_store_dwordx4 v[172:173], v[150:153], off offset:2064 sc1
	ds_read_b32 v153, v178 offset:128
	s_waitcnt lgkmcnt(0)
	v_fma_f32 v146, v106, v153, v142
	v_cmp_nlt_f32_e32 vcc, s10, v146
	s_and_saveexec_b64 s[0:1], vcc
	s_cbranch_execz .LBB0_385
	v_mul_f32_e32 v146, 0x3fb8aa3b, v146
	v_exp_f32_e32 v152, v146
	s_mov_b32 s2, 0x7f800000
	v_add_f32_e32 v148, 1.0, v152
	v_frexp_mant_f32_e32 v150, v148
	v_cvt_f64_f32_e32 v[146:147], v148
	v_frexp_exp_i32_f64_e32 v146, v[146:147]
	v_cmp_gt_f32_e32 vcc, s11, v150
	v_add_f32_e32 v149, -1.0, v148
	v_sub_f32_e32 v151, v149, v148
	v_subbrev_co_u32_e32 v179, vcc, 0, v146, vcc
	v_sub_u32_e32 v146, 0, v179
	v_sub_f32_e32 v149, v152, v149
	v_add_f32_e32 v151, 1.0, v151
	v_ldexp_f32 v147, v148, v146
	v_add_f32_e32 v149, v149, v151
	v_add_f32_e32 v148, -1.0, v147
	v_add_f32_e32 v150, 1.0, v147
	v_ldexp_f32 v146, v149, v146
	v_add_f32_e32 v149, 1.0, v148
	v_add_f32_e32 v151, -1.0, v150
	v_sub_f32_e32 v149, v147, v149
	v_sub_f32_e32 v147, v147, v151
	v_add_f32_e32 v149, v146, v149
	v_add_f32_e32 v146, v146, v147
	v_add_f32_e32 v175, v150, v146
	v_rcp_f32_e32 v181, v175
	v_sub_f32_e32 v147, v175, v150
	v_sub_f32_e32 v180, v146, v147
	v_add_f32_e32 v147, v148, v149
	v_mul_f32_e32 v183, v147, v181
	v_sub_f32_e32 v146, v147, v148
	v_mul_f32_e32 v148, v175, v183
	v_fma_f32 v150, v183, v175, -v148
	v_fmac_f32_e32 v150, v183, v180
	v_sub_f32_e32 v182, v149, v146
	v_add_f32_e32 v146, v148, v150
	v_sub_f32_e32 v149, v147, v146
	v_pk_add_f32 v[172:173], v[146:147], v[148:149] neg_lo:[0,1] neg_hi:[0,1]
	v_mov_b32_e32 v151, v146
	v_pk_add_f32 v[146:147], v[172:173], v[150:151] neg_lo:[0,1] neg_hi:[0,1]
	v_cmp_neq_f32_e32 vcc, s2, v152
	v_add_f32_e32 v147, v182, v147
	v_add_f32_e32 v146, v146, v147
	v_add_f32_e32 v147, v149, v146
	v_mul_f32_e32 v182, v181, v147
	v_mul_f32_e32 v148, v175, v182
	v_fma_f32 v150, v182, v175, -v148
	v_fmac_f32_e32 v150, v182, v180
	v_sub_f32_e32 v149, v149, v147
	v_add_f32_e32 v175, v146, v149
	v_add_f32_e32 v146, v148, v150
	v_sub_f32_e32 v149, v147, v146
	v_pk_add_f32 v[172:173], v[146:147], v[148:149] neg_lo:[0,1] neg_hi:[0,1]
	v_mov_b32_e32 v151, v146
	v_pk_add_f32 v[146:147], v[172:173], v[150:151] neg_lo:[0,1] neg_hi:[0,1]
	s_mov_b32 s2, 0x33800000
	v_add_f32_e32 v147, v175, v147
	v_add_f32_e32 v146, v146, v147
	v_add_f32_e32 v147, v183, v182
	v_add_f32_e32 v146, v149, v146
	v_sub_f32_e32 v148, v147, v183
	v_mul_f32_e32 v146, v181, v146
	v_sub_f32_e32 v148, v182, v148
	v_add_f32_e32 v148, v148, v146
	v_add_f32_e32 v150, v147, v148
	v_mul_f32_e32 v151, v150, v150
	v_fmamk_f32 v146, v151, 0x3e9b6dac, v206
	v_fmaak_f32 v175, v151, v146, 0x3f2aaada
	v_cvt_f32_i32_e32 v146, v179
	v_sub_f32_e32 v147, v150, v147
	v_sub_f32_e32 v147, v148, v147
	v_ldexp_f32 v172, v147, 1
	v_mul_f32_e32 v147, v150, v151
	v_ldexp_f32 v149, v150, 1
	v_pk_mul_f32 v[150:151], v[146:147], v[174:175]
	s_nop 0
	v_fma_f32 v148, v146, s26, -v150
	v_fmac_f32_e32 v148, 0xb102e308, v146
	v_pk_add_f32 v[146:147], v[150:151], v[148:149]
	s_nop 0
	v_sub_f32_e32 v149, v147, v149
	v_sub_f32_e32 v149, v151, v149
	v_add_f32_e32 v173, v172, v149
	v_mov_b32_e32 v172, v150
	v_pk_add_f32 v[150:151], v[146:147], v[150:151] neg_lo:[0,1] neg_hi:[0,1]
	v_pk_add_f32 v[180:181], v[146:147], v[172:173]
	v_mov_b32_e32 v149, v146
	v_mov_b32_e32 v151, v181
	v_pk_add_f32 v[182:183], v[148:149], v[150:151] neg_lo:[0,1] neg_hi:[0,1]
	v_pk_add_f32 v[148:149], v[148:149], v[150:151]
	v_mov_b32_e32 v172, v173
	v_pk_add_f32 v[150:151], v[148:149], v[146:147] op_sel:[1,0] op_sel_hi:[0,1] neg_lo:[0,1] neg_hi:[0,1]
	v_pk_add_f32 v[184:185], v[180:181], v[150:151] op_sel_hi:[1,0] neg_lo:[0,1] neg_hi:[0,1]
	v_mov_b32_e32 v180, v181
	v_mov_b32_e32 v181, v149
	v_pk_mov_b32 v[150:151], v[146:147], v[150:151] op_sel:[1,0]
	v_mov_b32_e32 v173, v146
	v_pk_add_f32 v[150:151], v[180:181], v[150:151] neg_lo:[0,1] neg_hi:[0,1]
	v_mov_b32_e32 v184, v182
	v_pk_add_f32 v[146:147], v[172:173], v[150:151] neg_lo:[0,1] neg_hi:[0,1]
	v_mov_b32_e32 v183, v149
	v_pk_add_f32 v[150:151], v[184:185], v[146:147]
	s_nop 0
	v_pk_add_f32 v[172:173], v[150:151], v[150:151] op_sel:[0,1] op_sel_hi:[1,0]
	s_nop 0
	v_pk_add_f32 v[148:149], v[148:149], v[172:173] op_sel:[1,0] op_sel_hi:[0,1]
	v_mov_b32_e32 v151, v148
	v_pk_add_f32 v[180:181], v[150:151], v[182:183] neg_lo:[0,1] neg_hi:[0,1]
	v_mov_b32_e32 v147, v172
	v_sub_f32_e32 v149, v150, v180
	v_pk_add_f32 v[146:147], v[146:147], v[180:181] neg_lo:[0,1] neg_hi:[0,1]
	v_sub_f32_e32 v149, v182, v149
	v_add_f32_e32 v146, v146, v149
	v_add_f32_e32 v146, v146, v147
	v_add_f32_e32 v146, v148, v146
	v_cndmask_b32_e32 v146, v216, v146, vcc
	v_cmp_ngt_f32_e32 vcc, -1.0, v152
	s_nop 1
	v_cndmask_b32_e32 v146, v217, v146, vcc
	v_cmp_neq_f32_e32 vcc, -1.0, v152
	s_nop 1
	v_cndmask_b32_e32 v146, v218, v146, vcc
	v_cmp_lt_f32_e64 vcc, |v152|, s2
	s_nop 1
	v_cndmask_b32_e32 v146, v146, v152, vcc

; __device__ __forceinline__ float softplus_f(float x) { return x > 20.f ? x : log1pf(__expf(x)); }
;     __device__ __forceinline__ void fast(const f32x4 (&acc)[2][2][4][2], const pg8::Unit& u, int wr, int wc, int fr, int fq, RsCache& rsc) const {
;     ...
;         } else if (wc == 0) {
;             const f32x4 b0 = *(const f32x4*)(dt_bias + 8 * fq), b1 = *(const f32x4*)(dt_bias + 8 * fq + 4);
; #pragma unroll
;             for (int ai = 0; ai < 2; ++ai)
; #pragma unroll
;                 for (int m = 0; m < 4; ++m) { const int row = row0 + ai * 128 + m * 16; const float s = rsc.tab[ai * 64 + m * 16 + fr];
;                     const f32x4 v0 = acc[ai][0][m][0] * s + b0, v1 = acc[ai][0][m][1] * s + b1; f32x4 o0, o1;
; #pragma unroll
;                     for (int e = 0; e < 4; ++e) { o0[e] = softplus_f(v0[e]); o1[e] = softplus_f(v1[e]); }
;                     float* dp = dt + (size_t)row * 32 + 8 * fq; *(f32x4*)dp = o0; *(f32x4*)(dp + 4) = o1;
;                     asm volatile("" ::: "memory"); }
.LBB0_399:
	s_or_b64 exec, exec, s[0:1]
	v_lshlrev_b64 v[172:173], 7, v[164:165]
	v_lshl_add_u64 v[172:173], s[80:81], 0, v[172:173]
	v_lshl_add_u64 v[172:173], v[166:167], 2, v[172:173]
	s_mov_b64 s[0:1], 0x1000
	v_lshl_add_u64 v[180:181], v[172:173], 0, s[0:1]
	v_add_co_u32_e32 v172, vcc, 0x1000, v172
	s_nop 1
	v_addc_co_u32_e32 v173, vcc, 0, v173, vcc
	global_store_dwordx4 v[172:173], v[146:149], off sc1
	global_store_dwordx4 v[180:181], v[150:153], off offset:16 sc1
	ds_read_b32 v153, v178 offset:192
	s_waitcnt lgkmcnt(0)
	v_fma_f32 v146, v86, v153, v142
	v_cmp_nlt_f32_e32 vcc, s10, v146
	s_and_saveexec_b64 s[0:1], vcc
	s_cbranch_execz .LBB0_401
	v_mul_f32_e32 v146, 0x3fb8aa3b, v146
	v_exp_f32_e32 v152, v146
	s_mov_b32 s2, 0x7f800000
	v_add_f32_e32 v148, 1.0, v152
	v_frexp_mant_f32_e32 v150, v148
	v_cvt_f64_f32_e32 v[146:147], v148
	v_frexp_exp_i32_f64_e32 v146, v[146:147]
	v_cmp_gt_f32_e32 vcc, s11, v150
	v_add_f32_e32 v149, -1.0, v148
	v_sub_f32_e32 v151, v149, v148
	v_subbrev_co_u32_e32 v179, vcc, 0, v146, vcc
	v_sub_u32_e32 v146, 0, v179
	v_sub_f32_e32 v149, v152, v149
	v_add_f32_e32 v151, 1.0, v151
	v_ldexp_f32 v147, v148, v146
	v_add_f32_e32 v149, v149, v151
	v_add_f32_e32 v148, -1.0, v147
	v_add_f32_e32 v150, 1.0, v147
	v_ldexp_f32 v146, v149, v146
	v_add_f32_e32 v149, 1.0, v148
	v_add_f32_e32 v151, -1.0, v150
	v_sub_f32_e32 v149, v147, v149
	v_sub_f32_e32 v147, v147, v151
	v_add_f32_e32 v149, v146, v149
	v_add_f32_e32 v146, v146, v147
	v_add_f32_e32 v175, v150, v146
	v_rcp_f32_e32 v181, v175
	v_sub_f32_e32 v147, v175, v150
	v_sub_f32_e32 v180, v146, v147
	v_add_f32_e32 v147, v148, v149
	v_mul_f32_e32 v183, v147, v181
	v_sub_f32_e32 v146, v147, v148
	v_mul_f32_e32 v148, v175, v183
	v_fma_f32 v150, v183, v175, -v148
	v_fmac_f32_e32 v150, v183, v180
	v_sub_f32_e32 v182, v149, v146
	v_add_f32_e32 v146, v148, v150
	v_sub_f32_e32 v149, v147, v146
	v_pk_add_f32 v[172:173], v[146:147], v[148:149] neg_lo:[0,1] neg_hi:[0,1]
	v_mov_b32_e32 v151, v146
	v_pk_add_f32 v[146:147], v[172:173], v[150:151] neg_lo:[0,1] neg_hi:[0,1]
	v_cmp_neq_f32_e32 vcc, s2, v152
	v_add_f32_e32 v147, v182, v147
	v_add_f32_e32 v146, v146, v147
	v_add_f32_e32 v147, v149, v146
	v_mul_f32_e32 v182, v181, v147
	v_mul_f32_e32 v148, v175, v182
	v_fma_f32 v150, v182, v175, -v148
	v_fmac_f32_e32 v150, v182, v180
	v_sub_f32_e32 v149, v149, v147
	v_add_f32_e32 v175, v146, v149
	v_add_f32_e32 v146, v148, v150
	v_sub_f32_e32 v149, v147, v146
	v_pk_add_f32 v[172:173], v[146:147], v[148:149] neg_lo:[0,1] neg_hi:[0,1]
	v_mov_b32_e32 v151, v146
	v_pk_add_f32 v[146:147], v[172:173], v[150:151] neg_lo:[0,1] neg_hi:[0,1]
	s_mov_b32 s2, 0x33800000
	v_add_f32_e32 v147, v175, v147
	v_add_f32_e32 v146, v146, v147
	v_add_f32_e32 v147, v183, v182
	v_add_f32_e32 v146, v149, v146
	v_sub_f32_e32 v148, v147, v183
	v_mul_f32_e32 v146, v181, v146
	v_sub_f32_e32 v148, v182, v148
	v_add_f32_e32 v148, v148, v146
	v_add_f32_e32 v150, v147, v148
	v_mul_f32_e32 v151, v150, v150
	v_fmamk_f32 v146, v151, 0x3e9b6dac, v206
	v_fmaak_f32 v175, v151, v146, 0x3f2aaada
	v_cvt_f32_i32_e32 v146, v179
	v_sub_f32_e32 v147, v150, v147
	v_sub_f32_e32 v147, v148, v147
	v_ldexp_f32 v172, v147, 1
	v_mul_f32_e32 v147, v150, v151
	v_ldexp_f32 v149, v150, 1
	v_pk_mul_f32 v[150:151], v[146:147], v[174:175]
	s_nop 0
	v_fma_f32 v148, v146, s26, -v150
	v_fmac_f32_e32 v148, 0xb102e308, v146
	v_pk_add_f32 v[146:147], v[150:151], v[148:149]
	s_nop 0
	v_sub_f32_e32 v149, v147, v149
	v_sub_f32_e32 v149, v151, v149
	v_add_f32_e32 v173, v172, v149
	v_mov_b32_e32 v172, v150
	v_pk_add_f32 v[150:151], v[146:147], v[150:151] neg_lo:[0,1] neg_hi:[0,1]
	v_pk_add_f32 v[180:181], v[146:147], v[172:173]
	v_mov_b32_e32 v149, v146
	v_mov_b32_e32 v151, v181
	v_pk_add_f32 v[182:183], v[148:149], v[150:151] neg_lo:[0,1] neg_hi:[0,1]
	v_pk_add_f32 v[148:149], v[148:149], v[150:151]
	v_mov_b32_e32 v172, v173
	v_pk_add_f32 v[150:151], v[148:149], v[146:147] op_sel:[1,0] op_sel_hi:[0,1] neg_lo:[0,1] neg_hi:[0,1]
	v_pk_add_f32 v[184:185], v[180:181], v[150:151] op_sel_hi:[1,0] neg_lo:[0,1] neg_hi:[0,1]
	v_mov_b32_e32 v180, v181
	v_mov_b32_e32 v181, v149
	v_pk_mov_b32 v[150:151], v[146:147], v[150:151] op_sel:[1,0]
	v_mov_b32_e32 v173, v146
	v_pk_add_f32 v[150:151], v[180:181], v[150:151] neg_lo:[0,1] neg_hi:[0,1]
	v_mov_b32_e32 v184, v182
	v_pk_add_f32 v[146:147], v[172:173], v[150:151] neg_lo:[0,1] neg_hi:[0,1]
	v_mov_b32_e32 v183, v149
	v_pk_add_f32 v[150:151], v[184:185], v[146:147]
	s_nop 0
	v_pk_add_f32 v[172:173], v[150:151], v[150:151] op_sel:[0,1] op_sel_hi:[1,0]
	s_nop 0
	v_pk_add_f32 v[148:149], v[148:149], v[172:173] op_sel:[1,0] op_sel_hi:[0,1]
	v_mov_b32_e32 v151, v148
	v_pk_add_f32 v[180:181], v[150:151], v[182:183] neg_lo:[0,1] neg_hi:[0,1]
	v_mov_b32_e32 v147, v172
	v_sub_f32_e32 v149, v150, v180
	v_pk_add_f32 v[146:147], v[146:147], v[180:181] neg_lo:[0,1] neg_hi:[0,1]
	v_sub_f32_e32 v149, v182, v149
	v_add_f32_e32 v146, v146, v149
	v_add_f32_e32 v146, v146, v147
	v_add_f32_e32 v146, v148, v146
	v_cndmask_b32_e32 v146, v216, v146, vcc
	v_cmp_ngt_f32_e32 vcc, -1.0, v152
	s_nop 1
	v_cndmask_b32_e32 v146, v217, v146, vcc
	v_cmp_neq_f32_e32 vcc, -1.0, v152
	s_nop 1
	v_cndmask_b32_e32 v146, v218, v146, vcc
	v_cmp_lt_f32_e64 vcc, |v152|, s2
	s_nop 1
	v_cndmask_b32_e32 v146, v146, v152, vcc

; __device__ __forceinline__ float softplus_f(float x) { return x > 20.f ? x : log1pf(__expf(x)); }
;     __device__ __forceinline__ void fast(const f32x4 (&acc)[2][2][4][2], const pg8::Unit& u, int wr, int wc, int fr, int fq, RsCache& rsc) const {
;     ...
;         } else if (wc == 0) {
;             const f32x4 b0 = *(const f32x4*)(dt_bias + 8 * fq), b1 = *(const f32x4*)(dt_bias + 8 * fq + 4);
; #pragma unroll
;             for (int ai = 0; ai < 2; ++ai)
; #pragma unroll
;                 for (int m = 0; m < 4; ++m) { const int row = row0 + ai * 128 + m * 16; const float s = rsc.tab[ai * 64 + m * 16 + fr];
;                     const f32x4 v0 = acc[ai][0][m][0] * s + b0, v1 = acc[ai][0][m][1] * s + b1; f32x4 o0, o1;
; #pragma unroll
;                     for (int e = 0; e < 4; ++e) { o0[e] = softplus_f(v0[e]); o1[e] = softplus_f(v1[e]); }
;                     float* dp = dt + (size_t)row * 32 + 8 * fq; *(f32x4*)dp = o0; *(f32x4*)(dp + 4) = o1;
;                     asm volatile("" ::: "memory"); }
.LBB0_415:
	s_or_b64 exec, exec, s[0:1]
	v_lshlrev_b64 v[172:173], 7, v[164:165]
	v_lshl_add_u64 v[172:173], s[80:81], 0, v[172:173]
	v_lshl_add_u64 v[172:173], v[166:167], 2, v[172:173]
	s_mov_b64 s[0:1], 0x1800
	v_lshl_add_u64 v[180:181], v[172:173], 0, s[0:1]
	v_add_co_u32_e32 v172, vcc, 0x1000, v172
	s_nop 1
	v_addc_co_u32_e32 v173, vcc, 0, v173, vcc
	global_store_dwordx4 v[172:173], v[146:149], off offset:2048 sc1
	global_store_dwordx4 v[180:181], v[150:153], off offset:16 sc1
	ds_read_b32 v153, v178 offset:256
	s_waitcnt lgkmcnt(0)
	v_fma_f32 v146, v70, v153, v142
	v_cmp_nlt_f32_e32 vcc, s10, v146
	s_and_saveexec_b64 s[0:1], vcc
	s_cbranch_execz .LBB0_417
	v_mul_f32_e32 v146, 0x3fb8aa3b, v146
	v_exp_f32_e32 v152, v146
	s_mov_b32 s2, 0x7f800000
	v_add_f32_e32 v148, 1.0, v152
	v_frexp_mant_f32_e32 v150, v148
	v_cvt_f64_f32_e32 v[146:147], v148
	v_frexp_exp_i32_f64_e32 v146, v[146:147]
	v_cmp_gt_f32_e32 vcc, s11, v150
	v_add_f32_e32 v149, -1.0, v148
	v_sub_f32_e32 v151, v149, v148
	v_subbrev_co_u32_e32 v179, vcc, 0, v146, vcc
	v_sub_u32_e32 v146, 0, v179
	v_sub_f32_e32 v149, v152, v149
	v_add_f32_e32 v151, 1.0, v151
	v_ldexp_f32 v147, v148, v146
	v_add_f32_e32 v149, v149, v151
	v_add_f32_e32 v148, -1.0, v147
	v_add_f32_e32 v150, 1.0, v147
	v_ldexp_f32 v146, v149, v146
	v_add_f32_e32 v149, 1.0, v148
	v_add_f32_e32 v151, -1.0, v150
	v_sub_f32_e32 v149, v147, v149
	v_sub_f32_e32 v147, v147, v151
	v_add_f32_e32 v149, v146, v149
	v_add_f32_e32 v146, v146, v147
	v_add_f32_e32 v175, v150, v146
	v_rcp_f32_e32 v181, v175
	v_sub_f32_e32 v147, v175, v150
	v_sub_f32_e32 v180, v146, v147
	v_add_f32_e32 v147, v148, v149
	v_mul_f32_e32 v183, v147, v181
	v_sub_f32_e32 v146, v147, v148
	v_mul_f32_e32 v148, v175, v183
	v_fma_f32 v150, v183, v175, -v148
	v_fmac_f32_e32 v150, v183, v180
	v_sub_f32_e32 v182, v149, v146
	v_add_f32_e32 v146, v148, v150
	v_sub_f32_e32 v149, v147, v146
	v_pk_add_f32 v[172:173], v[146:147], v[148:149] neg_lo:[0,1] neg_hi:[0,1]
	v_mov_b32_e32 v151, v146
	v_pk_add_f32 v[146:147], v[172:173], v[150:151] neg_lo:[0,1] neg_hi:[0,1]
	v_cmp_neq_f32_e32 vcc, s2, v152
	v_add_f32_e32 v147, v182, v147
	v_add_f32_e32 v146, v146, v147
	v_add_f32_e32 v147, v149, v146
	v_mul_f32_e32 v182, v181, v147
	v_mul_f32_e32 v148, v175, v182
	v_fma_f32 v150, v182, v175, -v148
	v_fmac_f32_e32 v150, v182, v180
	v_sub_f32_e32 v149, v149, v147
	v_add_f32_e32 v175, v146, v149
	v_add_f32_e32 v146, v148, v150
	v_sub_f32_e32 v149, v147, v146
	v_pk_add_f32 v[172:173], v[146:147], v[148:149] neg_lo:[0,1] neg_hi:[0,1]
	v_mov_b32_e32 v151, v146
	v_pk_add_f32 v[146:147], v[172:173], v[150:151] neg_lo:[0,1] neg_hi:[0,1]
	s_mov_b32 s2, 0x33800000
	v_add_f32_e32 v147, v175, v147
	v_add_f32_e32 v146, v146, v147
	v_add_f32_e32 v147, v183, v182
	v_add_f32_e32 v146, v149, v146
	v_sub_f32_e32 v148, v147, v183
	v_mul_f32_e32 v146, v181, v146
	v_sub_f32_e32 v148, v182, v148
	v_add_f32_e32 v148, v148, v146
	v_add_f32_e32 v150, v147, v148
	v_mul_f32_e32 v151, v150, v150
	v_fmamk_f32 v146, v151, 0x3e9b6dac, v206
	v_fmaak_f32 v175, v151, v146, 0x3f2aaada
	v_cvt_f32_i32_e32 v146, v179
	v_sub_f32_e32 v147, v150, v147
	v_sub_f32_e32 v147, v148, v147
	v_ldexp_f32 v172, v147, 1
	v_mul_f32_e32 v147, v150, v151
	v_ldexp_f32 v149, v150, 1
	v_pk_mul_f32 v[150:151], v[146:147], v[174:175]
	s_nop 0
	v_fma_f32 v148, v146, s26, -v150
	v_fmac_f32_e32 v148, 0xb102e308, v146
	v_pk_add_f32 v[146:147], v[150:151], v[148:149]
	s_nop 0
	v_sub_f32_e32 v149, v147, v149
	v_sub_f32_e32 v149, v151, v149
	v_add_f32_e32 v173, v172, v149
	v_mov_b32_e32 v172, v150
	v_pk_add_f32 v[150:151], v[146:147], v[150:151] neg_lo:[0,1] neg_hi:[0,1]
	v_pk_add_f32 v[180:181], v[146:147], v[172:173]
	v_mov_b32_e32 v149, v146
	v_mov_b32_e32 v151, v181
	v_pk_add_f32 v[182:183], v[148:149], v[150:151] neg_lo:[0,1] neg_hi:[0,1]
	v_pk_add_f32 v[148:149], v[148:149], v[150:151]
	v_mov_b32_e32 v172, v173
	v_pk_add_f32 v[150:151], v[148:149], v[146:147] op_sel:[1,0] op_sel_hi:[0,1] neg_lo:[0,1] neg_hi:[0,1]
	v_pk_add_f32 v[184:185], v[180:181], v[150:151] op_sel_hi:[1,0] neg_lo:[0,1] neg_hi:[0,1]
	v_mov_b32_e32 v180, v181
	v_mov_b32_e32 v181, v149
	v_pk_mov_b32 v[150:151], v[146:147], v[150:151] op_sel:[1,0]
	v_mov_b32_e32 v173, v146
	v_pk_add_f32 v[150:151], v[180:181], v[150:151] neg_lo:[0,1] neg_hi:[0,1]
	v_mov_b32_e32 v184, v182
	v_pk_add_f32 v[146:147], v[172:173], v[150:151] neg_lo:[0,1] neg_hi:[0,1]
	v_mov_b32_e32 v183, v149
	v_pk_add_f32 v[150:151], v[184:185], v[146:147]
	s_nop 0
	v_pk_add_f32 v[172:173], v[150:151], v[150:151] op_sel:[0,1] op_sel_hi:[1,0]
	s_nop 0
	v_pk_add_f32 v[148:149], v[148:149], v[172:173] op_sel:[1,0] op_sel_hi:[0,1]
	v_mov_b32_e32 v151, v148
	v_pk_add_f32 v[180:181], v[150:151], v[182:183] neg_lo:[0,1] neg_hi:[0,1]
	v_mov_b32_e32 v147, v172
	v_sub_f32_e32 v149, v150, v180
	v_pk_add_f32 v[146:147], v[146:147], v[180:181] neg_lo:[0,1] neg_hi:[0,1]
	v_sub_f32_e32 v149, v182, v149
	v_add_f32_e32 v146, v146, v149
	v_add_f32_e32 v146, v146, v147
	v_add_f32_e32 v146, v148, v146
	v_cndmask_b32_e32 v146, v216, v146, vcc
	v_cmp_ngt_f32_e32 vcc, -1.0, v152
	s_nop 1
	v_cndmask_b32_e32 v146, v217, v146, vcc
	v_cmp_neq_f32_e32 vcc, -1.0, v152
	s_nop 1
	v_cndmask_b32_e32 v146, v218, v146, vcc
	v_cmp_lt_f32_e64 vcc, |v152|, s2
	s_nop 1
	v_cndmask_b32_e32 v146, v146, v152, vcc

; __device__ __forceinline__ float softplus_f(float x) { return x > 20.f ? x : log1pf(__expf(x)); }
;     __device__ __forceinline__ void fast(const f32x4 (&acc)[2][2][4][2], const pg8::Unit& u, int wr, int wc, int fr, int fq, RsCache& rsc) const {
;     ...
;         } else if (wc == 0) {
;             const f32x4 b0 = *(const f32x4*)(dt_bias + 8 * fq), b1 = *(const f32x4*)(dt_bias + 8 * fq + 4);
; #pragma unroll
;             for (int ai = 0; ai < 2; ++ai)
; #pragma unroll
;                 for (int m = 0; m < 4; ++m) { const int row = row0 + ai * 128 + m * 16; const float s = rsc.tab[ai * 64 + m * 16 + fr];
;                     const f32x4 v0 = acc[ai][0][m][0] * s + b0, v1 = acc[ai][0][m][1] * s + b1; f32x4 o0, o1;
; #pragma unroll
;                     for (int e = 0; e < 4; ++e) { o0[e] = softplus_f(v0[e]); o1[e] = softplus_f(v1[e]); }
;                     float* dp = dt + (size_t)row * 32 + 8 * fq; *(f32x4*)dp = o0; *(f32x4*)(dp + 4) = o1;
;                     asm volatile("" ::: "memory"); }
.LBB0_431:
	s_or_b64 exec, exec, s[0:1]
	v_lshlrev_b64 v[172:173], 7, v[164:165]
	v_lshl_add_u64 v[172:173], s[80:81], 0, v[172:173]
	v_lshl_add_u64 v[172:173], v[166:167], 2, v[172:173]
	s_mov_b64 s[0:1], 0x4000
	v_lshl_add_u64 v[180:181], v[172:173], 0, s[0:1]
	v_add_co_u32_e32 v172, vcc, 0x4000, v172
	s_nop 1
	v_addc_co_u32_e32 v173, vcc, 0, v173, vcc
	global_store_dwordx4 v[172:173], v[146:149], off sc1
	global_store_dwordx4 v[180:181], v[150:153], off offset:16 sc1
	ds_read_b32 v153, v178 offset:320
	s_waitcnt lgkmcnt(0)
	v_fma_f32 v146, v58, v153, v142
	v_cmp_nlt_f32_e32 vcc, s10, v146
	s_and_saveexec_b64 s[0:1], vcc
	s_cbranch_execz .LBB0_433
	v_mul_f32_e32 v146, 0x3fb8aa3b, v146
	v_exp_f32_e32 v152, v146
	s_mov_b32 s2, 0x7f800000
	v_add_f32_e32 v148, 1.0, v152
	v_frexp_mant_f32_e32 v150, v148
	v_cvt_f64_f32_e32 v[146:147], v148
	v_frexp_exp_i32_f64_e32 v146, v[146:147]
	v_cmp_gt_f32_e32 vcc, s11, v150
	v_add_f32_e32 v149, -1.0, v148
	v_sub_f32_e32 v151, v149, v148
	v_subbrev_co_u32_e32 v179, vcc, 0, v146, vcc
	v_sub_u32_e32 v146, 0, v179
	v_sub_f32_e32 v149, v152, v149
	v_add_f32_e32 v151, 1.0, v151
	v_ldexp_f32 v147, v148, v146
	v_add_f32_e32 v149, v149, v151
	v_add_f32_e32 v148, -1.0, v147
	v_add_f32_e32 v150, 1.0, v147
	v_ldexp_f32 v146, v149, v146
	v_add_f32_e32 v149, 1.0, v148
	v_add_f32_e32 v151, -1.0, v150
	v_sub_f32_e32 v149, v147, v149
	v_sub_f32_e32 v147, v147, v151
	v_add_f32_e32 v149, v146, v149
	v_add_f32_e32 v146, v146, v147
	v_add_f32_e32 v175, v150, v146
	v_rcp_f32_e32 v181, v175
	v_sub_f32_e32 v147, v175, v150
	v_sub_f32_e32 v180, v146, v147
	v_add_f32_e32 v147, v148, v149
	v_mul_f32_e32 v183, v147, v181
	v_sub_f32_e32 v146, v147, v148
	v_mul_f32_e32 v148, v175, v183
	v_fma_f32 v150, v183, v175, -v148
	v_fmac_f32_e32 v150, v183, v180
	v_sub_f32_e32 v182, v149, v146
	v_add_f32_e32 v146, v148, v150
	v_sub_f32_e32 v149, v147, v146
	v_pk_add_f32 v[172:173], v[146:147], v[148:149] neg_lo:[0,1] neg_hi:[0,1]
	v_mov_b32_e32 v151, v146
	v_pk_add_f32 v[146:147], v[172:173], v[150:151] neg_lo:[0,1] neg_hi:[0,1]
	v_cmp_neq_f32_e32 vcc, s2, v152
	v_add_f32_e32 v147, v182, v147
	v_add_f32_e32 v146, v146, v147
	v_add_f32_e32 v147, v149, v146
	v_mul_f32_e32 v182, v181, v147
	v_mul_f32_e32 v148, v175, v182
	v_fma_f32 v150, v182, v175, -v148
	v_fmac_f32_e32 v150, v182, v180
	v_sub_f32_e32 v149, v149, v147
	v_add_f32_e32 v175, v146, v149
	v_add_f32_e32 v146, v148, v150
	v_sub_f32_e32 v149, v147, v146
	v_pk_add_f32 v[172:173], v[146:147], v[148:149] neg_lo:[0,1] neg_hi:[0,1]
	v_mov_b32_e32 v151, v146
	v_pk_add_f32 v[146:147], v[172:173], v[150:151] neg_lo:[0,1] neg_hi:[0,1]
	s_mov_b32 s2, 0x33800000
	v_add_f32_e32 v147, v175, v147
	v_add_f32_e32 v146, v146, v147
	v_add_f32_e32 v147, v183, v182
	v_add_f32_e32 v146, v149, v146
	v_sub_f32_e32 v148, v147, v183
	v_mul_f32_e32 v146, v181, v146
	v_sub_f32_e32 v148, v182, v148
	v_add_f32_e32 v148, v148, v146
	v_add_f32_e32 v150, v147, v148
	v_mul_f32_e32 v151, v150, v150
	v_fmamk_f32 v146, v151, 0x3e9b6dac, v206
	v_fmaak_f32 v175, v151, v146, 0x3f2aaada
	v_cvt_f32_i32_e32 v146, v179
	v_sub_f32_e32 v147, v150, v147
	v_sub_f32_e32 v147, v148, v147
	v_ldexp_f32 v172, v147, 1
	v_mul_f32_e32 v147, v150, v151
	v_ldexp_f32 v149, v150, 1
	v_pk_mul_f32 v[150:151], v[146:147], v[174:175]
	s_nop 0
	v_fma_f32 v148, v146, s26, -v150
	v_fmac_f32_e32 v148, 0xb102e308, v146
	v_pk_add_f32 v[146:147], v[150:151], v[148:149]
	s_nop 0
	v_sub_f32_e32 v149, v147, v149
	v_sub_f32_e32 v149, v151, v149
	v_add_f32_e32 v173, v172, v149
	v_mov_b32_e32 v172, v150
	v_pk_add_f32 v[150:151], v[146:147], v[150:151] neg_lo:[0,1] neg_hi:[0,1]
	v_pk_add_f32 v[180:181], v[146:147], v[172:173]
	v_mov_b32_e32 v149, v146
	v_mov_b32_e32 v151, v181
	v_pk_add_f32 v[182:183], v[148:149], v[150:151] neg_lo:[0,1] neg_hi:[0,1]
	v_pk_add_f32 v[148:149], v[148:149], v[150:151]
	v_mov_b32_e32 v172, v173
	v_pk_add_f32 v[150:151], v[148:149], v[146:147] op_sel:[1,0] op_sel_hi:[0,1] neg_lo:[0,1] neg_hi:[0,1]
	v_pk_add_f32 v[184:185], v[180:181], v[150:151] op_sel_hi:[1,0] neg_lo:[0,1] neg_hi:[0,1]
	v_mov_b32_e32 v180, v181
	v_mov_b32_e32 v181, v149
	v_pk_mov_b32 v[150:151], v[146:147], v[150:151] op_sel:[1,0]
	v_mov_b32_e32 v173, v146
	v_pk_add_f32 v[150:151], v[180:181], v[150:151] neg_lo:[0,1] neg_hi:[0,1]
	v_mov_b32_e32 v184, v182
	v_pk_add_f32 v[146:147], v[172:173], v[150:151] neg_lo:[0,1] neg_hi:[0,1]
	v_mov_b32_e32 v183, v149
	v_pk_add_f32 v[150:151], v[184:185], v[146:147]
	s_nop 0
	v_pk_add_f32 v[172:173], v[150:151], v[150:151] op_sel:[0,1] op_sel_hi:[1,0]
	s_nop 0
	v_pk_add_f32 v[148:149], v[148:149], v[172:173] op_sel:[1,0] op_sel_hi:[0,1]
	v_mov_b32_e32 v151, v148
	v_pk_add_f32 v[180:181], v[150:151], v[182:183] neg_lo:[0,1] neg_hi:[0,1]
	v_mov_b32_e32 v147, v172
	v_sub_f32_e32 v149, v150, v180
	v_pk_add_f32 v[146:147], v[146:147], v[180:181] neg_lo:[0,1] neg_hi:[0,1]
	v_sub_f32_e32 v149, v182, v149
	v_add_f32_e32 v146, v146, v149
	v_add_f32_e32 v146, v146, v147
	v_add_f32_e32 v146, v148, v146
	v_cndmask_b32_e32 v146, v216, v146, vcc
	v_cmp_ngt_f32_e32 vcc, -1.0, v152
	s_nop 1
	v_cndmask_b32_e32 v146, v217, v146, vcc
	v_cmp_neq_f32_e32 vcc, -1.0, v152
	s_nop 1
	v_cndmask_b32_e32 v146, v218, v146, vcc
	v_cmp_lt_f32_e64 vcc, |v152|, s2
	s_nop 1
	v_cndmask_b32_e32 v146, v146, v152, vcc

; __device__ __forceinline__ float softplus_f(float x) { return x > 20.f ? x : log1pf(__expf(x)); }
;     __device__ __forceinline__ void fast(const f32x4 (&acc)[2][2][4][2], const pg8::Unit& u, int wr, int wc, int fr, int fq, RsCache& rsc) const {
;     ...
;         } else if (wc == 0) {
;             const f32x4 b0 = *(const f32x4*)(dt_bias + 8 * fq), b1 = *(const f32x4*)(dt_bias + 8 * fq + 4);
; #pragma unroll
;             for (int ai = 0; ai < 2; ++ai)
; #pragma unroll
;                 for (int m = 0; m < 4; ++m) { const int row = row0 + ai * 128 + m * 16; const float s = rsc.tab[ai * 64 + m * 16 + fr];
;                     const f32x4 v0 = acc[ai][0][m][0] * s + b0, v1 = acc[ai][0][m][1] * s + b1; f32x4 o0, o1;
; #pragma unroll
;                     for (int e = 0; e < 4; ++e) { o0[e] = softplus_f(v0[e]); o1[e] = softplus_f(v1[e]); }
;                     float* dp = dt + (size_t)row * 32 + 8 * fq; *(f32x4*)dp = o0; *(f32x4*)(dp + 4) = o1;
;                     asm volatile("" ::: "memory"); }
.LBB0_447:
	s_or_b64 exec, exec, s[0:1]
	v_lshlrev_b64 v[172:173], 7, v[164:165]
	v_lshl_add_u64 v[172:173], s[80:81], 0, v[172:173]
	v_lshl_add_u64 v[172:173], v[166:167], 2, v[172:173]
	s_mov_b64 s[0:1], 0x4800
	v_lshl_add_u64 v[180:181], v[172:173], 0, s[0:1]
	v_add_co_u32_e32 v172, vcc, 0x4000, v172
	s_nop 1
	v_addc_co_u32_e32 v173, vcc, 0, v173, vcc
	global_store_dwordx4 v[172:173], v[146:149], off offset:2048 sc1
	global_store_dwordx4 v[180:181], v[150:153], off offset:16 sc1
	ds_read_b32 v153, v178 offset:384
	s_waitcnt lgkmcnt(0)
	v_fma_f32 v146, v42, v153, v142
	v_cmp_nlt_f32_e32 vcc, s10, v146
	s_and_saveexec_b64 s[0:1], vcc
	s_cbranch_execz .LBB0_449
	v_mul_f32_e32 v146, 0x3fb8aa3b, v146
	v_exp_f32_e32 v152, v146
	s_mov_b32 s2, 0x7f800000
	v_add_f32_e32 v148, 1.0, v152
	v_frexp_mant_f32_e32 v150, v148
	v_cvt_f64_f32_e32 v[146:147], v148
	v_frexp_exp_i32_f64_e32 v146, v[146:147]
	v_cmp_gt_f32_e32 vcc, s11, v150
	v_add_f32_e32 v149, -1.0, v148
	v_sub_f32_e32 v151, v149, v148
	v_subbrev_co_u32_e32 v179, vcc, 0, v146, vcc
	v_sub_u32_e32 v146, 0, v179
	v_sub_f32_e32 v149, v152, v149
	v_add_f32_e32 v151, 1.0, v151
	v_ldexp_f32 v147, v148, v146
	v_add_f32_e32 v149, v149, v151
	v_add_f32_e32 v148, -1.0, v147
	v_add_f32_e32 v150, 1.0, v147
	v_ldexp_f32 v146, v149, v146
	v_add_f32_e32 v149, 1.0, v148
	v_add_f32_e32 v151, -1.0, v150
	v_sub_f32_e32 v149, v147, v149
	v_sub_f32_e32 v147, v147, v151
	v_add_f32_e32 v149, v146, v149
	v_add_f32_e32 v146, v146, v147
	v_add_f32_e32 v175, v150, v146
	v_rcp_f32_e32 v181, v175
	v_sub_f32_e32 v147, v175, v150
	v_sub_f32_e32 v180, v146, v147
	v_add_f32_e32 v147, v148, v149
	v_mul_f32_e32 v183, v147, v181
	v_sub_f32_e32 v146, v147, v148
	v_mul_f32_e32 v148, v175, v183
	v_fma_f32 v150, v183, v175, -v148
	v_fmac_f32_e32 v150, v183, v180
	v_sub_f32_e32 v182, v149, v146
	v_add_f32_e32 v146, v148, v150
	v_sub_f32_e32 v149, v147, v146
	v_pk_add_f32 v[172:173], v[146:147], v[148:149] neg_lo:[0,1] neg_hi:[0,1]
	v_mov_b32_e32 v151, v146
	v_pk_add_f32 v[146:147], v[172:173], v[150:151] neg_lo:[0,1] neg_hi:[0,1]
	v_cmp_neq_f32_e32 vcc, s2, v152
	v_add_f32_e32 v147, v182, v147
	v_add_f32_e32 v146, v146, v147
	v_add_f32_e32 v147, v149, v146
	v_mul_f32_e32 v182, v181, v147
	v_mul_f32_e32 v148, v175, v182
	v_fma_f32 v150, v182, v175, -v148
	v_fmac_f32_e32 v150, v182, v180
	v_sub_f32_e32 v149, v149, v147
	v_add_f32_e32 v175, v146, v149
	v_add_f32_e32 v146, v148, v150
	v_sub_f32_e32 v149, v147, v146
	v_pk_add_f32 v[172:173], v[146:147], v[148:149] neg_lo:[0,1] neg_hi:[0,1]
	v_mov_b32_e32 v151, v146
	v_pk_add_f32 v[146:147], v[172:173], v[150:151] neg_lo:[0,1] neg_hi:[0,1]
	s_mov_b32 s2, 0x33800000
	v_add_f32_e32 v147, v175, v147
	v_add_f32_e32 v146, v146, v147
	v_add_f32_e32 v147, v183, v182
	v_add_f32_e32 v146, v149, v146
	v_sub_f32_e32 v148, v147, v183
	v_mul_f32_e32 v146, v181, v146
	v_sub_f32_e32 v148, v182, v148
	v_add_f32_e32 v148, v148, v146
	v_add_f32_e32 v150, v147, v148
	v_mul_f32_e32 v151, v150, v150
	v_fmamk_f32 v146, v151, 0x3e9b6dac, v206
	v_fmaak_f32 v175, v151, v146, 0x3f2aaada
	v_cvt_f32_i32_e32 v146, v179
	v_sub_f32_e32 v147, v150, v147
	v_sub_f32_e32 v147, v148, v147
	v_ldexp_f32 v172, v147, 1
	v_mul_f32_e32 v147, v150, v151
	v_ldexp_f32 v149, v150, 1
	v_pk_mul_f32 v[150:151], v[146:147], v[174:175]
	s_nop 0
	v_fma_f32 v148, v146, s26, -v150
	v_fmac_f32_e32 v148, 0xb102e308, v146
	v_pk_add_f32 v[146:147], v[150:151], v[148:149]
	s_nop 0
	v_sub_f32_e32 v149, v147, v149
	v_sub_f32_e32 v149, v151, v149
	v_add_f32_e32 v173, v172, v149
	v_mov_b32_e32 v172, v150
	v_pk_add_f32 v[150:151], v[146:147], v[150:151] neg_lo:[0,1] neg_hi:[0,1]
	v_pk_add_f32 v[180:181], v[146:147], v[172:173]
	v_mov_b32_e32 v149, v146
	v_mov_b32_e32 v151, v181
	v_pk_add_f32 v[182:183], v[148:149], v[150:151] neg_lo:[0,1] neg_hi:[0,1]
	v_pk_add_f32 v[148:149], v[148:149], v[150:151]
	v_mov_b32_e32 v172, v173
	v_pk_add_f32 v[150:151], v[148:149], v[146:147] op_sel:[1,0] op_sel_hi:[0,1] neg_lo:[0,1] neg_hi:[0,1]
	v_pk_add_f32 v[184:185], v[180:181], v[150:151] op_sel_hi:[1,0] neg_lo:[0,1] neg_hi:[0,1]
	v_mov_b32_e32 v180, v181
	v_mov_b32_e32 v181, v149
	v_pk_mov_b32 v[150:151], v[146:147], v[150:151] op_sel:[1,0]
	v_mov_b32_e32 v173, v146
	v_pk_add_f32 v[150:151], v[180:181], v[150:151] neg_lo:[0,1] neg_hi:[0,1]
	v_mov_b32_e32 v184, v182
	v_pk_add_f32 v[146:147], v[172:173], v[150:151] neg_lo:[0,1] neg_hi:[0,1]
	v_mov_b32_e32 v183, v149
	v_pk_add_f32 v[150:151], v[184:185], v[146:147]
	s_nop 0
	v_pk_add_f32 v[172:173], v[150:151], v[150:151] op_sel:[0,1] op_sel_hi:[1,0]
	s_nop 0
	v_pk_add_f32 v[148:149], v[148:149], v[172:173] op_sel:[1,0] op_sel_hi:[0,1]
	v_mov_b32_e32 v151, v148
	v_pk_add_f32 v[180:181], v[150:151], v[182:183] neg_lo:[0,1] neg_hi:[0,1]
	v_mov_b32_e32 v147, v172
	v_sub_f32_e32 v149, v150, v180
	v_pk_add_f32 v[146:147], v[146:147], v[180:181] neg_lo:[0,1] neg_hi:[0,1]
	v_sub_f32_e32 v149, v182, v149
	v_add_f32_e32 v146, v146, v149
	v_add_f32_e32 v146, v146, v147
	v_add_f32_e32 v146, v148, v146
	v_cndmask_b32_e32 v146, v216, v146, vcc
	v_cmp_ngt_f32_e32 vcc, -1.0, v152
	s_nop 1
	v_cndmask_b32_e32 v146, v217, v146, vcc
	v_cmp_neq_f32_e32 vcc, -1.0, v152
	s_nop 1
	v_cndmask_b32_e32 v146, v218, v146, vcc
	v_cmp_lt_f32_e64 vcc, |v152|, s2
	s_nop 1
	v_cndmask_b32_e32 v146, v146, v152, vcc

; __device__ __forceinline__ float softplus_f(float x) { return x > 20.f ? x : log1pf(__expf(x)); }
;     __device__ __forceinline__ void fast(const f32x4 (&acc)[2][2][4][2], const pg8::Unit& u, int wr, int wc, int fr, int fq, RsCache& rsc) const {
;     ...
;         } else if (wc == 0) {
;             const f32x4 b0 = *(const f32x4*)(dt_bias + 8 * fq), b1 = *(const f32x4*)(dt_bias + 8 * fq + 4);
; #pragma unroll
;             for (int ai = 0; ai < 2; ++ai)
; #pragma unroll
;                 for (int m = 0; m < 4; ++m) { const int row = row0 + ai * 128 + m * 16; const float s = rsc.tab[ai * 64 + m * 16 + fr];
;                     const f32x4 v0 = acc[ai][0][m][0] * s + b0, v1 = acc[ai][0][m][1] * s + b1; f32x4 o0, o1;
; #pragma unroll
;                     for (int e = 0; e < 4; ++e) { o0[e] = softplus_f(v0[e]); o1[e] = softplus_f(v1[e]); }
;                     float* dp = dt + (size_t)row * 32 + 8 * fq; *(f32x4*)dp = o0; *(f32x4*)(dp + 4) = o1;
;                     asm volatile("" ::: "memory"); }
.LBB0_463:
	s_or_b64 exec, exec, s[0:1]
	v_lshlrev_b64 v[172:173], 7, v[164:165]
	v_lshl_add_u64 v[172:173], s[80:81], 0, v[172:173]
	v_lshl_add_u64 v[172:173], v[166:167], 2, v[172:173]
	s_mov_b64 s[0:1], 0x5000
	v_lshl_add_u64 v[180:181], v[172:173], 0, s[0:1]
	v_add_co_u32_e32 v172, vcc, 0x5000, v172
	s_nop 1
	v_addc_co_u32_e32 v173, vcc, 0, v173, vcc
	global_store_dwordx4 v[172:173], v[146:149], off sc1
	global_store_dwordx4 v[180:181], v[150:153], off offset:16 sc1
	ds_read_b32 v146, v178 offset:448
	s_waitcnt lgkmcnt(0)
	v_fma_f32 v142, v22, v146, v142
	v_cmp_nlt_f32_e32 vcc, s10, v142
	s_and_saveexec_b64 s[0:1], vcc
	s_cbranch_execz .LBB0_465
	v_mul_f32_e32 v142, 0x3fb8aa3b, v142
	v_exp_f32_e32 v142, v142
	s_mov_b32 s2, 0x7f800000
	v_add_f32_e32 v147, 1.0, v142
	v_frexp_mant_f32_e32 v151, v147
	v_cvt_f64_f32_e32 v[148:149], v147
	v_add_f32_e32 v150, -1.0, v147
	v_frexp_exp_i32_f64_e32 v148, v[148:149]
	v_cmp_gt_f32_e32 vcc, s11, v151
	v_sub_f32_e32 v152, v150, v147
	v_sub_f32_e32 v150, v142, v150
	v_subbrev_co_u32_e32 v178, vcc, 0, v148, vcc
	v_add_f32_e32 v152, 1.0, v152
	v_sub_u32_e32 v148, 0, v178
	v_add_f32_e32 v150, v150, v152
	v_ldexp_f32 v147, v147, v148
	v_ldexp_f32 v148, v150, v148
	v_add_f32_e32 v150, -1.0, v147
	v_add_f32_e32 v149, 1.0, v150
	v_sub_f32_e32 v149, v147, v149
	v_add_f32_e32 v151, v148, v149
	v_add_f32_e32 v149, 1.0, v147
	v_add_f32_e32 v152, -1.0, v149
	v_sub_f32_e32 v147, v147, v152
	v_add_f32_e32 v147, v148, v147
	v_add_f32_e32 v175, v149, v147
	v_rcp_f32_e32 v179, v175
	v_sub_f32_e32 v148, v175, v149
	v_add_f32_e32 v149, v150, v151
	v_sub_f32_e32 v147, v147, v148
	v_mul_f32_e32 v181, v149, v179
	v_sub_f32_e32 v148, v149, v150
	v_mul_f32_e32 v150, v175, v181
	v_fma_f32 v152, v181, v175, -v150
	v_fmac_f32_e32 v152, v181, v147
	v_sub_f32_e32 v180, v151, v148
	v_add_f32_e32 v148, v150, v152
	v_sub_f32_e32 v151, v149, v148
	v_pk_add_f32 v[172:173], v[148:149], v[150:151] neg_lo:[0,1] neg_hi:[0,1]
	v_mov_b32_e32 v153, v148
	v_pk_add_f32 v[148:149], v[172:173], v[152:153] neg_lo:[0,1] neg_hi:[0,1]
	v_cmp_neq_f32_e32 vcc, s2, v142
	v_add_f32_e32 v149, v180, v149
	v_add_f32_e32 v148, v148, v149
	v_add_f32_e32 v149, v151, v148
	v_mul_f32_e32 v180, v179, v149
	v_mul_f32_e32 v150, v175, v180
	v_fma_f32 v152, v180, v175, -v150
	v_fmac_f32_e32 v152, v180, v147
	v_sub_f32_e32 v147, v151, v149
	v_add_f32_e32 v147, v148, v147
	v_add_f32_e32 v148, v150, v152
	v_sub_f32_e32 v151, v149, v148
	v_pk_add_f32 v[172:173], v[148:149], v[150:151] neg_lo:[0,1] neg_hi:[0,1]
	v_mov_b32_e32 v153, v148
	v_pk_add_f32 v[148:149], v[172:173], v[152:153] neg_lo:[0,1] neg_hi:[0,1]
	s_mov_b32 s2, 0x33800000
	v_add_f32_e32 v147, v147, v149
	v_add_f32_e32 v147, v148, v147
	v_add_f32_e32 v149, v181, v180
	v_add_f32_e32 v147, v151, v147
	v_sub_f32_e32 v148, v149, v181
	v_mul_f32_e32 v147, v179, v147
	v_sub_f32_e32 v148, v180, v148
	v_add_f32_e32 v147, v148, v147
	v_add_f32_e32 v150, v149, v147
	v_mul_f32_e32 v152, v150, v150
	v_fmamk_f32 v148, v152, 0x3e9b6dac, v206
	v_fmaak_f32 v175, v152, v148, 0x3f2aaada
	v_cvt_f32_i32_e32 v148, v178
	v_sub_f32_e32 v149, v150, v149
	v_sub_f32_e32 v147, v147, v149
	v_mul_f32_e32 v149, v150, v152
	v_pk_mul_f32 v[152:153], v[148:149], v[174:175]
	v_ldexp_f32 v151, v150, 1
	v_fma_f32 v150, v148, s26, -v152
	v_fmac_f32_e32 v150, 0xb102e308, v148
	v_pk_add_f32 v[148:149], v[152:153], v[150:151]
	v_ldexp_f32 v147, v147, 1
	v_sub_f32_e32 v151, v149, v151
	v_sub_f32_e32 v151, v153, v151
	v_add_f32_e32 v173, v147, v151
	v_mov_b32_e32 v172, v152
	v_pk_add_f32 v[152:153], v[148:149], v[152:153] neg_lo:[0,1] neg_hi:[0,1]
	v_pk_add_f32 v[178:179], v[148:149], v[172:173]
	v_mov_b32_e32 v151, v148
	v_mov_b32_e32 v153, v179
	v_pk_add_f32 v[180:181], v[150:151], v[152:153] neg_lo:[0,1] neg_hi:[0,1]
	v_pk_add_f32 v[150:151], v[150:151], v[152:153]
	v_mov_b32_e32 v172, v173
	v_pk_add_f32 v[152:153], v[150:151], v[148:149] op_sel:[1,0] op_sel_hi:[0,1] neg_lo:[0,1] neg_hi:[0,1]
	v_pk_add_f32 v[182:183], v[178:179], v[152:153] op_sel_hi:[1,0] neg_lo:[0,1] neg_hi:[0,1]
	v_mov_b32_e32 v178, v179
	v_mov_b32_e32 v179, v151
	v_pk_mov_b32 v[152:153], v[148:149], v[152:153] op_sel:[1,0]
	v_mov_b32_e32 v173, v148
	v_pk_add_f32 v[152:153], v[178:179], v[152:153] neg_lo:[0,1] neg_hi:[0,1]
	v_mov_b32_e32 v182, v180
	v_pk_add_f32 v[148:149], v[172:173], v[152:153] neg_lo:[0,1] neg_hi:[0,1]
	v_mov_b32_e32 v181, v151
	v_pk_add_f32 v[152:153], v[182:183], v[148:149]
	s_nop 0
	v_pk_add_f32 v[172:173], v[152:153], v[152:153] op_sel:[0,1] op_sel_hi:[1,0]
	s_nop 0
	v_pk_add_f32 v[150:151], v[150:151], v[172:173] op_sel:[1,0] op_sel_hi:[0,1]
	v_mov_b32_e32 v153, v150
	v_pk_add_f32 v[178:179], v[152:153], v[180:181] neg_lo:[0,1] neg_hi:[0,1]
	v_mov_b32_e32 v149, v172
	v_sub_f32_e32 v147, v152, v178
	v_pk_add_f32 v[148:149], v[148:149], v[178:179] neg_lo:[0,1] neg_hi:[0,1]
	v_sub_f32_e32 v147, v180, v147
	v_add_f32_e32 v147, v148, v147
	v_add_f32_e32 v147, v147, v149
	v_add_f32_e32 v147, v150, v147
	v_cndmask_b32_e32 v147, v216, v147, vcc
	v_cmp_ngt_f32_e32 vcc, -1.0, v142
	s_nop 1
	v_cndmask_b32_e32 v147, v217, v147, vcc
	v_cmp_neq_f32_e32 vcc, -1.0, v142
	s_nop 1
	v_cndmask_b32_e32 v147, v218, v147, vcc
	v_cmp_lt_f32_e64 vcc, |v142|, s2
	s_nop 1
	v_cndmask_b32_e32 v142, v147, v142, vcc

; __device__ __forceinline__ float softplus_f(float x) { return x > 20.f ? x : log1pf(__expf(x)); }
;     __device__ __forceinline__ void fast(const f32x4 (&acc)[2][2][4][2], const pg8::Unit& u, int wr, int wc, int fr, int fq, RsCache& rsc) const {
;     ...
;         } else if (wc == 0) {
;             const f32x4 b0 = *(const f32x4*)(dt_bias + 8 * fq), b1 = *(const f32x4*)(dt_bias + 8 * fq + 4);
; #pragma unroll
;             for (int ai = 0; ai < 2; ++ai)
; #pragma unroll
;                 for (int m = 0; m < 4; ++m) { const int row = row0 + ai * 128 + m * 16; const float s = rsc.tab[ai * 64 + m * 16 + fr];
;                     const f32x4 v0 = acc[ai][0][m][0] * s + b0, v1 = acc[ai][0][m][1] * s + b1; f32x4 o0, o1;
; #pragma unroll
;                     for (int e = 0; e < 4; ++e) { o0[e] = softplus_f(v0[e]); o1[e] = softplus_f(v1[e]); }
;                     float* dp = dt + (size_t)row * 32 + 8 * fq; *(f32x4*)dp = o0; *(f32x4*)(dp + 4) = o1;
;                     asm volatile("" ::: "memory"); }
.LBB0_479:
	s_or_b64 exec, exec, s[0:1]
	v_lshlrev_b64 v[146:147], 7, v[164:165]
	v_lshl_add_u64 v[146:147], s[80:81], 0, v[146:147]
	v_lshl_add_u64 v[146:147], v[166:167], 2, v[146:147]
	s_mov_b64 s[0:1], 0x5800
	v_lshl_add_u64 v[148:149], v[146:147], 0, s[0:1]
	v_add_co_u32_e32 v146, vcc, 0x5000, v146
	s_nop 1
	v_addc_co_u32_e32 v147, vcc, 0, v147, vcc
	global_store_dwordx4 v[146:147], v[142:145], off offset:2048 sc1
	global_store_dwordx4 v[148:149], v[138:141], off offset:16 sc1
	s_cbranch_execnz .LBB0_338
	s_branch .LBB0_340
